# lever 4: one static s_setprio 1 per GEMM unit for the trailing (younger, waves 4-7) half, all per-segment s_setprio flips in the 5 K loops deleted
# baseline (speedup 1.0000x reference)
;     __device__ __forceinline__ bool next(int i, Unit& u) const { if (!base.next(i >> 1, u)) return false; if (i & 1) { u.pm += 64; u.pn += 8; } return true; }
; #define PG8_STAGE(bufoff, gbase, voff) do { _Pragma("unroll") for (int _i = 0; _i < 2; ++_i) \
;         __builtin_amdgcn_global_load_lds((const unsigned*)((const char*)(gbase) + (voff)[_i]), (PG8_LAS unsigned*)(lds + (bufoff) + ldsw + _i * 8192), 16, 0, 0); } while (0)
; #define PG8_BAR __builtin_amdgcn_s_barrier()
; template <class Epi, class Sched, bool ALIGN_EPI = false, bool SP2 = false>
; __device__ __forceinline__ void gemm_phase(PG8_LAS unsigned char* lds, const Gemm g, const Sched& S, const Epi& E) {
;     ...
;     for (;;) {
;         const bool has_next = S.next(ui + 1, nxt);
;         const char* nA = has_next ? (const char*)g.A + (size_t)nxt.pm * tstep : cA; const char* nB = has_next ? (const char*)g.Bt + (size_t)nxt.pn * tstep : cB;
;         for (int t = 0; t < nt; t += 2) {
;             const bool last = (t == nt - 2);
;             const char* a1 = cA + (size_t)(t + 1) * kstep;
;             const char* a2 = last ? nA : cA + (size_t)(t + 2) * kstep; const char* b2 = last ? nB : cB + (size_t)(t + 2) * kstep;
;             const char* a3 = a2 + kstep; const char* b3 = b2 + kstep;
;             if (last && has_next) S.a_ready(nxt);
;             if constexpr (SP2) {
;             PG8_LDB(B0, 0, 0); PG8_LDB(B1, 0, 1); PG8_SCHED; PG8_LDA(At, 0, 0); PG8_STAGE(PG8_SA(1, 1), a1 + hstep, voffA);
;             PG8_WAIT_V(8); PG8_WAIT_L(0); PG8_BAR; PG8_MMA(0, 0, At, B0); PG8_MMA(0, 1, At, B1); PG8_BAR; PG8_SCHED;
;             PG8_LDA(At, 0, 1); PG8_STAGE(PG8_SB(0, 0), b2, voffB); PG8_STAGE(PG8_SB(0, 1), b2 + hstep, voffB); PG8_STAGE(PG8_SA(0, 0), a2, voffA);
;             PG8_WAIT_V(8); PG8_WAIT_L(0); PG8_BAR; PG8_MMA(1, 0, At, B0); PG8_MMA(1, 1, At, B1); PG8_BAR; PG8_SCHED;
;             PG8_LDB(B0, 1, 0); PG8_LDB(B1, 1, 1); PG8_SCHED; PG8_LDA(At, 1, 0); PG8_STAGE(PG8_SA(0, 1), a2 + hstep, voffA);
;             PG8_WAIT_V(8); PG8_WAIT_L(0); PG8_BAR; PG8_MMA(0, 0, At, B0); PG8_MMA(0, 1, At, B1); PG8_BAR; PG8_SCHED;
;             PG8_LDA(At, 1, 1); PG8_STAGE(PG8_SB(1, 0), b3, voffB); PG8_STAGE(PG8_SB(1, 1), b3 + hstep, voffB); PG8_STAGE(PG8_SA(1, 0), a3, voffA);
;             PG8_WAIT_V(8); PG8_WAIT_L(0); PG8_BAR; PG8_MMA(1, 0, At, B0); PG8_MMA(1, 1, At, B1); PG8_BAR; PG8_SCHED;
.LBB0_204:
	s_ashr_i32 s21, s20, 31
	s_lshl_b64 s[24:25], s[20:21], 20
	v_readlane_b32 s26, v236, 50
	v_readlane_b32 s27, v236, 51
	s_add_u32 s24, s26, s24
	s_addc_u32 s25, s27, s25
	s_and_b64 s[26:27], s[8:9], exec
	s_cselect_b32 s1, s25, s5
	s_cselect_b32 s3, s24, s4
	s_ashr_i32 s23, s22, 31
	s_lshl_b64 s[26:27], s[22:23], 20
	s_add_u32 s26, s10, s26
	s_addc_u32 s27, s11, s27
	s_and_b64 s[28:29], s[8:9], exec
	s_cselect_b32 s21, s27, s7
	s_cselect_b32 s23, s26, s6
	s_add_u32 s4, s4, 0x80080
	s_addc_u32 s5, s5, 0
	s_add_u32 s33, s6, 0x100
	s_addc_u32 s50, s7, 0
	s_mov_b32 s51, -2
	s_waitcnt vmcnt(0)
	s_cmp_eq_u64 s[18:19], 0
	s_cbranch_scc0 .Lprio_skip_205
	s_setprio 1
.Lprio_skip_205:
	ds_read_b128 v[128:131], v190
	ds_read_b128 v[132:135], v190 offset:1024
	ds_read_b128 v[136:139], v190 offset:2048
	ds_read_b128 v[140:143], v190 offset:3072
	ds_read_b128 v[144:147], v191
	ds_read_b128 v[148:151], v191 offset:1024
	ds_read_b128 v[152:155], v191 offset:2048
	ds_read_b128 v[156:159], v191 offset:3072
	s_add_u32 s6, s4, 0xfff80080
	s_addc_u32 s7, s5, -1
	s_cmp_eq_u32 s51, 28
	s_cselect_b32 s29, s1, s7
	s_cselect_b32 s28, s3, s6
	s_cselect_b32 s7, s21, s50
	s_cselect_b32 s6, s23, s33
	v_lshl_add_u64 v[184:185], s[4:5], 0, v[172:173]
	s_add_i32 m0, s31, 0xc000
	ds_read_b128 v[180:183], v192
	ds_read_b128 v[194:197], v192 offset:1024
	ds_read_b128 v[198:201], v192 offset:2048
	ds_read_b128 v[202:205], v192 offset:3072
	ds_read_b128 v[206:209], v192 offset:4096
	ds_read_b128 v[210:213], v192 offset:5120
	ds_read_b128 v[214:217], v192 offset:6144
	ds_read_b128 v[218:221], v192 offset:7168
	global_load_lds_dwordx4 v[184:185], off
	v_lshl_add_u64 v[184:185], s[4:5], 0, v[174:175]
	s_add_i32 m0, s31, 0xe000
	s_nop 0
	global_load_lds_dwordx4 v[184:185], off
	s_waitcnt vmcnt(8)
	s_waitcnt lgkmcnt(0)
	s_barrier
	v_mfma_f32_16x16x32_bf16 v[124:127], v[128:131], v[180:183], 0
	v_mfma_f32_16x16x32_bf16 v[120:123], v[136:139], v[180:183], 0
	v_mfma_f32_16x16x32_bf16 v[108:111], v[128:131], v[198:201], 0
	v_mfma_f32_16x16x32_bf16 v[104:107], v[136:139], v[198:201], 0
	v_mfma_f32_16x16x32_bf16 v[92:95], v[128:131], v[206:209], 0
	v_mfma_f32_16x16x32_bf16 v[88:91], v[136:139], v[206:209], 0
	v_mfma_f32_16x16x32_bf16 v[76:79], v[128:131], v[214:217], 0
	v_mfma_f32_16x16x32_bf16 v[72:75], v[136:139], v[214:217], 0
	v_mfma_f32_16x16x32_bf16 v[124:127], v[132:135], v[194:197], v[124:127]
	v_mfma_f32_16x16x32_bf16 v[120:123], v[140:143], v[194:197], v[120:123]
	v_mfma_f32_16x16x32_bf16 v[108:111], v[132:135], v[202:205], v[108:111]
	v_mfma_f32_16x16x32_bf16 v[104:107], v[140:143], v[202:205], v[104:107]
	v_mfma_f32_16x16x32_bf16 v[92:95], v[132:135], v[210:213], v[92:95]
	v_mfma_f32_16x16x32_bf16 v[88:91], v[140:143], v[210:213], v[88:91]
	v_mfma_f32_16x16x32_bf16 v[76:79], v[132:135], v[218:221], v[76:79]
	v_mfma_f32_16x16x32_bf16 v[72:75], v[140:143], v[218:221], v[72:75]
	v_mfma_f32_16x16x32_bf16 v[116:119], v[144:147], v[180:183], 0
	v_mfma_f32_16x16x32_bf16 v[112:115], v[152:155], v[180:183], 0
	v_mfma_f32_16x16x32_bf16 v[100:103], v[144:147], v[198:201], 0
	v_mfma_f32_16x16x32_bf16 v[96:99], v[152:155], v[198:201], 0
	v_mfma_f32_16x16x32_bf16 v[84:87], v[144:147], v[206:209], 0
	v_mfma_f32_16x16x32_bf16 v[80:83], v[152:155], v[206:209], 0
	v_mfma_f32_16x16x32_bf16 v[68:71], v[144:147], v[214:217], 0
	v_mfma_f32_16x16x32_bf16 v[64:67], v[152:155], v[214:217], 0
	v_mfma_f32_16x16x32_bf16 v[116:119], v[148:151], v[194:197], v[116:119]
	v_mfma_f32_16x16x32_bf16 v[112:115], v[156:159], v[194:197], v[112:115]
	v_mfma_f32_16x16x32_bf16 v[100:103], v[148:151], v[202:205], v[100:103]
	v_mfma_f32_16x16x32_bf16 v[96:99], v[156:159], v[202:205], v[96:99]
	v_mfma_f32_16x16x32_bf16 v[84:87], v[148:151], v[210:213], v[84:87]
	v_mfma_f32_16x16x32_bf16 v[80:83], v[156:159], v[210:213], v[80:83]
	v_mfma_f32_16x16x32_bf16 v[68:71], v[148:151], v[218:221], v[68:71]
	v_mfma_f32_16x16x32_bf16 v[64:67], v[156:159], v[218:221], v[64:67]
	s_barrier
	s_add_i32 s52, s43, s30
	v_lshl_add_u64 v[184:185], s[6:7], 0, v[164:165]
	s_mov_b32 m0, s52
	ds_read_b128 v[180:183], v192 offset:16384
	ds_read_b128 v[194:197], v192 offset:17408
	ds_read_b128 v[198:201], v192 offset:18432
	ds_read_b128 v[202:205], v192 offset:19456
	ds_read_b128 v[206:209], v192 offset:20480
	ds_read_b128 v[210:213], v192 offset:21504
	ds_read_b128 v[214:217], v192 offset:22528
	ds_read_b128 v[218:221], v192 offset:23552
	global_load_lds_dwordx4 v[184:185], off
	s_add_i32 m0, s52, 0x2000
	s_add_u32 s52, s6, 0x80000
	v_lshl_add_u64 v[222:223], s[6:7], 0, v[168:169]
	s_addc_u32 s53, s7, 0
	s_add_i32 s54, s44, s30
	global_load_lds_dwordx4 v[222:223], off
	v_lshl_add_u64 v[224:225], s[52:53], 0, v[164:165]
	s_mov_b32 m0, s54
	v_lshl_add_u64 v[226:227], s[28:29], 0, v[166:167]
	global_load_lds_dwordx4 v[224:225], off
	v_lshl_add_u64 v[224:225], s[52:53], 0, v[168:169]
	s_add_i32 m0, s54, 0x2000
	s_nop 0
	global_load_lds_dwordx4 v[224:225], off
	v_lshl_add_u64 v[224:225], s[28:29], 0, v[162:163]
	s_mov_b32 m0, s31
	s_nop 0
	global_load_lds_dwordx4 v[224:225], off
	s_mov_b32 m0, s34
	s_nop 0
	global_load_lds_dwordx4 v[226:227], off
	s_waitcnt vmcnt(8)
	s_waitcnt lgkmcnt(0)
	s_barrier
; #define PG8_STAGE(bufoff, gbase, voff) do { _Pragma("unroll") for (int _i = 0; _i < 2; ++_i) \
;         __builtin_amdgcn_global_load_lds((const unsigned*)((const char*)(gbase) + (voff)[_i]), (PG8_LAS unsigned*)(lds + (bufoff) + ldsw + _i * 8192), 16, 0, 0); } while (0)
; #define PG8_LDA(dst, b, h) do { _Pragma("unroll") for (int m = 0; m < 4; ++m) _Pragma("unroll") for (int k = 0; k < 2; ++k) dst[m][k] = *(const PG8_LAS bf16x8*)(lds + PG8_SA(b, h) + aoff + m * 2048 + k * 1024); } while (0)
; #define PG8_LDB(dst, b, h) do { _Pragma("unroll") for (int n = 0; n < 2; ++n) _Pragma("unroll") for (int k = 0; k < 2; ++k) dst[n][k] = *(const PG8_LAS bf16x8*)(lds + PG8_SB(b, h) + boff + n * 2048 + k * 1024); } while (0)
; #define PG8_MMA(ai, bj, At, Bt) do { __builtin_amdgcn_s_setprio(1); _Pragma("unroll") for (int m = 0; m < 4; ++m) _Pragma("unroll") for (int n = 0; n < 2; ++n) _Pragma("unroll") for (int k = 0; k < 2; ++k) \
;         acc[ai][bj][m][n] = __builtin_amdgcn_mfma_f32_16x16x32_bf16(Bt[n][k], At[m][k], acc[ai][bj][m][n], 0, 0, 0); __builtin_amdgcn_s_setprio(0); } while (0)
; #define PG8_WAIT_V(n) asm volatile("s_waitcnt vmcnt(" #n ")" ::: "memory")
; template <class Epi, class Sched, bool ALIGN_EPI = false, bool SP2 = false>
; __device__ __forceinline__ void gemm_phase(PG8_LAS unsigned char* lds, const Gemm g, const Sched& S, const Epi& E) {
;     ...
;             PG8_LDB(B0, 0, 0); PG8_LDB(B1, 0, 1); PG8_SCHED; PG8_LDA(At, 0, 0); PG8_STAGE(PG8_SA(1, 1), a1 + hstep, voffA);
;             PG8_WAIT_V(8); PG8_WAIT_L(0); PG8_BAR; PG8_MMA(0, 0, At, B0); PG8_MMA(0, 1, At, B1); PG8_BAR; PG8_SCHED;
;             PG8_LDA(At, 0, 1); PG8_STAGE(PG8_SB(0, 0), b2, voffB); PG8_STAGE(PG8_SB(0, 1), b2 + hstep, voffB); PG8_STAGE(PG8_SA(0, 0), a2, voffA);
;             PG8_WAIT_V(8); PG8_WAIT_L(0); PG8_BAR; PG8_MMA(1, 0, At, B0); PG8_MMA(1, 1, At, B1); PG8_BAR; PG8_SCHED;
;             PG8_LDB(B0, 1, 0); PG8_LDB(B1, 1, 1); PG8_SCHED; PG8_LDA(At, 1, 0); PG8_STAGE(PG8_SA(0, 1), a2 + hstep, voffA);
;             PG8_WAIT_V(8); PG8_WAIT_L(0); PG8_BAR; PG8_MMA(0, 0, At, B0); PG8_MMA(0, 1, At, B1); PG8_BAR; PG8_SCHED;
;             PG8_LDA(At, 1, 1); PG8_STAGE(PG8_SB(1, 0), b3, voffB); PG8_STAGE(PG8_SB(1, 1), b3 + hstep, voffB); PG8_STAGE(PG8_SA(1, 0), a3, voffA);
;             PG8_WAIT_V(8); PG8_WAIT_L(0); PG8_BAR; PG8_MMA(1, 0, At, B0); PG8_MMA(1, 1, At, B1); PG8_BAR; PG8_SCHED;
	v_mfma_f32_16x16x32_bf16 v[60:63], v[128:131], v[180:183], 0
	v_mfma_f32_16x16x32_bf16 v[56:59], v[136:139], v[180:183], 0
	v_mfma_f32_16x16x32_bf16 v[44:47], v[128:131], v[198:201], 0
	v_mfma_f32_16x16x32_bf16 v[40:43], v[136:139], v[198:201], 0
	v_mfma_f32_16x16x32_bf16 v[28:31], v[128:131], v[206:209], 0
	v_mfma_f32_16x16x32_bf16 v[24:27], v[136:139], v[206:209], 0
	v_mfma_f32_16x16x32_bf16 v[12:15], v[128:131], v[214:217], 0
	v_mfma_f32_16x16x32_bf16 v[8:11], v[136:139], v[214:217], 0
	v_mfma_f32_16x16x32_bf16 v[60:63], v[132:135], v[194:197], v[60:63]
	v_mfma_f32_16x16x32_bf16 v[56:59], v[140:143], v[194:197], v[56:59]
	v_mfma_f32_16x16x32_bf16 v[44:47], v[132:135], v[202:205], v[44:47]
	v_mfma_f32_16x16x32_bf16 v[40:43], v[140:143], v[202:205], v[40:43]
	v_mfma_f32_16x16x32_bf16 v[28:31], v[132:135], v[210:213], v[28:31]
	v_mfma_f32_16x16x32_bf16 v[24:27], v[140:143], v[210:213], v[24:27]
	v_mfma_f32_16x16x32_bf16 v[12:15], v[132:135], v[218:221], v[12:15]
	v_mfma_f32_16x16x32_bf16 v[8:11], v[140:143], v[218:221], v[8:11]
	v_mfma_f32_16x16x32_bf16 v[52:55], v[144:147], v[180:183], 0
	v_mfma_f32_16x16x32_bf16 v[48:51], v[152:155], v[180:183], 0
	v_mfma_f32_16x16x32_bf16 v[36:39], v[144:147], v[198:201], 0
	v_mfma_f32_16x16x32_bf16 v[32:35], v[152:155], v[198:201], 0
	v_mfma_f32_16x16x32_bf16 v[20:23], v[144:147], v[206:209], 0
	v_mfma_f32_16x16x32_bf16 v[16:19], v[152:155], v[206:209], 0
	v_mfma_f32_16x16x32_bf16 v[4:7], v[144:147], v[214:217], 0
	v_mfma_f32_16x16x32_bf16 v[0:3], v[152:155], v[214:217], 0
	v_mfma_f32_16x16x32_bf16 v[52:55], v[148:151], v[194:197], v[52:55]
	v_mfma_f32_16x16x32_bf16 v[48:51], v[156:159], v[194:197], v[48:51]
	v_mfma_f32_16x16x32_bf16 v[36:39], v[148:151], v[202:205], v[36:39]
	v_mfma_f32_16x16x32_bf16 v[32:35], v[156:159], v[202:205], v[32:35]
	v_mfma_f32_16x16x32_bf16 v[20:23], v[148:151], v[210:213], v[20:23]
	v_mfma_f32_16x16x32_bf16 v[16:19], v[156:159], v[210:213], v[16:19]
	v_mfma_f32_16x16x32_bf16 v[4:7], v[148:151], v[218:221], v[4:7]
	v_mfma_f32_16x16x32_bf16 v[0:3], v[156:159], v[218:221], v[0:3]
	s_barrier
	s_add_i32 s52, 0, 0x18000
	s_add_i32 s53, 0, 0x1c000
	v_add_u32_e32 v140, s52, v188
	v_add_u32_e32 v156, s53, v188
	ds_read_b128 v[128:131], v140
	ds_read_b128 v[132:135], v140 offset:1024
	ds_read_b128 v[136:139], v140 offset:2048
	ds_read_b128 v[140:143], v140 offset:3072
	ds_read_b128 v[144:147], v156
	ds_read_b128 v[148:151], v156 offset:1024
	ds_read_b128 v[152:155], v156 offset:2048
	ds_read_b128 v[156:159], v156 offset:3072
	s_add_u32 s28, s28, 0x80000
	s_addc_u32 s29, s29, 0
	s_mov_b32 m0, s35
	v_lshl_add_u64 v[228:229], s[28:29], 0, v[162:163]
	ds_read_b128 v[180:183], v192 offset:32768
	ds_read_b128 v[194:197], v192 offset:33792
	ds_read_b128 v[198:201], v192 offset:34816
	ds_read_b128 v[202:205], v192 offset:35840
	ds_read_b128 v[206:209], v192 offset:36864
	ds_read_b128 v[210:213], v192 offset:37888
	ds_read_b128 v[214:217], v192 offset:38912
	ds_read_b128 v[218:221], v192 offset:39936
	global_load_lds_dwordx4 v[228:229], off
	v_lshl_add_u64 v[228:229], s[28:29], 0, v[166:167]
	s_mov_b32 m0, s36
	s_nop 0
	global_load_lds_dwordx4 v[228:229], off
	s_waitcnt vmcnt(8)
	s_waitcnt lgkmcnt(0)
	s_barrier
	v_mfma_f32_16x16x32_bf16 v[124:127], v[128:131], v[180:183], v[124:127]
	v_mfma_f32_16x16x32_bf16 v[120:123], v[136:139], v[180:183], v[120:123]
	v_mfma_f32_16x16x32_bf16 v[108:111], v[128:131], v[198:201], v[108:111]
	v_mfma_f32_16x16x32_bf16 v[104:107], v[136:139], v[198:201], v[104:107]
	v_mfma_f32_16x16x32_bf16 v[92:95], v[128:131], v[206:209], v[92:95]
	v_mfma_f32_16x16x32_bf16 v[88:91], v[136:139], v[206:209], v[88:91]
	v_mfma_f32_16x16x32_bf16 v[76:79], v[128:131], v[214:217], v[76:79]
	v_mfma_f32_16x16x32_bf16 v[72:75], v[136:139], v[214:217], v[72:75]
	v_mfma_f32_16x16x32_bf16 v[124:127], v[132:135], v[194:197], v[124:127]
	v_mfma_f32_16x16x32_bf16 v[120:123], v[140:143], v[194:197], v[120:123]
	v_mfma_f32_16x16x32_bf16 v[108:111], v[132:135], v[202:205], v[108:111]
	v_mfma_f32_16x16x32_bf16 v[104:107], v[140:143], v[202:205], v[104:107]
	v_mfma_f32_16x16x32_bf16 v[92:95], v[132:135], v[210:213], v[92:95]
	v_mfma_f32_16x16x32_bf16 v[88:91], v[140:143], v[210:213], v[88:91]
	v_mfma_f32_16x16x32_bf16 v[76:79], v[132:135], v[218:221], v[76:79]
	v_mfma_f32_16x16x32_bf16 v[72:75], v[140:143], v[218:221], v[72:75]
	v_mfma_f32_16x16x32_bf16 v[116:119], v[144:147], v[180:183], v[116:119]
	v_mfma_f32_16x16x32_bf16 v[112:115], v[152:155], v[180:183], v[112:115]
	v_mfma_f32_16x16x32_bf16 v[100:103], v[144:147], v[198:201], v[100:103]
	v_mfma_f32_16x16x32_bf16 v[96:99], v[152:155], v[198:201], v[96:99]
	v_mfma_f32_16x16x32_bf16 v[84:87], v[144:147], v[206:209], v[84:87]
	v_mfma_f32_16x16x32_bf16 v[80:83], v[152:155], v[206:209], v[80:83]
	v_mfma_f32_16x16x32_bf16 v[68:71], v[144:147], v[214:217], v[68:71]
	v_mfma_f32_16x16x32_bf16 v[64:67], v[152:155], v[214:217], v[64:67]
	v_mfma_f32_16x16x32_bf16 v[116:119], v[148:151], v[194:197], v[116:119]
	v_mfma_f32_16x16x32_bf16 v[112:115], v[156:159], v[194:197], v[112:115]
	v_mfma_f32_16x16x32_bf16 v[100:103], v[148:151], v[202:205], v[100:103]
	v_mfma_f32_16x16x32_bf16 v[96:99], v[156:159], v[202:205], v[96:99]
	v_mfma_f32_16x16x32_bf16 v[84:87], v[148:151], v[210:213], v[84:87]
	v_mfma_f32_16x16x32_bf16 v[80:83], v[156:159], v[210:213], v[80:83]
	v_mfma_f32_16x16x32_bf16 v[68:71], v[148:151], v[218:221], v[68:71]
	v_mfma_f32_16x16x32_bf16 v[64:67], v[156:159], v[218:221], v[64:67]
	s_barrier
; #define PG8_STAGE(bufoff, gbase, voff) do { _Pragma("unroll") for (int _i = 0; _i < 2; ++_i) \
;         __builtin_amdgcn_global_load_lds((const unsigned*)((const char*)(gbase) + (voff)[_i]), (PG8_LAS unsigned*)(lds + (bufoff) + ldsw + _i * 8192), 16, 0, 0); } while (0)
; #define PG8_LDA(dst, b, h) do { _Pragma("unroll") for (int m = 0; m < 4; ++m) _Pragma("unroll") for (int k = 0; k < 2; ++k) dst[m][k] = *(const PG8_LAS bf16x8*)(lds + PG8_SA(b, h) + aoff + m * 2048 + k * 1024); } while (0)
; #define PG8_LDB(dst, b, h) do { _Pragma("unroll") for (int n = 0; n < 2; ++n) _Pragma("unroll") for (int k = 0; k < 2; ++k) dst[n][k] = *(const PG8_LAS bf16x8*)(lds + PG8_SB(b, h) + boff + n * 2048 + k * 1024); } while (0)
; #define PG8_MMA(ai, bj, At, Bt) do { __builtin_amdgcn_s_setprio(1); _Pragma("unroll") for (int m = 0; m < 4; ++m) _Pragma("unroll") for (int n = 0; n < 2; ++n) _Pragma("unroll") for (int k = 0; k < 2; ++k) \
;         acc[ai][bj][m][n] = __builtin_amdgcn_mfma_f32_16x16x32_bf16(Bt[n][k], At[m][k], acc[ai][bj][m][n], 0, 0, 0); __builtin_amdgcn_s_setprio(0); } while (0)
; #define PG8_WAIT_V(n) asm volatile("s_waitcnt vmcnt(" #n ")" ::: "memory")
; template <class Epi, class Sched, bool ALIGN_EPI = false, bool SP2 = false>
; __device__ __forceinline__ void gemm_phase(PG8_LAS unsigned char* lds, const Gemm g, const Sched& S, const Epi& E) {
;     ...
;             PG8_LDB(B0, 0, 0); PG8_LDB(B1, 0, 1); PG8_SCHED; PG8_LDA(At, 0, 0); PG8_STAGE(PG8_SA(1, 1), a1 + hstep, voffA);
;             PG8_WAIT_V(8); PG8_WAIT_L(0); PG8_BAR; PG8_MMA(0, 0, At, B0); PG8_MMA(0, 1, At, B1); PG8_BAR; PG8_SCHED;
;             PG8_LDA(At, 0, 1); PG8_STAGE(PG8_SB(0, 0), b2, voffB); PG8_STAGE(PG8_SB(0, 1), b2 + hstep, voffB); PG8_STAGE(PG8_SA(0, 0), a2, voffA);
;             PG8_WAIT_V(8); PG8_WAIT_L(0); PG8_BAR; PG8_MMA(1, 0, At, B0); PG8_MMA(1, 1, At, B1); PG8_BAR; PG8_SCHED;
;             PG8_LDB(B0, 1, 0); PG8_LDB(B1, 1, 1); PG8_SCHED; PG8_LDA(At, 1, 0); PG8_STAGE(PG8_SA(0, 1), a2 + hstep, voffA);
;             PG8_WAIT_V(8); PG8_WAIT_L(0); PG8_BAR; PG8_MMA(0, 0, At, B0); PG8_MMA(0, 1, At, B1); PG8_BAR; PG8_SCHED;
;             PG8_LDA(At, 1, 1); PG8_STAGE(PG8_SB(1, 0), b3, voffB); PG8_STAGE(PG8_SB(1, 1), b3 + hstep, voffB); PG8_STAGE(PG8_SA(1, 0), a3, voffA);
;             PG8_WAIT_V(8); PG8_WAIT_L(0); PG8_BAR; PG8_MMA(1, 0, At, B0); PG8_MMA(1, 1, At, B1); PG8_BAR; PG8_SCHED;
	s_add_i32 s28, s52, s30
	v_lshl_add_u64 v[184:185], v[184:185], 0, s[16:17]
	s_mov_b32 m0, s28
	ds_read_b128 v[180:183], v192 offset:49152
	ds_read_b128 v[194:197], v192 offset:50176
	ds_read_b128 v[198:201], v192 offset:51200
	ds_read_b128 v[202:205], v192 offset:52224
	ds_read_b128 v[206:209], v192 offset:53248
	ds_read_b128 v[210:213], v192 offset:54272
	ds_read_b128 v[214:217], v192 offset:55296
	ds_read_b128 v[218:221], v192 offset:56320
	global_load_lds_dwordx4 v[184:185], off
	s_add_i32 m0, s28, 0x2000
	s_add_u32 s6, s6, 0x80080
	v_lshl_add_u64 v[184:185], v[222:223], 0, s[16:17]
	s_addc_u32 s7, s7, 0
	s_add_i32 s28, s53, s30
	global_load_lds_dwordx4 v[184:185], off
	v_lshl_add_u64 v[184:185], s[6:7], 0, v[164:165]
	s_mov_b32 m0, s28
	s_nop 0
	global_load_lds_dwordx4 v[184:185], off
	v_lshl_add_u64 v[184:185], s[6:7], 0, v[168:169]
	s_add_i32 m0, s28, 0x2000
	s_nop 0
	global_load_lds_dwordx4 v[184:185], off
	v_lshl_add_u64 v[184:185], v[224:225], 0, s[16:17]
	s_mov_b32 m0, s38
	s_nop 0
	global_load_lds_dwordx4 v[184:185], off
	v_lshl_add_u64 v[184:185], v[226:227], 0, s[16:17]
	s_mov_b32 m0, s39
	s_nop 0
	global_load_lds_dwordx4 v[184:185], off
	s_waitcnt vmcnt(8)
	s_waitcnt lgkmcnt(0)
	s_barrier
	v_mfma_f32_16x16x32_bf16 v[60:63], v[128:131], v[180:183], v[60:63]
	v_mfma_f32_16x16x32_bf16 v[56:59], v[136:139], v[180:183], v[56:59]
	v_mfma_f32_16x16x32_bf16 v[44:47], v[128:131], v[198:201], v[44:47]
	v_mfma_f32_16x16x32_bf16 v[40:43], v[136:139], v[198:201], v[40:43]
	v_mfma_f32_16x16x32_bf16 v[28:31], v[128:131], v[206:209], v[28:31]
	v_mfma_f32_16x16x32_bf16 v[24:27], v[136:139], v[206:209], v[24:27]
	v_mfma_f32_16x16x32_bf16 v[12:15], v[128:131], v[214:217], v[12:15]
	v_mfma_f32_16x16x32_bf16 v[8:11], v[136:139], v[214:217], v[8:11]
	v_mfma_f32_16x16x32_bf16 v[60:63], v[132:135], v[194:197], v[60:63]
	v_mfma_f32_16x16x32_bf16 v[56:59], v[140:143], v[194:197], v[56:59]
	v_mfma_f32_16x16x32_bf16 v[44:47], v[132:135], v[202:205], v[44:47]
	v_mfma_f32_16x16x32_bf16 v[40:43], v[140:143], v[202:205], v[40:43]
	v_mfma_f32_16x16x32_bf16 v[28:31], v[132:135], v[210:213], v[28:31]
	v_mfma_f32_16x16x32_bf16 v[24:27], v[140:143], v[210:213], v[24:27]
	v_mfma_f32_16x16x32_bf16 v[12:15], v[132:135], v[218:221], v[12:15]
	v_mfma_f32_16x16x32_bf16 v[8:11], v[140:143], v[218:221], v[8:11]
	v_mfma_f32_16x16x32_bf16 v[52:55], v[144:147], v[180:183], v[52:55]
	v_mfma_f32_16x16x32_bf16 v[48:51], v[152:155], v[180:183], v[48:51]
	v_mfma_f32_16x16x32_bf16 v[36:39], v[144:147], v[198:201], v[36:39]
	v_mfma_f32_16x16x32_bf16 v[32:35], v[152:155], v[198:201], v[32:35]
	v_mfma_f32_16x16x32_bf16 v[20:23], v[144:147], v[206:209], v[20:23]
	v_mfma_f32_16x16x32_bf16 v[16:19], v[152:155], v[206:209], v[16:19]
	v_mfma_f32_16x16x32_bf16 v[4:7], v[144:147], v[214:217], v[4:7]
	v_mfma_f32_16x16x32_bf16 v[0:3], v[152:155], v[214:217], v[0:3]
	v_mfma_f32_16x16x32_bf16 v[52:55], v[148:151], v[194:197], v[52:55]
	v_mfma_f32_16x16x32_bf16 v[48:51], v[156:159], v[194:197], v[48:51]
	v_mfma_f32_16x16x32_bf16 v[36:39], v[148:151], v[202:205], v[36:39]
	v_mfma_f32_16x16x32_bf16 v[32:35], v[156:159], v[202:205], v[32:35]
	v_mfma_f32_16x16x32_bf16 v[20:23], v[148:151], v[210:213], v[20:23]
	v_mfma_f32_16x16x32_bf16 v[16:19], v[156:159], v[210:213], v[16:19]
	v_mfma_f32_16x16x32_bf16 v[4:7], v[148:151], v[218:221], v[4:7]
	v_mfma_f32_16x16x32_bf16 v[0:3], v[156:159], v[218:221], v[0:3]
	s_barrier
	s_add_i32 s51, s51, 2
	s_add_u32 s4, s4, 0x100
	s_addc_u32 s5, s5, 0
	s_add_u32 s33, s33, 0x100
	s_addc_u32 s50, s50, 0
	s_cmp_gt_u32 s51, 29
.LBB0_205:
	ds_read_b128 v[128:131], v190
	ds_read_b128 v[132:135], v190 offset:1024
	ds_read_b128 v[136:139], v190 offset:2048
	ds_read_b128 v[140:143], v190 offset:3072
	ds_read_b128 v[144:147], v191
	ds_read_b128 v[148:151], v191 offset:1024
	ds_read_b128 v[152:155], v191 offset:2048
	ds_read_b128 v[156:159], v191 offset:3072
	s_add_u32 s6, s4, 0xfff80080
	s_addc_u32 s7, s5, -1
	s_cmp_eq_u32 s51, 28
	s_cselect_b32 s29, s1, s7
	s_cselect_b32 s28, s3, s6
	s_cselect_b32 s7, s21, s50
	s_cselect_b32 s6, s23, s33
	v_lshl_add_u64 v[184:185], s[4:5], 0, v[172:173]
	s_add_i32 m0, s31, 0xc000
	ds_read_b128 v[180:183], v192
	ds_read_b128 v[194:197], v192 offset:1024
	ds_read_b128 v[198:201], v192 offset:2048
	ds_read_b128 v[202:205], v192 offset:3072
	ds_read_b128 v[206:209], v192 offset:4096
	ds_read_b128 v[210:213], v192 offset:5120
	ds_read_b128 v[214:217], v192 offset:6144
	ds_read_b128 v[218:221], v192 offset:7168
	global_load_lds_dwordx4 v[184:185], off
	v_lshl_add_u64 v[184:185], s[4:5], 0, v[174:175]
	s_add_i32 m0, s31, 0xe000
	s_nop 0
	global_load_lds_dwordx4 v[184:185], off
	s_waitcnt vmcnt(8)
	s_waitcnt lgkmcnt(0)
	s_barrier
; #define PG8_STAGE(bufoff, gbase, voff) do { _Pragma("unroll") for (int _i = 0; _i < 2; ++_i) \
;         __builtin_amdgcn_global_load_lds((const unsigned*)((const char*)(gbase) + (voff)[_i]), (PG8_LAS unsigned*)(lds + (bufoff) + ldsw + _i * 8192), 16, 0, 0); } while (0)
; #define PG8_LDA(dst, b, h) do { _Pragma("unroll") for (int m = 0; m < 4; ++m) _Pragma("unroll") for (int k = 0; k < 2; ++k) dst[m][k] = *(const PG8_LAS bf16x8*)(lds + PG8_SA(b, h) + aoff + m * 2048 + k * 1024); } while (0)
; #define PG8_LDB(dst, b, h) do { _Pragma("unroll") for (int n = 0; n < 2; ++n) _Pragma("unroll") for (int k = 0; k < 2; ++k) dst[n][k] = *(const PG8_LAS bf16x8*)(lds + PG8_SB(b, h) + boff + n * 2048 + k * 1024); } while (0)
; #define PG8_MMA(ai, bj, At, Bt) do { __builtin_amdgcn_s_setprio(1); _Pragma("unroll") for (int m = 0; m < 4; ++m) _Pragma("unroll") for (int n = 0; n < 2; ++n) _Pragma("unroll") for (int k = 0; k < 2; ++k) \
;         acc[ai][bj][m][n] = __builtin_amdgcn_mfma_f32_16x16x32_bf16(Bt[n][k], At[m][k], acc[ai][bj][m][n], 0, 0, 0); __builtin_amdgcn_s_setprio(0); } while (0)
; #define PG8_WAIT_V(n) asm volatile("s_waitcnt vmcnt(" #n ")" ::: "memory")
; template <class Epi, class Sched, bool ALIGN_EPI = false, bool SP2 = false>
; __device__ __forceinline__ void gemm_phase(PG8_LAS unsigned char* lds, const Gemm g, const Sched& S, const Epi& E) {
;     ...
;             PG8_LDB(B0, 0, 0); PG8_LDB(B1, 0, 1); PG8_SCHED; PG8_LDA(At, 0, 0); PG8_STAGE(PG8_SA(1, 1), a1 + hstep, voffA);
;             PG8_WAIT_V(8); PG8_WAIT_L(0); PG8_BAR; PG8_MMA(0, 0, At, B0); PG8_MMA(0, 1, At, B1); PG8_BAR; PG8_SCHED;
;             PG8_LDA(At, 0, 1); PG8_STAGE(PG8_SB(0, 0), b2, voffB); PG8_STAGE(PG8_SB(0, 1), b2 + hstep, voffB); PG8_STAGE(PG8_SA(0, 0), a2, voffA);
;             PG8_WAIT_V(8); PG8_WAIT_L(0); PG8_BAR; PG8_MMA(1, 0, At, B0); PG8_MMA(1, 1, At, B1); PG8_BAR; PG8_SCHED;
;             PG8_LDB(B0, 1, 0); PG8_LDB(B1, 1, 1); PG8_SCHED; PG8_LDA(At, 1, 0); PG8_STAGE(PG8_SA(0, 1), a2 + hstep, voffA);
;             PG8_WAIT_V(8); PG8_WAIT_L(0); PG8_BAR; PG8_MMA(0, 0, At, B0); PG8_MMA(0, 1, At, B1); PG8_BAR; PG8_SCHED;
;             PG8_LDA(At, 1, 1); PG8_STAGE(PG8_SB(1, 0), b3, voffB); PG8_STAGE(PG8_SB(1, 1), b3 + hstep, voffB); PG8_STAGE(PG8_SA(1, 0), a3, voffA);
;             PG8_WAIT_V(8); PG8_WAIT_L(0); PG8_BAR; PG8_MMA(1, 0, At, B0); PG8_MMA(1, 1, At, B1); PG8_BAR; PG8_SCHED;
	v_mfma_f32_16x16x32_bf16 v[124:127], v[128:131], v[180:183], v[124:127]
	v_mfma_f32_16x16x32_bf16 v[120:123], v[136:139], v[180:183], v[120:123]
	v_mfma_f32_16x16x32_bf16 v[108:111], v[128:131], v[198:201], v[108:111]
	v_mfma_f32_16x16x32_bf16 v[104:107], v[136:139], v[198:201], v[104:107]
	v_mfma_f32_16x16x32_bf16 v[92:95], v[128:131], v[206:209], v[92:95]
	v_mfma_f32_16x16x32_bf16 v[88:91], v[136:139], v[206:209], v[88:91]
	v_mfma_f32_16x16x32_bf16 v[76:79], v[128:131], v[214:217], v[76:79]
	v_mfma_f32_16x16x32_bf16 v[72:75], v[136:139], v[214:217], v[72:75]
	v_mfma_f32_16x16x32_bf16 v[124:127], v[132:135], v[194:197], v[124:127]
	v_mfma_f32_16x16x32_bf16 v[120:123], v[140:143], v[194:197], v[120:123]
	v_mfma_f32_16x16x32_bf16 v[108:111], v[132:135], v[202:205], v[108:111]
	v_mfma_f32_16x16x32_bf16 v[104:107], v[140:143], v[202:205], v[104:107]
	v_mfma_f32_16x16x32_bf16 v[92:95], v[132:135], v[210:213], v[92:95]
	v_mfma_f32_16x16x32_bf16 v[88:91], v[140:143], v[210:213], v[88:91]
	v_mfma_f32_16x16x32_bf16 v[76:79], v[132:135], v[218:221], v[76:79]
	v_mfma_f32_16x16x32_bf16 v[72:75], v[140:143], v[218:221], v[72:75]
	v_mfma_f32_16x16x32_bf16 v[116:119], v[144:147], v[180:183], v[116:119]
	v_mfma_f32_16x16x32_bf16 v[112:115], v[152:155], v[180:183], v[112:115]
	v_mfma_f32_16x16x32_bf16 v[100:103], v[144:147], v[198:201], v[100:103]
	v_mfma_f32_16x16x32_bf16 v[96:99], v[152:155], v[198:201], v[96:99]
	v_mfma_f32_16x16x32_bf16 v[84:87], v[144:147], v[206:209], v[84:87]
	v_mfma_f32_16x16x32_bf16 v[80:83], v[152:155], v[206:209], v[80:83]
	v_mfma_f32_16x16x32_bf16 v[68:71], v[144:147], v[214:217], v[68:71]
	v_mfma_f32_16x16x32_bf16 v[64:67], v[152:155], v[214:217], v[64:67]
	v_mfma_f32_16x16x32_bf16 v[116:119], v[148:151], v[194:197], v[116:119]
	v_mfma_f32_16x16x32_bf16 v[112:115], v[156:159], v[194:197], v[112:115]
	v_mfma_f32_16x16x32_bf16 v[100:103], v[148:151], v[202:205], v[100:103]
	v_mfma_f32_16x16x32_bf16 v[96:99], v[156:159], v[202:205], v[96:99]
	v_mfma_f32_16x16x32_bf16 v[84:87], v[148:151], v[210:213], v[84:87]
	v_mfma_f32_16x16x32_bf16 v[80:83], v[156:159], v[210:213], v[80:83]
	v_mfma_f32_16x16x32_bf16 v[68:71], v[148:151], v[218:221], v[68:71]
	v_mfma_f32_16x16x32_bf16 v[64:67], v[156:159], v[218:221], v[64:67]
	s_barrier
	s_add_i32 s52, s43, s30
	v_lshl_add_u64 v[184:185], s[6:7], 0, v[164:165]
	s_mov_b32 m0, s52
	ds_read_b128 v[180:183], v192 offset:16384
	ds_read_b128 v[194:197], v192 offset:17408
	ds_read_b128 v[198:201], v192 offset:18432
	ds_read_b128 v[202:205], v192 offset:19456
	ds_read_b128 v[206:209], v192 offset:20480
	ds_read_b128 v[210:213], v192 offset:21504
	ds_read_b128 v[214:217], v192 offset:22528
	ds_read_b128 v[218:221], v192 offset:23552
	global_load_lds_dwordx4 v[184:185], off
	s_add_i32 m0, s52, 0x2000
	s_add_u32 s52, s6, 0x80000
	v_lshl_add_u64 v[222:223], s[6:7], 0, v[168:169]
	s_addc_u32 s53, s7, 0
	s_add_i32 s54, s44, s30
	global_load_lds_dwordx4 v[222:223], off
	v_lshl_add_u64 v[224:225], s[52:53], 0, v[164:165]
	s_mov_b32 m0, s54
	v_lshl_add_u64 v[226:227], s[28:29], 0, v[166:167]
	global_load_lds_dwordx4 v[224:225], off
	v_lshl_add_u64 v[224:225], s[52:53], 0, v[168:169]
	s_add_i32 m0, s54, 0x2000
	s_nop 0
	global_load_lds_dwordx4 v[224:225], off
	v_lshl_add_u64 v[224:225], s[28:29], 0, v[162:163]
	s_mov_b32 m0, s31
	s_nop 0
	global_load_lds_dwordx4 v[224:225], off
	s_mov_b32 m0, s34
	s_nop 0
	global_load_lds_dwordx4 v[226:227], off
	s_waitcnt vmcnt(8)
	s_waitcnt lgkmcnt(0)
	s_barrier
	v_mfma_f32_16x16x32_bf16 v[60:63], v[128:131], v[180:183], v[60:63]
	v_mfma_f32_16x16x32_bf16 v[56:59], v[136:139], v[180:183], v[56:59]
	v_mfma_f32_16x16x32_bf16 v[44:47], v[128:131], v[198:201], v[44:47]
	v_mfma_f32_16x16x32_bf16 v[40:43], v[136:139], v[198:201], v[40:43]
	v_mfma_f32_16x16x32_bf16 v[28:31], v[128:131], v[206:209], v[28:31]
	v_mfma_f32_16x16x32_bf16 v[24:27], v[136:139], v[206:209], v[24:27]
	v_mfma_f32_16x16x32_bf16 v[12:15], v[128:131], v[214:217], v[12:15]
	v_mfma_f32_16x16x32_bf16 v[8:11], v[136:139], v[214:217], v[8:11]
	v_mfma_f32_16x16x32_bf16 v[60:63], v[132:135], v[194:197], v[60:63]
	v_mfma_f32_16x16x32_bf16 v[56:59], v[140:143], v[194:197], v[56:59]
	v_mfma_f32_16x16x32_bf16 v[44:47], v[132:135], v[202:205], v[44:47]
	v_mfma_f32_16x16x32_bf16 v[40:43], v[140:143], v[202:205], v[40:43]
	v_mfma_f32_16x16x32_bf16 v[28:31], v[132:135], v[210:213], v[28:31]
	v_mfma_f32_16x16x32_bf16 v[24:27], v[140:143], v[210:213], v[24:27]
	v_mfma_f32_16x16x32_bf16 v[12:15], v[132:135], v[218:221], v[12:15]
	v_mfma_f32_16x16x32_bf16 v[8:11], v[140:143], v[218:221], v[8:11]
	v_mfma_f32_16x16x32_bf16 v[52:55], v[144:147], v[180:183], v[52:55]
	v_mfma_f32_16x16x32_bf16 v[48:51], v[152:155], v[180:183], v[48:51]
	v_mfma_f32_16x16x32_bf16 v[36:39], v[144:147], v[198:201], v[36:39]
	v_mfma_f32_16x16x32_bf16 v[32:35], v[152:155], v[198:201], v[32:35]
	v_mfma_f32_16x16x32_bf16 v[20:23], v[144:147], v[206:209], v[20:23]
	v_mfma_f32_16x16x32_bf16 v[16:19], v[152:155], v[206:209], v[16:19]
	v_mfma_f32_16x16x32_bf16 v[4:7], v[144:147], v[214:217], v[4:7]
	v_mfma_f32_16x16x32_bf16 v[0:3], v[152:155], v[214:217], v[0:3]
	v_mfma_f32_16x16x32_bf16 v[52:55], v[148:151], v[194:197], v[52:55]
	v_mfma_f32_16x16x32_bf16 v[48:51], v[156:159], v[194:197], v[48:51]
	v_mfma_f32_16x16x32_bf16 v[36:39], v[148:151], v[202:205], v[36:39]
	v_mfma_f32_16x16x32_bf16 v[32:35], v[156:159], v[202:205], v[32:35]
	v_mfma_f32_16x16x32_bf16 v[20:23], v[148:151], v[210:213], v[20:23]
	v_mfma_f32_16x16x32_bf16 v[16:19], v[156:159], v[210:213], v[16:19]
	v_mfma_f32_16x16x32_bf16 v[4:7], v[148:151], v[218:221], v[4:7]
	v_mfma_f32_16x16x32_bf16 v[0:3], v[156:159], v[218:221], v[0:3]
	s_barrier
; #define PG8_STAGE(bufoff, gbase, voff) do { _Pragma("unroll") for (int _i = 0; _i < 2; ++_i) \
;         __builtin_amdgcn_global_load_lds((const unsigned*)((const char*)(gbase) + (voff)[_i]), (PG8_LAS unsigned*)(lds + (bufoff) + ldsw + _i * 8192), 16, 0, 0); } while (0)
; #define PG8_LDA(dst, b, h) do { _Pragma("unroll") for (int m = 0; m < 4; ++m) _Pragma("unroll") for (int k = 0; k < 2; ++k) dst[m][k] = *(const PG8_LAS bf16x8*)(lds + PG8_SA(b, h) + aoff + m * 2048 + k * 1024); } while (0)
; #define PG8_LDB(dst, b, h) do { _Pragma("unroll") for (int n = 0; n < 2; ++n) _Pragma("unroll") for (int k = 0; k < 2; ++k) dst[n][k] = *(const PG8_LAS bf16x8*)(lds + PG8_SB(b, h) + boff + n * 2048 + k * 1024); } while (0)
; #define PG8_MMA(ai, bj, At, Bt) do { __builtin_amdgcn_s_setprio(1); _Pragma("unroll") for (int m = 0; m < 4; ++m) _Pragma("unroll") for (int n = 0; n < 2; ++n) _Pragma("unroll") for (int k = 0; k < 2; ++k) \
;         acc[ai][bj][m][n] = __builtin_amdgcn_mfma_f32_16x16x32_bf16(Bt[n][k], At[m][k], acc[ai][bj][m][n], 0, 0, 0); __builtin_amdgcn_s_setprio(0); } while (0)
; #define PG8_WAIT_V(n) asm volatile("s_waitcnt vmcnt(" #n ")" ::: "memory")
; template <class Epi, class Sched, bool ALIGN_EPI = false, bool SP2 = false>
; __device__ __forceinline__ void gemm_phase(PG8_LAS unsigned char* lds, const Gemm g, const Sched& S, const Epi& E) {
;     ...
;             PG8_LDB(B0, 0, 0); PG8_LDB(B1, 0, 1); PG8_SCHED; PG8_LDA(At, 0, 0); PG8_STAGE(PG8_SA(1, 1), a1 + hstep, voffA);
;             PG8_WAIT_V(8); PG8_WAIT_L(0); PG8_BAR; PG8_MMA(0, 0, At, B0); PG8_MMA(0, 1, At, B1); PG8_BAR; PG8_SCHED;
;             PG8_LDA(At, 0, 1); PG8_STAGE(PG8_SB(0, 0), b2, voffB); PG8_STAGE(PG8_SB(0, 1), b2 + hstep, voffB); PG8_STAGE(PG8_SA(0, 0), a2, voffA);
;             PG8_WAIT_V(8); PG8_WAIT_L(0); PG8_BAR; PG8_MMA(1, 0, At, B0); PG8_MMA(1, 1, At, B1); PG8_BAR; PG8_SCHED;
;             PG8_LDB(B0, 1, 0); PG8_LDB(B1, 1, 1); PG8_SCHED; PG8_LDA(At, 1, 0); PG8_STAGE(PG8_SA(0, 1), a2 + hstep, voffA);
;             PG8_WAIT_V(8); PG8_WAIT_L(0); PG8_BAR; PG8_MMA(0, 0, At, B0); PG8_MMA(0, 1, At, B1); PG8_BAR; PG8_SCHED;
;             PG8_LDA(At, 1, 1); PG8_STAGE(PG8_SB(1, 0), b3, voffB); PG8_STAGE(PG8_SB(1, 1), b3 + hstep, voffB); PG8_STAGE(PG8_SA(1, 0), a3, voffA);
;             PG8_WAIT_V(8); PG8_WAIT_L(0); PG8_BAR; PG8_MMA(1, 0, At, B0); PG8_MMA(1, 1, At, B1); PG8_BAR; PG8_SCHED;
	s_add_i32 s52, 0, 0x18000
	s_add_i32 s53, 0, 0x1c000
	v_add_u32_e32 v140, s52, v188
	v_add_u32_e32 v156, s53, v188
	ds_read_b128 v[128:131], v140
	ds_read_b128 v[132:135], v140 offset:1024
	ds_read_b128 v[136:139], v140 offset:2048
	ds_read_b128 v[140:143], v140 offset:3072
	ds_read_b128 v[144:147], v156
	ds_read_b128 v[148:151], v156 offset:1024
	ds_read_b128 v[152:155], v156 offset:2048
	ds_read_b128 v[156:159], v156 offset:3072
	s_add_u32 s28, s28, 0x80000
	s_addc_u32 s29, s29, 0
	s_mov_b32 m0, s35
	v_lshl_add_u64 v[228:229], s[28:29], 0, v[162:163]
	ds_read_b128 v[180:183], v192 offset:32768
	ds_read_b128 v[194:197], v192 offset:33792
	ds_read_b128 v[198:201], v192 offset:34816
	ds_read_b128 v[202:205], v192 offset:35840
	ds_read_b128 v[206:209], v192 offset:36864
	ds_read_b128 v[210:213], v192 offset:37888
	ds_read_b128 v[214:217], v192 offset:38912
	ds_read_b128 v[218:221], v192 offset:39936
	global_load_lds_dwordx4 v[228:229], off
	v_lshl_add_u64 v[228:229], s[28:29], 0, v[166:167]
	s_mov_b32 m0, s36
	s_nop 0
	global_load_lds_dwordx4 v[228:229], off
	s_waitcnt vmcnt(8)
	s_waitcnt lgkmcnt(0)
	s_barrier
	v_mfma_f32_16x16x32_bf16 v[124:127], v[128:131], v[180:183], v[124:127]
	v_mfma_f32_16x16x32_bf16 v[120:123], v[136:139], v[180:183], v[120:123]
	v_mfma_f32_16x16x32_bf16 v[108:111], v[128:131], v[198:201], v[108:111]
	v_mfma_f32_16x16x32_bf16 v[104:107], v[136:139], v[198:201], v[104:107]
	v_mfma_f32_16x16x32_bf16 v[92:95], v[128:131], v[206:209], v[92:95]
	v_mfma_f32_16x16x32_bf16 v[88:91], v[136:139], v[206:209], v[88:91]
	v_mfma_f32_16x16x32_bf16 v[76:79], v[128:131], v[214:217], v[76:79]
	v_mfma_f32_16x16x32_bf16 v[72:75], v[136:139], v[214:217], v[72:75]
	v_mfma_f32_16x16x32_bf16 v[124:127], v[132:135], v[194:197], v[124:127]
	v_mfma_f32_16x16x32_bf16 v[120:123], v[140:143], v[194:197], v[120:123]
	v_mfma_f32_16x16x32_bf16 v[108:111], v[132:135], v[202:205], v[108:111]
	v_mfma_f32_16x16x32_bf16 v[104:107], v[140:143], v[202:205], v[104:107]
	v_mfma_f32_16x16x32_bf16 v[92:95], v[132:135], v[210:213], v[92:95]
	v_mfma_f32_16x16x32_bf16 v[88:91], v[140:143], v[210:213], v[88:91]
	v_mfma_f32_16x16x32_bf16 v[76:79], v[132:135], v[218:221], v[76:79]
	v_mfma_f32_16x16x32_bf16 v[72:75], v[140:143], v[218:221], v[72:75]
	v_mfma_f32_16x16x32_bf16 v[116:119], v[144:147], v[180:183], v[116:119]
	v_mfma_f32_16x16x32_bf16 v[112:115], v[152:155], v[180:183], v[112:115]
	v_mfma_f32_16x16x32_bf16 v[100:103], v[144:147], v[198:201], v[100:103]
	v_mfma_f32_16x16x32_bf16 v[96:99], v[152:155], v[198:201], v[96:99]
	v_mfma_f32_16x16x32_bf16 v[84:87], v[144:147], v[206:209], v[84:87]
	v_mfma_f32_16x16x32_bf16 v[80:83], v[152:155], v[206:209], v[80:83]
	v_mfma_f32_16x16x32_bf16 v[68:71], v[144:147], v[214:217], v[68:71]
	v_mfma_f32_16x16x32_bf16 v[64:67], v[152:155], v[214:217], v[64:67]
	v_mfma_f32_16x16x32_bf16 v[116:119], v[148:151], v[194:197], v[116:119]
	v_mfma_f32_16x16x32_bf16 v[112:115], v[156:159], v[194:197], v[112:115]
	v_mfma_f32_16x16x32_bf16 v[100:103], v[148:151], v[202:205], v[100:103]
	v_mfma_f32_16x16x32_bf16 v[96:99], v[156:159], v[202:205], v[96:99]
	v_mfma_f32_16x16x32_bf16 v[84:87], v[148:151], v[210:213], v[84:87]
	v_mfma_f32_16x16x32_bf16 v[80:83], v[156:159], v[210:213], v[80:83]
	v_mfma_f32_16x16x32_bf16 v[68:71], v[148:151], v[218:221], v[68:71]
	v_mfma_f32_16x16x32_bf16 v[64:67], v[156:159], v[218:221], v[64:67]
	s_barrier
; #define PG8_STAGE(bufoff, gbase, voff) do { _Pragma("unroll") for (int _i = 0; _i < 2; ++_i) \
;         __builtin_amdgcn_global_load_lds((const unsigned*)((const char*)(gbase) + (voff)[_i]), (PG8_LAS unsigned*)(lds + (bufoff) + ldsw + _i * 8192), 16, 0, 0); } while (0)
; #define PG8_LDA(dst, b, h) do { _Pragma("unroll") for (int m = 0; m < 4; ++m) _Pragma("unroll") for (int k = 0; k < 2; ++k) dst[m][k] = *(const PG8_LAS bf16x8*)(lds + PG8_SA(b, h) + aoff + m * 2048 + k * 1024); } while (0)
; #define PG8_LDB(dst, b, h) do { _Pragma("unroll") for (int n = 0; n < 2; ++n) _Pragma("unroll") for (int k = 0; k < 2; ++k) dst[n][k] = *(const PG8_LAS bf16x8*)(lds + PG8_SB(b, h) + boff + n * 2048 + k * 1024); } while (0)
; #define PG8_MMA(ai, bj, At, Bt) do { __builtin_amdgcn_s_setprio(1); _Pragma("unroll") for (int m = 0; m < 4; ++m) _Pragma("unroll") for (int n = 0; n < 2; ++n) _Pragma("unroll") for (int k = 0; k < 2; ++k) \
;         acc[ai][bj][m][n] = __builtin_amdgcn_mfma_f32_16x16x32_bf16(Bt[n][k], At[m][k], acc[ai][bj][m][n], 0, 0, 0); __builtin_amdgcn_s_setprio(0); } while (0)
; template <class Epi, class Sched, bool ALIGN_EPI = false, bool SP2 = false>
; __device__ __forceinline__ void gemm_phase(PG8_LAS unsigned char* lds, const Gemm g, const Sched& S, const Epi& E) {
;     ...
;             PG8_LDB(B0, 0, 0); PG8_LDB(B1, 0, 1); PG8_SCHED; PG8_LDA(At, 0, 0); PG8_STAGE(PG8_SA(1, 1), a1 + hstep, voffA);
;             PG8_WAIT_V(8); PG8_WAIT_L(0); PG8_BAR; PG8_MMA(0, 0, At, B0); PG8_MMA(0, 1, At, B1); PG8_BAR; PG8_SCHED;
;             PG8_LDA(At, 0, 1); PG8_STAGE(PG8_SB(0, 0), b2, voffB); PG8_STAGE(PG8_SB(0, 1), b2 + hstep, voffB); PG8_STAGE(PG8_SA(0, 0), a2, voffA);
;             PG8_WAIT_V(8); PG8_WAIT_L(0); PG8_BAR; PG8_MMA(1, 0, At, B0); PG8_MMA(1, 1, At, B1); PG8_BAR; PG8_SCHED;
;             PG8_LDB(B0, 1, 0); PG8_LDB(B1, 1, 1); PG8_SCHED; PG8_LDA(At, 1, 0); PG8_STAGE(PG8_SA(0, 1), a2 + hstep, voffA);
;             PG8_WAIT_V(8); PG8_WAIT_L(0); PG8_BAR; PG8_MMA(0, 0, At, B0); PG8_MMA(0, 1, At, B1); PG8_BAR; PG8_SCHED;
;             PG8_LDA(At, 1, 1); PG8_STAGE(PG8_SB(1, 0), b3, voffB); PG8_STAGE(PG8_SB(1, 1), b3 + hstep, voffB); PG8_STAGE(PG8_SA(1, 0), a3, voffA);
;             PG8_WAIT_V(8); PG8_WAIT_L(0); PG8_BAR; PG8_MMA(1, 0, At, B0); PG8_MMA(1, 1, At, B1); PG8_BAR; PG8_SCHED;
;     ...
;         if constexpr (ALIGN_EPI) { if (wr == 0) PG8_BAR; }
	s_add_i32 s28, s52, s30
	v_lshl_add_u64 v[184:185], v[184:185], 0, s[16:17]
	s_mov_b32 m0, s28
	ds_read_b128 v[180:183], v192 offset:49152
	ds_read_b128 v[194:197], v192 offset:50176
	ds_read_b128 v[198:201], v192 offset:51200
	ds_read_b128 v[202:205], v192 offset:52224
	ds_read_b128 v[206:209], v192 offset:53248
	ds_read_b128 v[210:213], v192 offset:54272
	ds_read_b128 v[214:217], v192 offset:55296
	ds_read_b128 v[218:221], v192 offset:56320
	global_load_lds_dwordx4 v[184:185], off
	s_add_i32 m0, s28, 0x2000
	s_add_u32 s6, s6, 0x80080
	v_lshl_add_u64 v[184:185], v[222:223], 0, s[16:17]
	s_addc_u32 s7, s7, 0
	s_add_i32 s28, s53, s30
	global_load_lds_dwordx4 v[184:185], off
	v_lshl_add_u64 v[184:185], s[6:7], 0, v[164:165]
	s_mov_b32 m0, s28
	s_nop 0
	global_load_lds_dwordx4 v[184:185], off
	v_lshl_add_u64 v[184:185], s[6:7], 0, v[168:169]
	s_add_i32 m0, s28, 0x2000
	s_nop 0
	global_load_lds_dwordx4 v[184:185], off
	v_lshl_add_u64 v[184:185], v[224:225], 0, s[16:17]
	s_mov_b32 m0, s38
	s_nop 0
	global_load_lds_dwordx4 v[184:185], off
	v_lshl_add_u64 v[184:185], v[226:227], 0, s[16:17]
	s_mov_b32 m0, s39
	s_nop 0
	global_load_lds_dwordx4 v[184:185], off
	s_waitcnt vmcnt(8)
	s_waitcnt lgkmcnt(0)
	s_barrier
	v_mfma_f32_16x16x32_bf16 v[60:63], v[128:131], v[180:183], v[60:63]
	v_mfma_f32_16x16x32_bf16 v[56:59], v[136:139], v[180:183], v[56:59]
	v_mfma_f32_16x16x32_bf16 v[44:47], v[128:131], v[198:201], v[44:47]
	v_mfma_f32_16x16x32_bf16 v[40:43], v[136:139], v[198:201], v[40:43]
	v_mfma_f32_16x16x32_bf16 v[28:31], v[128:131], v[206:209], v[28:31]
	v_mfma_f32_16x16x32_bf16 v[24:27], v[136:139], v[206:209], v[24:27]
	v_mfma_f32_16x16x32_bf16 v[12:15], v[128:131], v[214:217], v[12:15]
	v_mfma_f32_16x16x32_bf16 v[8:11], v[136:139], v[214:217], v[8:11]
	v_mfma_f32_16x16x32_bf16 v[60:63], v[132:135], v[194:197], v[60:63]
	v_mfma_f32_16x16x32_bf16 v[56:59], v[140:143], v[194:197], v[56:59]
	v_mfma_f32_16x16x32_bf16 v[44:47], v[132:135], v[202:205], v[44:47]
	v_mfma_f32_16x16x32_bf16 v[40:43], v[140:143], v[202:205], v[40:43]
	v_mfma_f32_16x16x32_bf16 v[28:31], v[132:135], v[210:213], v[28:31]
	v_mfma_f32_16x16x32_bf16 v[24:27], v[140:143], v[210:213], v[24:27]
	v_mfma_f32_16x16x32_bf16 v[12:15], v[132:135], v[218:221], v[12:15]
	v_mfma_f32_16x16x32_bf16 v[8:11], v[140:143], v[218:221], v[8:11]
	v_mfma_f32_16x16x32_bf16 v[52:55], v[144:147], v[180:183], v[52:55]
	v_mfma_f32_16x16x32_bf16 v[48:51], v[152:155], v[180:183], v[48:51]
	v_mfma_f32_16x16x32_bf16 v[36:39], v[144:147], v[198:201], v[36:39]
	v_mfma_f32_16x16x32_bf16 v[32:35], v[152:155], v[198:201], v[32:35]
	v_mfma_f32_16x16x32_bf16 v[20:23], v[144:147], v[206:209], v[20:23]
	v_mfma_f32_16x16x32_bf16 v[16:19], v[152:155], v[206:209], v[16:19]
	v_mfma_f32_16x16x32_bf16 v[4:7], v[144:147], v[214:217], v[4:7]
	v_mfma_f32_16x16x32_bf16 v[0:3], v[152:155], v[214:217], v[0:3]
	v_mfma_f32_16x16x32_bf16 v[52:55], v[148:151], v[194:197], v[52:55]
	v_mfma_f32_16x16x32_bf16 v[48:51], v[156:159], v[194:197], v[48:51]
	v_mfma_f32_16x16x32_bf16 v[36:39], v[148:151], v[202:205], v[36:39]
	v_mfma_f32_16x16x32_bf16 v[32:35], v[156:159], v[202:205], v[32:35]
	v_mfma_f32_16x16x32_bf16 v[20:23], v[148:151], v[210:213], v[20:23]
	v_mfma_f32_16x16x32_bf16 v[16:19], v[156:159], v[210:213], v[16:19]
	v_mfma_f32_16x16x32_bf16 v[4:7], v[148:151], v[218:221], v[4:7]
	v_mfma_f32_16x16x32_bf16 v[0:3], v[156:159], v[218:221], v[0:3]
	s_barrier
	s_add_i32 s51, s51, 2
	s_add_u32 s4, s4, 0x100
	s_addc_u32 s5, s5, 0
	s_add_u32 s33, s33, 0x100
	s_addc_u32 s50, s50, 0
	s_cmp_gt_u32 s51, 29
	s_cbranch_scc0 .LBB0_205
	s_setprio 0
	s_and_b64 vcc, exec, s[18:19]
	s_cbranch_vccz .LBB0_208
	s_barrier

;     __device__ __forceinline__ bool next(int i, Unit& u) const { if (!base.next(i >> 1, u)) return false; if (i & 1) { u.pm += 64; u.pn += 8; } return true; }
; #define PG8_STAGE(bufoff, gbase, voff) do { _Pragma("unroll") for (int _i = 0; _i < 2; ++_i) \
;         __builtin_amdgcn_global_load_lds((const unsigned*)((const char*)(gbase) + (voff)[_i]), (PG8_LAS unsigned*)(lds + (bufoff) + ldsw + _i * 8192), 16, 0, 0); } while (0)
; #define PG8_WAIT_V(n) asm volatile("s_waitcnt vmcnt(" #n ")" ::: "memory")
; template <class Epi, class Sched, bool ALIGN_EPI = false, bool SP2 = false>
; __device__ __forceinline__ void gemm_phase(PG8_LAS unsigned char* lds, const Gemm g, const Sched& S, const Epi& E) {
;     ...
;         const bool has_next = S.next(ui + 1, nxt);
;         const char* nA = has_next ? (const char*)g.A + (size_t)nxt.pm * tstep : cA; const char* nB = has_next ? (const char*)g.Bt + (size_t)nxt.pn * tstep : cB;
;         for (int t = 0; t < nt; t += 2) {
;             const bool last = (t == nt - 2);
;             const char* a1 = cA + (size_t)(t + 1) * kstep;
;             const char* a2 = last ? nA : cA + (size_t)(t + 2) * kstep; const char* b2 = last ? nB : cB + (size_t)(t + 2) * kstep;
;             const char* a3 = a2 + kstep; const char* b3 = b2 + kstep;
;             if (last && has_next) S.a_ready(nxt);
;             if constexpr (SP2) {
;             PG8_LDB(B0, 0, 0); PG8_LDB(B1, 0, 1); PG8_SCHED; PG8_LDA(At, 0, 0); PG8_STAGE(PG8_SA(1, 1), a1 + hstep, voffA);
;             PG8_WAIT_V(8); PG8_WAIT_L(0); PG8_BAR; PG8_MMA(0, 0, At, B0); PG8_MMA(0, 1, At, B1); PG8_BAR; PG8_SCHED;
;             PG8_LDA(At, 0, 1); PG8_STAGE(PG8_SB(0, 0), b2, voffB); PG8_STAGE(PG8_SB(0, 1), b2 + hstep, voffB); PG8_STAGE(PG8_SA(0, 0), a2, voffA);
;             PG8_WAIT_V(8); PG8_WAIT_L(0); PG8_BAR; PG8_MMA(1, 0, At, B0); PG8_MMA(1, 1, At, B1); PG8_BAR; PG8_SCHED;
;             PG8_LDB(B0, 1, 0); PG8_LDB(B1, 1, 1); PG8_SCHED; PG8_LDA(At, 1, 0); PG8_STAGE(PG8_SA(0, 1), a2 + hstep, voffA);
;             PG8_WAIT_V(8); PG8_WAIT_L(0); PG8_BAR; PG8_MMA(0, 0, At, B0); PG8_MMA(0, 1, At, B1); PG8_BAR; PG8_SCHED;
;             PG8_LDA(At, 1, 1); PG8_STAGE(PG8_SB(1, 0), b3, voffB); PG8_STAGE(PG8_SB(1, 1), b3 + hstep, voffB); PG8_STAGE(PG8_SA(1, 0), a3, voffA);
;             PG8_WAIT_V(8); PG8_WAIT_L(0); PG8_BAR; PG8_MMA(1, 0, At, B0); PG8_MMA(1, 1, At, B1); PG8_BAR; PG8_SCHED;
.LBB0_571:
	s_bitcmp0_b32 s7, 0
	s_cselect_b64 s[16:17], -1, 0
	s_and_b64 s[16:17], s[16:17], s[4:5]
	s_add_i32 s7, s14, 64
	s_add_i32 s13, s12, 8
	s_and_b64 s[16:17], s[16:17], exec
	s_cselect_b32 s14, s7, s14
	s_cselect_b32 s12, s13, s12
	s_ashr_i32 s15, s14, 31
	s_lshl_b64 s[16:17], s[14:15], 19
	s_add_u32 s16, s29, s16
	s_addc_u32 s17, s30, s17
	s_and_b64 s[18:19], s[4:5], exec
	s_cselect_b32 s7, s17, s23
	s_cselect_b32 s15, s16, s22
	s_ashr_i32 s13, s12, 31
	s_lshl_b64 s[18:19], s[12:13], 19
	v_readlane_b32 s26, v236, 41
	v_readlane_b32 s27, v236, 42
	s_add_u32 s18, s26, s18
	s_addc_u32 s19, s27, s19
	s_and_b64 s[26:27], s[4:5], exec
	s_cselect_b32 s13, s19, s25
	s_cselect_b32 s21, s18, s24
	s_add_u32 s22, s22, 0x40080
	s_addc_u32 s23, s23, 0
	s_add_u32 s44, s24, 0x100
	s_addc_u32 s45, s25, 0
	s_mov_b32 s46, -2
	s_cmp_eq_u64 s[10:11], 0
	s_cbranch_scc0 .Lprio_skip_572
	s_setprio 1
.Lprio_skip_572:
	ds_read_b128 v[146:149], v159
	ds_read_b128 v[150:153], v159 offset:1024
	ds_read_b128 v[164:167], v159 offset:2048
	ds_read_b128 v[168:171], v159 offset:3072
	ds_read_b128 v[172:175], v161
	ds_read_b128 v[176:179], v161 offset:1024
	ds_read_b128 v[180:183], v161 offset:2048
	ds_read_b128 v[188:191], v161 offset:3072
	s_add_u32 s24, s22, 0xfffc0080
	s_addc_u32 s25, s23, -1
	s_cmp_eq_u32 s46, 12
	s_cselect_b32 s27, s7, s25
	s_cselect_b32 s26, s15, s24
	s_cselect_b32 s25, s13, s45
	s_cselect_b32 s24, s21, s44
	v_lshl_add_u64 v[154:155], s[22:23], 0, v[138:139]
	s_add_i32 m0, s31, 0xc000
	ds_read_b128 v[192:195], v162
	ds_read_b128 v[196:199], v162 offset:1024
	ds_read_b128 v[200:203], v162 offset:2048
	ds_read_b128 v[204:207], v162 offset:3072
	ds_read_b128 v[208:211], v162 offset:4096
	ds_read_b128 v[212:215], v162 offset:5120
	ds_read_b128 v[216:219], v162 offset:6144
	ds_read_b128 v[220:223], v162 offset:7168
	global_load_lds_dwordx4 v[154:155], off
	v_lshl_add_u64 v[154:155], s[22:23], 0, v[140:141]
	s_add_i32 m0, s31, 0xe000
	s_nop 0
	global_load_lds_dwordx4 v[154:155], off
	s_waitcnt vmcnt(8)
	s_waitcnt lgkmcnt(0)
	s_barrier
	v_mfma_f32_16x16x32_bf16 v[124:127], v[146:149], v[192:195], 0
	v_mfma_f32_16x16x32_bf16 v[120:123], v[164:167], v[192:195], 0
	v_mfma_f32_16x16x32_bf16 v[108:111], v[146:149], v[200:203], 0
	v_mfma_f32_16x16x32_bf16 v[104:107], v[164:167], v[200:203], 0
	v_mfma_f32_16x16x32_bf16 v[92:95], v[146:149], v[208:211], 0
	v_mfma_f32_16x16x32_bf16 v[88:91], v[164:167], v[208:211], 0
	v_mfma_f32_16x16x32_bf16 v[76:79], v[146:149], v[216:219], 0
	v_mfma_f32_16x16x32_bf16 v[72:75], v[164:167], v[216:219], 0
	v_mfma_f32_16x16x32_bf16 v[124:127], v[150:153], v[196:199], v[124:127]
	v_mfma_f32_16x16x32_bf16 v[120:123], v[168:171], v[196:199], v[120:123]
	v_mfma_f32_16x16x32_bf16 v[108:111], v[150:153], v[204:207], v[108:111]
	v_mfma_f32_16x16x32_bf16 v[104:107], v[168:171], v[204:207], v[104:107]
	v_mfma_f32_16x16x32_bf16 v[92:95], v[150:153], v[212:215], v[92:95]
	v_mfma_f32_16x16x32_bf16 v[88:91], v[168:171], v[212:215], v[88:91]
	v_mfma_f32_16x16x32_bf16 v[76:79], v[150:153], v[220:223], v[76:79]
	v_mfma_f32_16x16x32_bf16 v[72:75], v[168:171], v[220:223], v[72:75]
	v_mfma_f32_16x16x32_bf16 v[116:119], v[172:175], v[192:195], 0
	v_mfma_f32_16x16x32_bf16 v[112:115], v[180:183], v[192:195], 0
	v_mfma_f32_16x16x32_bf16 v[100:103], v[172:175], v[200:203], 0
	v_mfma_f32_16x16x32_bf16 v[96:99], v[180:183], v[200:203], 0
	v_mfma_f32_16x16x32_bf16 v[84:87], v[172:175], v[208:211], 0
	v_mfma_f32_16x16x32_bf16 v[80:83], v[180:183], v[208:211], 0
	v_mfma_f32_16x16x32_bf16 v[68:71], v[172:175], v[216:219], 0
	v_mfma_f32_16x16x32_bf16 v[64:67], v[180:183], v[216:219], 0
	v_mfma_f32_16x16x32_bf16 v[116:119], v[176:179], v[196:199], v[116:119]
	v_mfma_f32_16x16x32_bf16 v[112:115], v[188:191], v[196:199], v[112:115]
	v_mfma_f32_16x16x32_bf16 v[100:103], v[176:179], v[204:207], v[100:103]
	v_mfma_f32_16x16x32_bf16 v[96:99], v[188:191], v[204:207], v[96:99]
	v_mfma_f32_16x16x32_bf16 v[84:87], v[176:179], v[212:215], v[84:87]
	v_mfma_f32_16x16x32_bf16 v[80:83], v[188:191], v[212:215], v[80:83]
	v_mfma_f32_16x16x32_bf16 v[68:71], v[176:179], v[220:223], v[68:71]
	v_mfma_f32_16x16x32_bf16 v[64:67], v[188:191], v[220:223], v[64:67]
	s_barrier
	s_add_i32 s47, s39, s28
	v_lshl_add_u64 v[154:155], s[24:25], 0, v[130:131]
	s_mov_b32 m0, s47
	ds_read_b128 v[192:195], v162 offset:16384
	ds_read_b128 v[196:199], v162 offset:17408
	ds_read_b128 v[200:203], v162 offset:18432
	ds_read_b128 v[204:207], v162 offset:19456
	ds_read_b128 v[208:211], v162 offset:20480
	ds_read_b128 v[212:215], v162 offset:21504
	ds_read_b128 v[216:219], v162 offset:22528
	ds_read_b128 v[220:223], v162 offset:23552
	global_load_lds_dwordx4 v[154:155], off
	s_add_i32 m0, s47, 0x2000
	s_add_u32 s48, s24, 0x40000
	v_lshl_add_u64 v[184:185], s[24:25], 0, v[134:135]
	s_addc_u32 s49, s25, 0
	s_add_i32 s47, s40, s28
	global_load_lds_dwordx4 v[184:185], off
	v_lshl_add_u64 v[224:225], s[48:49], 0, v[130:131]
	s_mov_b32 m0, s47
	v_lshl_add_u64 v[226:227], s[26:27], 0, v[132:133]
	global_load_lds_dwordx4 v[224:225], off
	v_lshl_add_u64 v[224:225], s[48:49], 0, v[134:135]
	s_add_i32 m0, s47, 0x2000
	s_nop 0
	global_load_lds_dwordx4 v[224:225], off
	v_lshl_add_u64 v[224:225], s[26:27], 0, v[128:129]
	s_mov_b32 m0, s31
	s_nop 0
	global_load_lds_dwordx4 v[224:225], off
	s_mov_b32 m0, s33
	s_nop 0
	global_load_lds_dwordx4 v[226:227], off
	s_waitcnt vmcnt(8)
	s_waitcnt lgkmcnt(0)
	s_barrier
; #define PG8_STAGE(bufoff, gbase, voff) do { _Pragma("unroll") for (int _i = 0; _i < 2; ++_i) \
;         __builtin_amdgcn_global_load_lds((const unsigned*)((const char*)(gbase) + (voff)[_i]), (PG8_LAS unsigned*)(lds + (bufoff) + ldsw + _i * 8192), 16, 0, 0); } while (0)
; #define PG8_LDA(dst, b, h) do { _Pragma("unroll") for (int m = 0; m < 4; ++m) _Pragma("unroll") for (int k = 0; k < 2; ++k) dst[m][k] = *(const PG8_LAS bf16x8*)(lds + PG8_SA(b, h) + aoff + m * 2048 + k * 1024); } while (0)
; #define PG8_LDB(dst, b, h) do { _Pragma("unroll") for (int n = 0; n < 2; ++n) _Pragma("unroll") for (int k = 0; k < 2; ++k) dst[n][k] = *(const PG8_LAS bf16x8*)(lds + PG8_SB(b, h) + boff + n * 2048 + k * 1024); } while (0)
; #define PG8_MMA(ai, bj, At, Bt) do { __builtin_amdgcn_s_setprio(1); _Pragma("unroll") for (int m = 0; m < 4; ++m) _Pragma("unroll") for (int n = 0; n < 2; ++n) _Pragma("unroll") for (int k = 0; k < 2; ++k) \
;         acc[ai][bj][m][n] = __builtin_amdgcn_mfma_f32_16x16x32_bf16(Bt[n][k], At[m][k], acc[ai][bj][m][n], 0, 0, 0); __builtin_amdgcn_s_setprio(0); } while (0)
; #define PG8_WAIT_V(n) asm volatile("s_waitcnt vmcnt(" #n ")" ::: "memory")
; template <class Epi, class Sched, bool ALIGN_EPI = false, bool SP2 = false>
; __device__ __forceinline__ void gemm_phase(PG8_LAS unsigned char* lds, const Gemm g, const Sched& S, const Epi& E) {
;     ...
;             PG8_LDB(B0, 0, 0); PG8_LDB(B1, 0, 1); PG8_SCHED; PG8_LDA(At, 0, 0); PG8_STAGE(PG8_SA(1, 1), a1 + hstep, voffA);
;             PG8_WAIT_V(8); PG8_WAIT_L(0); PG8_BAR; PG8_MMA(0, 0, At, B0); PG8_MMA(0, 1, At, B1); PG8_BAR; PG8_SCHED;
;             PG8_LDA(At, 0, 1); PG8_STAGE(PG8_SB(0, 0), b2, voffB); PG8_STAGE(PG8_SB(0, 1), b2 + hstep, voffB); PG8_STAGE(PG8_SA(0, 0), a2, voffA);
;             PG8_WAIT_V(8); PG8_WAIT_L(0); PG8_BAR; PG8_MMA(1, 0, At, B0); PG8_MMA(1, 1, At, B1); PG8_BAR; PG8_SCHED;
;             PG8_LDB(B0, 1, 0); PG8_LDB(B1, 1, 1); PG8_SCHED; PG8_LDA(At, 1, 0); PG8_STAGE(PG8_SA(0, 1), a2 + hstep, voffA);
;             PG8_WAIT_V(8); PG8_WAIT_L(0); PG8_BAR; PG8_MMA(0, 0, At, B0); PG8_MMA(0, 1, At, B1); PG8_BAR; PG8_SCHED;
;             PG8_LDA(At, 1, 1); PG8_STAGE(PG8_SB(1, 0), b3, voffB); PG8_STAGE(PG8_SB(1, 1), b3 + hstep, voffB); PG8_STAGE(PG8_SA(1, 0), a3, voffA);
;             PG8_WAIT_V(8); PG8_WAIT_L(0); PG8_BAR; PG8_MMA(1, 0, At, B0); PG8_MMA(1, 1, At, B1); PG8_BAR; PG8_SCHED;
	v_mfma_f32_16x16x32_bf16 v[60:63], v[146:149], v[192:195], 0
	v_mfma_f32_16x16x32_bf16 v[56:59], v[164:167], v[192:195], 0
	v_mfma_f32_16x16x32_bf16 v[44:47], v[146:149], v[200:203], 0
	v_mfma_f32_16x16x32_bf16 v[40:43], v[164:167], v[200:203], 0
	v_mfma_f32_16x16x32_bf16 v[28:31], v[146:149], v[208:211], 0
	v_mfma_f32_16x16x32_bf16 v[24:27], v[164:167], v[208:211], 0
	v_mfma_f32_16x16x32_bf16 v[12:15], v[146:149], v[216:219], 0
	v_mfma_f32_16x16x32_bf16 v[8:11], v[164:167], v[216:219], 0
	v_mfma_f32_16x16x32_bf16 v[60:63], v[150:153], v[196:199], v[60:63]
	v_mfma_f32_16x16x32_bf16 v[56:59], v[168:171], v[196:199], v[56:59]
	v_mfma_f32_16x16x32_bf16 v[44:47], v[150:153], v[204:207], v[44:47]
	v_mfma_f32_16x16x32_bf16 v[40:43], v[168:171], v[204:207], v[40:43]
	v_mfma_f32_16x16x32_bf16 v[28:31], v[150:153], v[212:215], v[28:31]
	v_mfma_f32_16x16x32_bf16 v[24:27], v[168:171], v[212:215], v[24:27]
	v_mfma_f32_16x16x32_bf16 v[12:15], v[150:153], v[220:223], v[12:15]
	v_mfma_f32_16x16x32_bf16 v[8:11], v[168:171], v[220:223], v[8:11]
	v_mfma_f32_16x16x32_bf16 v[52:55], v[172:175], v[192:195], 0
	v_mfma_f32_16x16x32_bf16 v[48:51], v[180:183], v[192:195], 0
	v_mfma_f32_16x16x32_bf16 v[36:39], v[172:175], v[200:203], 0
	v_mfma_f32_16x16x32_bf16 v[32:35], v[180:183], v[200:203], 0
	v_mfma_f32_16x16x32_bf16 v[20:23], v[172:175], v[208:211], 0
	v_mfma_f32_16x16x32_bf16 v[16:19], v[180:183], v[208:211], 0
	v_mfma_f32_16x16x32_bf16 v[4:7], v[172:175], v[216:219], 0
	v_mfma_f32_16x16x32_bf16 v[0:3], v[180:183], v[216:219], 0
	v_mfma_f32_16x16x32_bf16 v[52:55], v[176:179], v[196:199], v[52:55]
	v_mfma_f32_16x16x32_bf16 v[48:51], v[188:191], v[196:199], v[48:51]
	v_mfma_f32_16x16x32_bf16 v[36:39], v[176:179], v[204:207], v[36:39]
	v_mfma_f32_16x16x32_bf16 v[32:35], v[188:191], v[204:207], v[32:35]
	v_mfma_f32_16x16x32_bf16 v[20:23], v[176:179], v[212:215], v[20:23]
	v_mfma_f32_16x16x32_bf16 v[16:19], v[188:191], v[212:215], v[16:19]
	v_mfma_f32_16x16x32_bf16 v[4:7], v[176:179], v[220:223], v[4:7]
	v_mfma_f32_16x16x32_bf16 v[0:3], v[188:191], v[220:223], v[0:3]
	s_barrier
	s_add_i32 s47, 0, 0x18000
	v_add_u32_e32 v136, s47, v157
	s_add_i32 s48, 0, 0x1c000
	ds_read_b128 v[146:149], v136
	ds_read_b128 v[150:153], v136 offset:1024
	ds_read_b128 v[164:167], v136 offset:2048
	ds_read_b128 v[168:171], v136 offset:3072
	v_add_u32_e32 v136, s48, v157
	ds_read_b128 v[172:175], v136
	ds_read_b128 v[176:179], v136 offset:1024
	ds_read_b128 v[180:183], v136 offset:2048
	ds_read_b128 v[188:191], v136 offset:3072
	s_add_u32 s26, s26, 0x40000
	s_addc_u32 s27, s27, 0
	s_mov_b32 m0, s34
	v_lshl_add_u64 v[228:229], s[26:27], 0, v[128:129]
	ds_read_b128 v[192:195], v162 offset:32768
	ds_read_b128 v[196:199], v162 offset:33792
	ds_read_b128 v[200:203], v162 offset:34816
	ds_read_b128 v[204:207], v162 offset:35840
	ds_read_b128 v[208:211], v162 offset:36864
	ds_read_b128 v[212:215], v162 offset:37888
	ds_read_b128 v[216:219], v162 offset:38912
	ds_read_b128 v[220:223], v162 offset:39936
	global_load_lds_dwordx4 v[228:229], off
	v_lshl_add_u64 v[228:229], s[26:27], 0, v[132:133]
	s_mov_b32 m0, s35
	s_nop 0
	global_load_lds_dwordx4 v[228:229], off
	s_waitcnt vmcnt(8)
	s_waitcnt lgkmcnt(0)
	s_barrier
	v_mfma_f32_16x16x32_bf16 v[124:127], v[146:149], v[192:195], v[124:127]
	v_mfma_f32_16x16x32_bf16 v[120:123], v[164:167], v[192:195], v[120:123]
	v_mfma_f32_16x16x32_bf16 v[108:111], v[146:149], v[200:203], v[108:111]
	v_mfma_f32_16x16x32_bf16 v[104:107], v[164:167], v[200:203], v[104:107]
	v_mfma_f32_16x16x32_bf16 v[92:95], v[146:149], v[208:211], v[92:95]
	v_mfma_f32_16x16x32_bf16 v[88:91], v[164:167], v[208:211], v[88:91]
	v_mfma_f32_16x16x32_bf16 v[76:79], v[146:149], v[216:219], v[76:79]
	v_mfma_f32_16x16x32_bf16 v[72:75], v[164:167], v[216:219], v[72:75]
	v_mfma_f32_16x16x32_bf16 v[124:127], v[150:153], v[196:199], v[124:127]
	v_mfma_f32_16x16x32_bf16 v[120:123], v[168:171], v[196:199], v[120:123]
	v_mfma_f32_16x16x32_bf16 v[108:111], v[150:153], v[204:207], v[108:111]
	v_mfma_f32_16x16x32_bf16 v[104:107], v[168:171], v[204:207], v[104:107]
	v_mfma_f32_16x16x32_bf16 v[92:95], v[150:153], v[212:215], v[92:95]
	v_mfma_f32_16x16x32_bf16 v[88:91], v[168:171], v[212:215], v[88:91]
	v_mfma_f32_16x16x32_bf16 v[76:79], v[150:153], v[220:223], v[76:79]
	v_mfma_f32_16x16x32_bf16 v[72:75], v[168:171], v[220:223], v[72:75]
	v_mfma_f32_16x16x32_bf16 v[116:119], v[172:175], v[192:195], v[116:119]
	v_mfma_f32_16x16x32_bf16 v[112:115], v[180:183], v[192:195], v[112:115]
	v_mfma_f32_16x16x32_bf16 v[100:103], v[172:175], v[200:203], v[100:103]
	v_mfma_f32_16x16x32_bf16 v[96:99], v[180:183], v[200:203], v[96:99]
	v_mfma_f32_16x16x32_bf16 v[84:87], v[172:175], v[208:211], v[84:87]
	v_mfma_f32_16x16x32_bf16 v[80:83], v[180:183], v[208:211], v[80:83]
	v_mfma_f32_16x16x32_bf16 v[68:71], v[172:175], v[216:219], v[68:71]
	v_mfma_f32_16x16x32_bf16 v[64:67], v[180:183], v[216:219], v[64:67]
	v_mfma_f32_16x16x32_bf16 v[116:119], v[176:179], v[196:199], v[116:119]
	v_mfma_f32_16x16x32_bf16 v[112:115], v[188:191], v[196:199], v[112:115]
	v_mfma_f32_16x16x32_bf16 v[100:103], v[176:179], v[204:207], v[100:103]
	v_mfma_f32_16x16x32_bf16 v[96:99], v[188:191], v[204:207], v[96:99]
	v_mfma_f32_16x16x32_bf16 v[84:87], v[176:179], v[212:215], v[84:87]
	v_mfma_f32_16x16x32_bf16 v[80:83], v[188:191], v[212:215], v[80:83]
	v_mfma_f32_16x16x32_bf16 v[68:71], v[176:179], v[220:223], v[68:71]
	v_mfma_f32_16x16x32_bf16 v[64:67], v[188:191], v[220:223], v[64:67]
	s_barrier
; #define PG8_STAGE(bufoff, gbase, voff) do { _Pragma("unroll") for (int _i = 0; _i < 2; ++_i) \
;         __builtin_amdgcn_global_load_lds((const unsigned*)((const char*)(gbase) + (voff)[_i]), (PG8_LAS unsigned*)(lds + (bufoff) + ldsw + _i * 8192), 16, 0, 0); } while (0)
; #define PG8_LDA(dst, b, h) do { _Pragma("unroll") for (int m = 0; m < 4; ++m) _Pragma("unroll") for (int k = 0; k < 2; ++k) dst[m][k] = *(const PG8_LAS bf16x8*)(lds + PG8_SA(b, h) + aoff + m * 2048 + k * 1024); } while (0)
; #define PG8_LDB(dst, b, h) do { _Pragma("unroll") for (int n = 0; n < 2; ++n) _Pragma("unroll") for (int k = 0; k < 2; ++k) dst[n][k] = *(const PG8_LAS bf16x8*)(lds + PG8_SB(b, h) + boff + n * 2048 + k * 1024); } while (0)
; #define PG8_MMA(ai, bj, At, Bt) do { __builtin_amdgcn_s_setprio(1); _Pragma("unroll") for (int m = 0; m < 4; ++m) _Pragma("unroll") for (int n = 0; n < 2; ++n) _Pragma("unroll") for (int k = 0; k < 2; ++k) \
;         acc[ai][bj][m][n] = __builtin_amdgcn_mfma_f32_16x16x32_bf16(Bt[n][k], At[m][k], acc[ai][bj][m][n], 0, 0, 0); __builtin_amdgcn_s_setprio(0); } while (0)
; #define PG8_WAIT_V(n) asm volatile("s_waitcnt vmcnt(" #n ")" ::: "memory")
; template <class Epi, class Sched, bool ALIGN_EPI = false, bool SP2 = false>
; __device__ __forceinline__ void gemm_phase(PG8_LAS unsigned char* lds, const Gemm g, const Sched& S, const Epi& E) {
;     ...
;             PG8_LDB(B0, 0, 0); PG8_LDB(B1, 0, 1); PG8_SCHED; PG8_LDA(At, 0, 0); PG8_STAGE(PG8_SA(1, 1), a1 + hstep, voffA);
;             PG8_WAIT_V(8); PG8_WAIT_L(0); PG8_BAR; PG8_MMA(0, 0, At, B0); PG8_MMA(0, 1, At, B1); PG8_BAR; PG8_SCHED;
;             PG8_LDA(At, 0, 1); PG8_STAGE(PG8_SB(0, 0), b2, voffB); PG8_STAGE(PG8_SB(0, 1), b2 + hstep, voffB); PG8_STAGE(PG8_SA(0, 0), a2, voffA);
;             PG8_WAIT_V(8); PG8_WAIT_L(0); PG8_BAR; PG8_MMA(1, 0, At, B0); PG8_MMA(1, 1, At, B1); PG8_BAR; PG8_SCHED;
;             PG8_LDB(B0, 1, 0); PG8_LDB(B1, 1, 1); PG8_SCHED; PG8_LDA(At, 1, 0); PG8_STAGE(PG8_SA(0, 1), a2 + hstep, voffA);
;             PG8_WAIT_V(8); PG8_WAIT_L(0); PG8_BAR; PG8_MMA(0, 0, At, B0); PG8_MMA(0, 1, At, B1); PG8_BAR; PG8_SCHED;
;             PG8_LDA(At, 1, 1); PG8_STAGE(PG8_SB(1, 0), b3, voffB); PG8_STAGE(PG8_SB(1, 1), b3 + hstep, voffB); PG8_STAGE(PG8_SA(1, 0), a3, voffA);
;             PG8_WAIT_V(8); PG8_WAIT_L(0); PG8_BAR; PG8_MMA(1, 0, At, B0); PG8_MMA(1, 1, At, B1); PG8_BAR; PG8_SCHED;
	s_add_i32 s26, s47, s28
	v_lshl_add_u64 v[154:155], v[154:155], 0, s[8:9]
	s_mov_b32 m0, s26
	ds_read_b128 v[192:195], v162 offset:49152
	ds_read_b128 v[196:199], v162 offset:50176
	ds_read_b128 v[200:203], v162 offset:51200
	ds_read_b128 v[204:207], v162 offset:52224
	ds_read_b128 v[208:211], v162 offset:53248
	ds_read_b128 v[212:215], v162 offset:54272
	ds_read_b128 v[216:219], v162 offset:55296
	ds_read_b128 v[220:223], v162 offset:56320
	global_load_lds_dwordx4 v[154:155], off
	s_add_i32 m0, s26, 0x2000
	s_add_u32 s24, s24, 0x40080
	v_lshl_add_u64 v[154:155], v[184:185], 0, s[8:9]
	s_addc_u32 s25, s25, 0
	s_add_i32 s26, s48, s28
	global_load_lds_dwordx4 v[154:155], off
	v_lshl_add_u64 v[154:155], s[24:25], 0, v[130:131]
	s_mov_b32 m0, s26
	s_nop 0
	global_load_lds_dwordx4 v[154:155], off
	v_lshl_add_u64 v[154:155], s[24:25], 0, v[134:135]
	s_add_i32 m0, s26, 0x2000
	s_nop 0
	global_load_lds_dwordx4 v[154:155], off
	v_lshl_add_u64 v[154:155], v[224:225], 0, s[8:9]
	s_mov_b32 m0, s36
	s_nop 0
	global_load_lds_dwordx4 v[154:155], off
	v_lshl_add_u64 v[154:155], v[226:227], 0, s[8:9]
	s_mov_b32 m0, s37
	s_nop 0
	global_load_lds_dwordx4 v[154:155], off
	s_waitcnt vmcnt(8)
	s_waitcnt lgkmcnt(0)
	s_barrier
	v_mfma_f32_16x16x32_bf16 v[60:63], v[146:149], v[192:195], v[60:63]
	v_mfma_f32_16x16x32_bf16 v[56:59], v[164:167], v[192:195], v[56:59]
	v_mfma_f32_16x16x32_bf16 v[44:47], v[146:149], v[200:203], v[44:47]
	v_mfma_f32_16x16x32_bf16 v[40:43], v[164:167], v[200:203], v[40:43]
	v_mfma_f32_16x16x32_bf16 v[28:31], v[146:149], v[208:211], v[28:31]
	v_mfma_f32_16x16x32_bf16 v[24:27], v[164:167], v[208:211], v[24:27]
	v_mfma_f32_16x16x32_bf16 v[12:15], v[146:149], v[216:219], v[12:15]
	v_mfma_f32_16x16x32_bf16 v[8:11], v[164:167], v[216:219], v[8:11]
	v_mfma_f32_16x16x32_bf16 v[60:63], v[150:153], v[196:199], v[60:63]
	v_mfma_f32_16x16x32_bf16 v[56:59], v[168:171], v[196:199], v[56:59]
	v_mfma_f32_16x16x32_bf16 v[44:47], v[150:153], v[204:207], v[44:47]
	v_mfma_f32_16x16x32_bf16 v[40:43], v[168:171], v[204:207], v[40:43]
	v_mfma_f32_16x16x32_bf16 v[28:31], v[150:153], v[212:215], v[28:31]
	v_mfma_f32_16x16x32_bf16 v[24:27], v[168:171], v[212:215], v[24:27]
	v_mfma_f32_16x16x32_bf16 v[12:15], v[150:153], v[220:223], v[12:15]
	v_mfma_f32_16x16x32_bf16 v[8:11], v[168:171], v[220:223], v[8:11]
	v_mfma_f32_16x16x32_bf16 v[52:55], v[172:175], v[192:195], v[52:55]
	v_mfma_f32_16x16x32_bf16 v[48:51], v[180:183], v[192:195], v[48:51]
	v_mfma_f32_16x16x32_bf16 v[36:39], v[172:175], v[200:203], v[36:39]
	v_mfma_f32_16x16x32_bf16 v[32:35], v[180:183], v[200:203], v[32:35]
	v_mfma_f32_16x16x32_bf16 v[20:23], v[172:175], v[208:211], v[20:23]
	v_mfma_f32_16x16x32_bf16 v[16:19], v[180:183], v[208:211], v[16:19]
	v_mfma_f32_16x16x32_bf16 v[4:7], v[172:175], v[216:219], v[4:7]
	v_mfma_f32_16x16x32_bf16 v[0:3], v[180:183], v[216:219], v[0:3]
	v_mfma_f32_16x16x32_bf16 v[52:55], v[176:179], v[196:199], v[52:55]
	v_mfma_f32_16x16x32_bf16 v[48:51], v[188:191], v[196:199], v[48:51]
	v_mfma_f32_16x16x32_bf16 v[36:39], v[176:179], v[204:207], v[36:39]
	v_mfma_f32_16x16x32_bf16 v[32:35], v[188:191], v[204:207], v[32:35]
	v_mfma_f32_16x16x32_bf16 v[20:23], v[176:179], v[212:215], v[20:23]
	v_mfma_f32_16x16x32_bf16 v[16:19], v[188:191], v[212:215], v[16:19]
	v_mfma_f32_16x16x32_bf16 v[4:7], v[176:179], v[220:223], v[4:7]
	v_mfma_f32_16x16x32_bf16 v[0:3], v[188:191], v[220:223], v[0:3]
	s_barrier
	s_add_i32 s46, s46, 2
	s_add_u32 s22, s22, 0x100
	s_addc_u32 s23, s23, 0
	s_add_u32 s44, s44, 0x100
	s_addc_u32 s45, s45, 0
	s_cmp_gt_u32 s46, 13
.LBB0_572:
	ds_read_b128 v[146:149], v159
	ds_read_b128 v[150:153], v159 offset:1024
	ds_read_b128 v[164:167], v159 offset:2048
	ds_read_b128 v[168:171], v159 offset:3072
	ds_read_b128 v[172:175], v161
	ds_read_b128 v[176:179], v161 offset:1024
	ds_read_b128 v[180:183], v161 offset:2048
	ds_read_b128 v[188:191], v161 offset:3072
	s_add_u32 s24, s22, 0xfffc0080
	s_addc_u32 s25, s23, -1
	s_cmp_eq_u32 s46, 12
	s_cselect_b32 s27, s7, s25
	s_cselect_b32 s26, s15, s24
	s_cselect_b32 s25, s13, s45
	s_cselect_b32 s24, s21, s44
	v_lshl_add_u64 v[154:155], s[22:23], 0, v[138:139]
	s_add_i32 m0, s31, 0xc000
	ds_read_b128 v[192:195], v162
	ds_read_b128 v[196:199], v162 offset:1024
	ds_read_b128 v[200:203], v162 offset:2048
	ds_read_b128 v[204:207], v162 offset:3072
	ds_read_b128 v[208:211], v162 offset:4096
	ds_read_b128 v[212:215], v162 offset:5120
	ds_read_b128 v[216:219], v162 offset:6144
	ds_read_b128 v[220:223], v162 offset:7168
	global_load_lds_dwordx4 v[154:155], off
	v_lshl_add_u64 v[154:155], s[22:23], 0, v[140:141]
	s_add_i32 m0, s31, 0xe000
	s_nop 0
	global_load_lds_dwordx4 v[154:155], off
	s_waitcnt vmcnt(8)
	s_waitcnt lgkmcnt(0)
	s_barrier
; #define PG8_STAGE(bufoff, gbase, voff) do { _Pragma("unroll") for (int _i = 0; _i < 2; ++_i) \
;         __builtin_amdgcn_global_load_lds((const unsigned*)((const char*)(gbase) + (voff)[_i]), (PG8_LAS unsigned*)(lds + (bufoff) + ldsw + _i * 8192), 16, 0, 0); } while (0)
; #define PG8_LDA(dst, b, h) do { _Pragma("unroll") for (int m = 0; m < 4; ++m) _Pragma("unroll") for (int k = 0; k < 2; ++k) dst[m][k] = *(const PG8_LAS bf16x8*)(lds + PG8_SA(b, h) + aoff + m * 2048 + k * 1024); } while (0)
; #define PG8_MMA(ai, bj, At, Bt) do { __builtin_amdgcn_s_setprio(1); _Pragma("unroll") for (int m = 0; m < 4; ++m) _Pragma("unroll") for (int n = 0; n < 2; ++n) _Pragma("unroll") for (int k = 0; k < 2; ++k) \
;         acc[ai][bj][m][n] = __builtin_amdgcn_mfma_f32_16x16x32_bf16(Bt[n][k], At[m][k], acc[ai][bj][m][n], 0, 0, 0); __builtin_amdgcn_s_setprio(0); } while (0)
; #define PG8_WAIT_V(n) asm volatile("s_waitcnt vmcnt(" #n ")" ::: "memory")
; #define PG8_WAIT_L(n) asm volatile("s_waitcnt lgkmcnt(" #n ")" ::: "memory")
; #define PG8_BAR __builtin_amdgcn_s_barrier()
; #define PG8_SCHED __builtin_amdgcn_sched_barrier(0)
; template <class Epi, class Sched, bool ALIGN_EPI = false, bool SP2 = false>
; __device__ __forceinline__ void gemm_phase(PG8_LAS unsigned char* lds, const Gemm g, const Sched& S, const Epi& E) {
;     ...
;             PG8_WAIT_V(8); PG8_WAIT_L(0); PG8_BAR; PG8_MMA(0, 0, At, B0); PG8_MMA(0, 1, At, B1); PG8_BAR; PG8_SCHED;
;             PG8_LDA(At, 0, 1); PG8_STAGE(PG8_SB(0, 0), b2, voffB); PG8_STAGE(PG8_SB(0, 1), b2 + hstep, voffB); PG8_STAGE(PG8_SA(0, 0), a2, voffA);
;             PG8_WAIT_V(8); PG8_WAIT_L(0); PG8_BAR; PG8_MMA(1, 0, At, B0); PG8_MMA(1, 1, At, B1); PG8_BAR; PG8_SCHED;
	v_mfma_f32_16x16x32_bf16 v[124:127], v[146:149], v[192:195], v[124:127]
	v_mfma_f32_16x16x32_bf16 v[120:123], v[164:167], v[192:195], v[120:123]
	v_mfma_f32_16x16x32_bf16 v[108:111], v[146:149], v[200:203], v[108:111]
	v_mfma_f32_16x16x32_bf16 v[104:107], v[164:167], v[200:203], v[104:107]
	v_mfma_f32_16x16x32_bf16 v[92:95], v[146:149], v[208:211], v[92:95]
	v_mfma_f32_16x16x32_bf16 v[88:91], v[164:167], v[208:211], v[88:91]
	v_mfma_f32_16x16x32_bf16 v[76:79], v[146:149], v[216:219], v[76:79]
	v_mfma_f32_16x16x32_bf16 v[72:75], v[164:167], v[216:219], v[72:75]
	v_mfma_f32_16x16x32_bf16 v[124:127], v[150:153], v[196:199], v[124:127]
	v_mfma_f32_16x16x32_bf16 v[120:123], v[168:171], v[196:199], v[120:123]
	v_mfma_f32_16x16x32_bf16 v[108:111], v[150:153], v[204:207], v[108:111]
	v_mfma_f32_16x16x32_bf16 v[104:107], v[168:171], v[204:207], v[104:107]
	v_mfma_f32_16x16x32_bf16 v[92:95], v[150:153], v[212:215], v[92:95]
	v_mfma_f32_16x16x32_bf16 v[88:91], v[168:171], v[212:215], v[88:91]
	v_mfma_f32_16x16x32_bf16 v[76:79], v[150:153], v[220:223], v[76:79]
	v_mfma_f32_16x16x32_bf16 v[72:75], v[168:171], v[220:223], v[72:75]
	v_mfma_f32_16x16x32_bf16 v[116:119], v[172:175], v[192:195], v[116:119]
	v_mfma_f32_16x16x32_bf16 v[112:115], v[180:183], v[192:195], v[112:115]
	v_mfma_f32_16x16x32_bf16 v[100:103], v[172:175], v[200:203], v[100:103]
	v_mfma_f32_16x16x32_bf16 v[96:99], v[180:183], v[200:203], v[96:99]
	v_mfma_f32_16x16x32_bf16 v[84:87], v[172:175], v[208:211], v[84:87]
	v_mfma_f32_16x16x32_bf16 v[80:83], v[180:183], v[208:211], v[80:83]
	v_mfma_f32_16x16x32_bf16 v[68:71], v[172:175], v[216:219], v[68:71]
	v_mfma_f32_16x16x32_bf16 v[64:67], v[180:183], v[216:219], v[64:67]
	v_mfma_f32_16x16x32_bf16 v[116:119], v[176:179], v[196:199], v[116:119]
	v_mfma_f32_16x16x32_bf16 v[112:115], v[188:191], v[196:199], v[112:115]
	v_mfma_f32_16x16x32_bf16 v[100:103], v[176:179], v[204:207], v[100:103]
	v_mfma_f32_16x16x32_bf16 v[96:99], v[188:191], v[204:207], v[96:99]
	v_mfma_f32_16x16x32_bf16 v[84:87], v[176:179], v[212:215], v[84:87]
	v_mfma_f32_16x16x32_bf16 v[80:83], v[188:191], v[212:215], v[80:83]
	v_mfma_f32_16x16x32_bf16 v[68:71], v[176:179], v[220:223], v[68:71]
	v_mfma_f32_16x16x32_bf16 v[64:67], v[188:191], v[220:223], v[64:67]
	s_barrier
	s_add_i32 s47, s39, s28
	v_lshl_add_u64 v[154:155], s[24:25], 0, v[130:131]
	s_mov_b32 m0, s47
	ds_read_b128 v[192:195], v162 offset:16384
	ds_read_b128 v[196:199], v162 offset:17408
	ds_read_b128 v[200:203], v162 offset:18432
	ds_read_b128 v[204:207], v162 offset:19456
	ds_read_b128 v[208:211], v162 offset:20480
	ds_read_b128 v[212:215], v162 offset:21504
	ds_read_b128 v[216:219], v162 offset:22528
	ds_read_b128 v[220:223], v162 offset:23552
	global_load_lds_dwordx4 v[154:155], off
	s_add_i32 m0, s47, 0x2000
	s_add_u32 s48, s24, 0x40000
	v_lshl_add_u64 v[184:185], s[24:25], 0, v[134:135]
	s_addc_u32 s49, s25, 0
	s_add_i32 s47, s40, s28
	global_load_lds_dwordx4 v[184:185], off
	v_lshl_add_u64 v[224:225], s[48:49], 0, v[130:131]
	s_mov_b32 m0, s47
	v_lshl_add_u64 v[226:227], s[26:27], 0, v[132:133]
	global_load_lds_dwordx4 v[224:225], off
	v_lshl_add_u64 v[224:225], s[48:49], 0, v[134:135]
	s_add_i32 m0, s47, 0x2000
	s_nop 0
	global_load_lds_dwordx4 v[224:225], off
	v_lshl_add_u64 v[224:225], s[26:27], 0, v[128:129]
	s_mov_b32 m0, s31
	s_nop 0
	global_load_lds_dwordx4 v[224:225], off
	s_mov_b32 m0, s33
	s_nop 0
	global_load_lds_dwordx4 v[226:227], off
	s_waitcnt vmcnt(8)
	s_waitcnt lgkmcnt(0)
	s_barrier
	v_mfma_f32_16x16x32_bf16 v[60:63], v[146:149], v[192:195], v[60:63]
	v_mfma_f32_16x16x32_bf16 v[56:59], v[164:167], v[192:195], v[56:59]
	v_mfma_f32_16x16x32_bf16 v[44:47], v[146:149], v[200:203], v[44:47]
	v_mfma_f32_16x16x32_bf16 v[40:43], v[164:167], v[200:203], v[40:43]
	v_mfma_f32_16x16x32_bf16 v[28:31], v[146:149], v[208:211], v[28:31]
	v_mfma_f32_16x16x32_bf16 v[24:27], v[164:167], v[208:211], v[24:27]
	v_mfma_f32_16x16x32_bf16 v[12:15], v[146:149], v[216:219], v[12:15]
	v_mfma_f32_16x16x32_bf16 v[8:11], v[164:167], v[216:219], v[8:11]
	v_mfma_f32_16x16x32_bf16 v[60:63], v[150:153], v[196:199], v[60:63]
	v_mfma_f32_16x16x32_bf16 v[56:59], v[168:171], v[196:199], v[56:59]
	v_mfma_f32_16x16x32_bf16 v[44:47], v[150:153], v[204:207], v[44:47]
	v_mfma_f32_16x16x32_bf16 v[40:43], v[168:171], v[204:207], v[40:43]
	v_mfma_f32_16x16x32_bf16 v[28:31], v[150:153], v[212:215], v[28:31]
	v_mfma_f32_16x16x32_bf16 v[24:27], v[168:171], v[212:215], v[24:27]
	v_mfma_f32_16x16x32_bf16 v[12:15], v[150:153], v[220:223], v[12:15]
	v_mfma_f32_16x16x32_bf16 v[8:11], v[168:171], v[220:223], v[8:11]
	v_mfma_f32_16x16x32_bf16 v[52:55], v[172:175], v[192:195], v[52:55]
	v_mfma_f32_16x16x32_bf16 v[48:51], v[180:183], v[192:195], v[48:51]
	v_mfma_f32_16x16x32_bf16 v[36:39], v[172:175], v[200:203], v[36:39]
	v_mfma_f32_16x16x32_bf16 v[32:35], v[180:183], v[200:203], v[32:35]
	v_mfma_f32_16x16x32_bf16 v[20:23], v[172:175], v[208:211], v[20:23]
	v_mfma_f32_16x16x32_bf16 v[16:19], v[180:183], v[208:211], v[16:19]
	v_mfma_f32_16x16x32_bf16 v[4:7], v[172:175], v[216:219], v[4:7]
	v_mfma_f32_16x16x32_bf16 v[0:3], v[180:183], v[216:219], v[0:3]
	v_mfma_f32_16x16x32_bf16 v[52:55], v[176:179], v[196:199], v[52:55]
	v_mfma_f32_16x16x32_bf16 v[48:51], v[188:191], v[196:199], v[48:51]
	v_mfma_f32_16x16x32_bf16 v[36:39], v[176:179], v[204:207], v[36:39]
	v_mfma_f32_16x16x32_bf16 v[32:35], v[188:191], v[204:207], v[32:35]
	v_mfma_f32_16x16x32_bf16 v[20:23], v[176:179], v[212:215], v[20:23]
	v_mfma_f32_16x16x32_bf16 v[16:19], v[188:191], v[212:215], v[16:19]
	v_mfma_f32_16x16x32_bf16 v[4:7], v[176:179], v[220:223], v[4:7]
	v_mfma_f32_16x16x32_bf16 v[0:3], v[188:191], v[220:223], v[0:3]
	s_barrier
; #define PG8_STAGE(bufoff, gbase, voff) do { _Pragma("unroll") for (int _i = 0; _i < 2; ++_i) \
;         __builtin_amdgcn_global_load_lds((const unsigned*)((const char*)(gbase) + (voff)[_i]), (PG8_LAS unsigned*)(lds + (bufoff) + ldsw + _i * 8192), 16, 0, 0); } while (0)
; #define PG8_LDA(dst, b, h) do { _Pragma("unroll") for (int m = 0; m < 4; ++m) _Pragma("unroll") for (int k = 0; k < 2; ++k) dst[m][k] = *(const PG8_LAS bf16x8*)(lds + PG8_SA(b, h) + aoff + m * 2048 + k * 1024); } while (0)
; #define PG8_LDB(dst, b, h) do { _Pragma("unroll") for (int n = 0; n < 2; ++n) _Pragma("unroll") for (int k = 0; k < 2; ++k) dst[n][k] = *(const PG8_LAS bf16x8*)(lds + PG8_SB(b, h) + boff + n * 2048 + k * 1024); } while (0)
; #define PG8_MMA(ai, bj, At, Bt) do { __builtin_amdgcn_s_setprio(1); _Pragma("unroll") for (int m = 0; m < 4; ++m) _Pragma("unroll") for (int n = 0; n < 2; ++n) _Pragma("unroll") for (int k = 0; k < 2; ++k) \
;         acc[ai][bj][m][n] = __builtin_amdgcn_mfma_f32_16x16x32_bf16(Bt[n][k], At[m][k], acc[ai][bj][m][n], 0, 0, 0); __builtin_amdgcn_s_setprio(0); } while (0)
; #define PG8_WAIT_V(n) asm volatile("s_waitcnt vmcnt(" #n ")" ::: "memory")
; #define PG8_WAIT_L(n) asm volatile("s_waitcnt lgkmcnt(" #n ")" ::: "memory")
; #define PG8_BAR __builtin_amdgcn_s_barrier()
; #define PG8_SCHED __builtin_amdgcn_sched_barrier(0)
; template <class Epi, class Sched, bool ALIGN_EPI = false, bool SP2 = false>
; __device__ __forceinline__ void gemm_phase(PG8_LAS unsigned char* lds, const Gemm g, const Sched& S, const Epi& E) {
;     ...
;             PG8_LDB(B0, 1, 0); PG8_LDB(B1, 1, 1); PG8_SCHED; PG8_LDA(At, 1, 0); PG8_STAGE(PG8_SA(0, 1), a2 + hstep, voffA);
;             PG8_WAIT_V(8); PG8_WAIT_L(0); PG8_BAR; PG8_MMA(0, 0, At, B0); PG8_MMA(0, 1, At, B1); PG8_BAR; PG8_SCHED;
	s_add_i32 s47, 0, 0x18000
	v_add_u32_e32 v136, s47, v157
	s_add_i32 s48, 0, 0x1c000
	ds_read_b128 v[146:149], v136
	ds_read_b128 v[150:153], v136 offset:1024
	ds_read_b128 v[164:167], v136 offset:2048
	ds_read_b128 v[168:171], v136 offset:3072
	v_add_u32_e32 v136, s48, v157
	ds_read_b128 v[172:175], v136
	ds_read_b128 v[176:179], v136 offset:1024
	ds_read_b128 v[180:183], v136 offset:2048
	ds_read_b128 v[188:191], v136 offset:3072
	s_add_u32 s26, s26, 0x40000
	s_addc_u32 s27, s27, 0
	s_mov_b32 m0, s34
	v_lshl_add_u64 v[228:229], s[26:27], 0, v[128:129]
	ds_read_b128 v[192:195], v162 offset:32768
	ds_read_b128 v[196:199], v162 offset:33792
	ds_read_b128 v[200:203], v162 offset:34816
	ds_read_b128 v[204:207], v162 offset:35840
	ds_read_b128 v[208:211], v162 offset:36864
	ds_read_b128 v[212:215], v162 offset:37888
	ds_read_b128 v[216:219], v162 offset:38912
	ds_read_b128 v[220:223], v162 offset:39936
	global_load_lds_dwordx4 v[228:229], off
	v_lshl_add_u64 v[228:229], s[26:27], 0, v[132:133]
	s_mov_b32 m0, s35
	s_nop 0
	global_load_lds_dwordx4 v[228:229], off
	s_waitcnt vmcnt(8)
	s_waitcnt lgkmcnt(0)
	s_barrier
	v_mfma_f32_16x16x32_bf16 v[124:127], v[146:149], v[192:195], v[124:127]
	v_mfma_f32_16x16x32_bf16 v[120:123], v[164:167], v[192:195], v[120:123]
	v_mfma_f32_16x16x32_bf16 v[108:111], v[146:149], v[200:203], v[108:111]
	v_mfma_f32_16x16x32_bf16 v[104:107], v[164:167], v[200:203], v[104:107]
	v_mfma_f32_16x16x32_bf16 v[92:95], v[146:149], v[208:211], v[92:95]
	v_mfma_f32_16x16x32_bf16 v[88:91], v[164:167], v[208:211], v[88:91]
	v_mfma_f32_16x16x32_bf16 v[76:79], v[146:149], v[216:219], v[76:79]
	v_mfma_f32_16x16x32_bf16 v[72:75], v[164:167], v[216:219], v[72:75]
	v_mfma_f32_16x16x32_bf16 v[124:127], v[150:153], v[196:199], v[124:127]
	v_mfma_f32_16x16x32_bf16 v[120:123], v[168:171], v[196:199], v[120:123]
	v_mfma_f32_16x16x32_bf16 v[108:111], v[150:153], v[204:207], v[108:111]
	v_mfma_f32_16x16x32_bf16 v[104:107], v[168:171], v[204:207], v[104:107]
	v_mfma_f32_16x16x32_bf16 v[92:95], v[150:153], v[212:215], v[92:95]
	v_mfma_f32_16x16x32_bf16 v[88:91], v[168:171], v[212:215], v[88:91]
	v_mfma_f32_16x16x32_bf16 v[76:79], v[150:153], v[220:223], v[76:79]
	v_mfma_f32_16x16x32_bf16 v[72:75], v[168:171], v[220:223], v[72:75]
	v_mfma_f32_16x16x32_bf16 v[116:119], v[172:175], v[192:195], v[116:119]
	v_mfma_f32_16x16x32_bf16 v[112:115], v[180:183], v[192:195], v[112:115]
	v_mfma_f32_16x16x32_bf16 v[100:103], v[172:175], v[200:203], v[100:103]
	v_mfma_f32_16x16x32_bf16 v[96:99], v[180:183], v[200:203], v[96:99]
	v_mfma_f32_16x16x32_bf16 v[84:87], v[172:175], v[208:211], v[84:87]
	v_mfma_f32_16x16x32_bf16 v[80:83], v[180:183], v[208:211], v[80:83]
	v_mfma_f32_16x16x32_bf16 v[68:71], v[172:175], v[216:219], v[68:71]
	v_mfma_f32_16x16x32_bf16 v[64:67], v[180:183], v[216:219], v[64:67]
	v_mfma_f32_16x16x32_bf16 v[116:119], v[176:179], v[196:199], v[116:119]
	v_mfma_f32_16x16x32_bf16 v[112:115], v[188:191], v[196:199], v[112:115]
	v_mfma_f32_16x16x32_bf16 v[100:103], v[176:179], v[204:207], v[100:103]
	v_mfma_f32_16x16x32_bf16 v[96:99], v[188:191], v[204:207], v[96:99]
	v_mfma_f32_16x16x32_bf16 v[84:87], v[176:179], v[212:215], v[84:87]
	v_mfma_f32_16x16x32_bf16 v[80:83], v[188:191], v[212:215], v[80:83]
	v_mfma_f32_16x16x32_bf16 v[68:71], v[176:179], v[220:223], v[68:71]
	v_mfma_f32_16x16x32_bf16 v[64:67], v[188:191], v[220:223], v[64:67]
	s_barrier
; #define PG8_STAGE(bufoff, gbase, voff) do { _Pragma("unroll") for (int _i = 0; _i < 2; ++_i) \
;         __builtin_amdgcn_global_load_lds((const unsigned*)((const char*)(gbase) + (voff)[_i]), (PG8_LAS unsigned*)(lds + (bufoff) + ldsw + _i * 8192), 16, 0, 0); } while (0)
; #define PG8_LDA(dst, b, h) do { _Pragma("unroll") for (int m = 0; m < 4; ++m) _Pragma("unroll") for (int k = 0; k < 2; ++k) dst[m][k] = *(const PG8_LAS bf16x8*)(lds + PG8_SA(b, h) + aoff + m * 2048 + k * 1024); } while (0)
; #define PG8_MMA(ai, bj, At, Bt) do { __builtin_amdgcn_s_setprio(1); _Pragma("unroll") for (int m = 0; m < 4; ++m) _Pragma("unroll") for (int n = 0; n < 2; ++n) _Pragma("unroll") for (int k = 0; k < 2; ++k) \
;         acc[ai][bj][m][n] = __builtin_amdgcn_mfma_f32_16x16x32_bf16(Bt[n][k], At[m][k], acc[ai][bj][m][n], 0, 0, 0); __builtin_amdgcn_s_setprio(0); } while (0)
; #define PG8_WAIT_V(n) asm volatile("s_waitcnt vmcnt(" #n ")" ::: "memory")
; #define PG8_WAIT_L(n) asm volatile("s_waitcnt lgkmcnt(" #n ")" ::: "memory")
; #define PG8_BAR __builtin_amdgcn_s_barrier()
; #define PG8_SCHED __builtin_amdgcn_sched_barrier(0)
; template <class Epi, class Sched, bool ALIGN_EPI = false, bool SP2 = false>
; __device__ __forceinline__ void gemm_phase(PG8_LAS unsigned char* lds, const Gemm g, const Sched& S, const Epi& E) {
;     ...
;         for (int t = 0; t < nt; t += 2) {
;     ...
;             PG8_LDA(At, 1, 1); PG8_STAGE(PG8_SB(1, 0), b3, voffB); PG8_STAGE(PG8_SB(1, 1), b3 + hstep, voffB); PG8_STAGE(PG8_SA(1, 0), a3, voffA);
;             PG8_WAIT_V(8); PG8_WAIT_L(0); PG8_BAR; PG8_MMA(1, 0, At, B0); PG8_MMA(1, 1, At, B1); PG8_BAR; PG8_SCHED;
;     ...
;         if constexpr (ALIGN_EPI) { if (wr == 0) PG8_BAR; }
	s_add_i32 s26, s47, s28
	v_lshl_add_u64 v[154:155], v[154:155], 0, s[8:9]
	s_mov_b32 m0, s26
	ds_read_b128 v[192:195], v162 offset:49152
	ds_read_b128 v[196:199], v162 offset:50176
	ds_read_b128 v[200:203], v162 offset:51200
	ds_read_b128 v[204:207], v162 offset:52224
	ds_read_b128 v[208:211], v162 offset:53248
	ds_read_b128 v[212:215], v162 offset:54272
	ds_read_b128 v[216:219], v162 offset:55296
	ds_read_b128 v[220:223], v162 offset:56320
	global_load_lds_dwordx4 v[154:155], off
	s_add_i32 m0, s26, 0x2000
	s_add_u32 s24, s24, 0x40080
	v_lshl_add_u64 v[154:155], v[184:185], 0, s[8:9]
	s_addc_u32 s25, s25, 0
	s_add_i32 s26, s48, s28
	global_load_lds_dwordx4 v[154:155], off
	v_lshl_add_u64 v[154:155], s[24:25], 0, v[130:131]
	s_mov_b32 m0, s26
	s_nop 0
	global_load_lds_dwordx4 v[154:155], off
	v_lshl_add_u64 v[154:155], s[24:25], 0, v[134:135]
	s_add_i32 m0, s26, 0x2000
	s_nop 0
	global_load_lds_dwordx4 v[154:155], off
	v_lshl_add_u64 v[154:155], v[224:225], 0, s[8:9]
	s_mov_b32 m0, s36
	s_nop 0
	global_load_lds_dwordx4 v[154:155], off
	v_lshl_add_u64 v[154:155], v[226:227], 0, s[8:9]
	s_mov_b32 m0, s37
	s_nop 0
	global_load_lds_dwordx4 v[154:155], off
	s_waitcnt vmcnt(8)
	s_waitcnt lgkmcnt(0)
	s_barrier
	v_mfma_f32_16x16x32_bf16 v[60:63], v[146:149], v[192:195], v[60:63]
	v_mfma_f32_16x16x32_bf16 v[56:59], v[164:167], v[192:195], v[56:59]
	v_mfma_f32_16x16x32_bf16 v[44:47], v[146:149], v[200:203], v[44:47]
	v_mfma_f32_16x16x32_bf16 v[40:43], v[164:167], v[200:203], v[40:43]
	v_mfma_f32_16x16x32_bf16 v[28:31], v[146:149], v[208:211], v[28:31]
	v_mfma_f32_16x16x32_bf16 v[24:27], v[164:167], v[208:211], v[24:27]
	v_mfma_f32_16x16x32_bf16 v[12:15], v[146:149], v[216:219], v[12:15]
	v_mfma_f32_16x16x32_bf16 v[8:11], v[164:167], v[216:219], v[8:11]
	v_mfma_f32_16x16x32_bf16 v[60:63], v[150:153], v[196:199], v[60:63]
	v_mfma_f32_16x16x32_bf16 v[56:59], v[168:171], v[196:199], v[56:59]
	v_mfma_f32_16x16x32_bf16 v[44:47], v[150:153], v[204:207], v[44:47]
	v_mfma_f32_16x16x32_bf16 v[40:43], v[168:171], v[204:207], v[40:43]
	v_mfma_f32_16x16x32_bf16 v[28:31], v[150:153], v[212:215], v[28:31]
	v_mfma_f32_16x16x32_bf16 v[24:27], v[168:171], v[212:215], v[24:27]
	v_mfma_f32_16x16x32_bf16 v[12:15], v[150:153], v[220:223], v[12:15]
	v_mfma_f32_16x16x32_bf16 v[8:11], v[168:171], v[220:223], v[8:11]
	v_mfma_f32_16x16x32_bf16 v[52:55], v[172:175], v[192:195], v[52:55]
	v_mfma_f32_16x16x32_bf16 v[48:51], v[180:183], v[192:195], v[48:51]
	v_mfma_f32_16x16x32_bf16 v[36:39], v[172:175], v[200:203], v[36:39]
	v_mfma_f32_16x16x32_bf16 v[32:35], v[180:183], v[200:203], v[32:35]
	v_mfma_f32_16x16x32_bf16 v[20:23], v[172:175], v[208:211], v[20:23]
	v_mfma_f32_16x16x32_bf16 v[16:19], v[180:183], v[208:211], v[16:19]
	v_mfma_f32_16x16x32_bf16 v[4:7], v[172:175], v[216:219], v[4:7]
	v_mfma_f32_16x16x32_bf16 v[0:3], v[180:183], v[216:219], v[0:3]
	v_mfma_f32_16x16x32_bf16 v[52:55], v[176:179], v[196:199], v[52:55]
	v_mfma_f32_16x16x32_bf16 v[48:51], v[188:191], v[196:199], v[48:51]
	v_mfma_f32_16x16x32_bf16 v[36:39], v[176:179], v[204:207], v[36:39]
	v_mfma_f32_16x16x32_bf16 v[32:35], v[188:191], v[204:207], v[32:35]
	v_mfma_f32_16x16x32_bf16 v[20:23], v[176:179], v[212:215], v[20:23]
	v_mfma_f32_16x16x32_bf16 v[16:19], v[188:191], v[212:215], v[16:19]
	v_mfma_f32_16x16x32_bf16 v[4:7], v[176:179], v[220:223], v[4:7]
	v_mfma_f32_16x16x32_bf16 v[0:3], v[188:191], v[220:223], v[0:3]
	s_barrier
	s_add_i32 s46, s46, 2
	s_add_u32 s22, s22, 0x100
	s_addc_u32 s23, s23, 0
	s_add_u32 s44, s44, 0x100
	s_addc_u32 s45, s45, 0
	s_cmp_gt_u32 s46, 13
	s_cbranch_scc0 .LBB0_572
	s_setprio 0
	s_and_b64 vcc, exec, s[10:11]
	s_cbranch_vccz .LBB0_575
	s_barrier

;     __device__ __forceinline__ bool next(int i, Unit& u) const { if (!base.next(i >> 1, u)) return false; if (i & 1) { u.pm += 64; u.pn += 8; } return true; }
; #define PG8_STAGE(bufoff, gbase, voff) do { _Pragma("unroll") for (int _i = 0; _i < 2; ++_i) \
;         __builtin_amdgcn_global_load_lds((const unsigned*)((const char*)(gbase) + (voff)[_i]), (PG8_LAS unsigned*)(lds + (bufoff) + ldsw + _i * 8192), 16, 0, 0); } while (0)
; #define PG8_LDA(dst, b, h) do { _Pragma("unroll") for (int m = 0; m < 4; ++m) _Pragma("unroll") for (int k = 0; k < 2; ++k) dst[m][k] = *(const PG8_LAS bf16x8*)(lds + PG8_SA(b, h) + aoff + m * 2048 + k * 1024); } while (0)
; #define PG8_LDB(dst, b, h) do { _Pragma("unroll") for (int n = 0; n < 2; ++n) _Pragma("unroll") for (int k = 0; k < 2; ++k) dst[n][k] = *(const PG8_LAS bf16x8*)(lds + PG8_SB(b, h) + boff + n * 2048 + k * 1024); } while (0)
; #define PG8_WAIT_V(n) asm volatile("s_waitcnt vmcnt(" #n ")" ::: "memory")
; #define PG8_BAR __builtin_amdgcn_s_barrier()
; template <class Epi, class Sched, bool ALIGN_EPI = false, bool SP2 = false>
; __device__ __forceinline__ void gemm_phase(PG8_LAS unsigned char* lds, const Gemm g, const Sched& S, const Epi& E) {
;     ...
;         const bool has_next = S.next(ui + 1, nxt);
;         const char* nA = has_next ? (const char*)g.A + (size_t)nxt.pm * tstep : cA; const char* nB = has_next ? (const char*)g.Bt + (size_t)nxt.pn * tstep : cB;
;         for (int t = 0; t < nt; t += 2) {
;             const bool last = (t == nt - 2);
;             const char* a1 = cA + (size_t)(t + 1) * kstep;
;             const char* a2 = last ? nA : cA + (size_t)(t + 2) * kstep; const char* b2 = last ? nB : cB + (size_t)(t + 2) * kstep;
;             const char* a3 = a2 + kstep; const char* b3 = b2 + kstep;
;             if (last && has_next) S.a_ready(nxt);
;             if constexpr (SP2) {
;             PG8_LDB(B0, 0, 0); PG8_LDB(B1, 0, 1); PG8_SCHED; PG8_LDA(At, 0, 0); PG8_STAGE(PG8_SA(1, 1), a1 + hstep, voffA);
;             PG8_WAIT_V(8); PG8_WAIT_L(0); PG8_BAR; PG8_MMA(0, 0, At, B0); PG8_MMA(0, 1, At, B1); PG8_BAR; PG8_SCHED;
;             PG8_LDA(At, 0, 1); PG8_STAGE(PG8_SB(0, 0), b2, voffB); PG8_STAGE(PG8_SB(0, 1), b2 + hstep, voffB); PG8_STAGE(PG8_SA(0, 0), a2, voffA);
;             PG8_WAIT_V(8); PG8_WAIT_L(0); PG8_BAR; PG8_MMA(1, 0, At, B0); PG8_MMA(1, 1, At, B1); PG8_BAR; PG8_SCHED;
.LBB0_893:
	s_ashr_i32 s25, s24, 31
	s_lshl_b64 s[28:29], s[24:25], 20
	v_readlane_b32 s30, v236, 50
	v_readlane_b32 s31, v236, 51
	s_add_u32 s28, s30, s28
	s_addc_u32 s29, s31, s29
	s_and_b64 s[30:31], s[6:7], exec
	s_cselect_b32 s25, s29, s39
	s_cselect_b32 s35, s28, s38
	s_ashr_i32 s27, s26, 31
	s_lshl_b64 s[30:31], s[26:27], 20
	v_readlane_b32 s42, v236, 43
	v_readlane_b32 s43, v236, 44
	s_add_u32 s30, s42, s30
	s_addc_u32 s31, s43, s31
	s_and_b64 s[42:43], s[6:7], exec
	s_cselect_b32 s27, s31, s41
	s_cselect_b32 s55, s30, s40
	s_add_u32 s38, s38, 0x80080
	s_addc_u32 s39, s39, 0
	s_add_u32 s56, s40, 0x100
	s_addc_u32 s57, s41, 0
	s_mov_b32 s58, -2
	s_waitcnt lgkmcnt(0)
	s_cmp_eq_u64 s[14:15], 0
	s_cbranch_scc0 .Lprio_skip_894
	s_setprio 1
.Lprio_skip_894:
	ds_read_b128 v[72:75], v169
	ds_read_b128 v[84:87], v169 offset:1024
	ds_read_b128 v[92:95], v169 offset:2048
	ds_read_b128 v[96:99], v169 offset:3072
	ds_read_b128 v[156:159], v170
	ds_read_b128 v[160:163], v170 offset:1024
	ds_read_b128 v[174:177], v170 offset:2048
	ds_read_b128 v[178:181], v170 offset:3072
	s_add_u32 s40, s38, 0xfff80080
	s_addc_u32 s41, s39, -1
	s_cmp_eq_u32 s58, 28
	s_cselect_b32 s43, s25, s41
	s_cselect_b32 s42, s35, s40
	s_cselect_b32 s41, s27, s57
	s_cselect_b32 s40, s55, s56
	v_lshl_add_u64 v[164:165], s[38:39], 0, v[148:149]
	s_add_i32 m0, s37, 0xc000
	ds_read_b128 v[182:185], v171
	ds_read_b128 v[188:191], v171 offset:1024
	ds_read_b128 v[192:195], v171 offset:2048
	ds_read_b128 v[196:199], v171 offset:3072
	ds_read_b128 v[200:203], v171 offset:4096
	ds_read_b128 v[204:207], v171 offset:5120
	ds_read_b128 v[208:211], v171 offset:6144
	ds_read_b128 v[212:215], v171 offset:7168
	global_load_lds_dwordx4 v[164:165], off
	v_lshl_add_u64 v[164:165], s[38:39], 0, v[150:151]
	s_add_i32 m0, s37, 0xe000
	s_nop 0
	global_load_lds_dwordx4 v[164:165], off
	s_waitcnt vmcnt(8)
	s_waitcnt lgkmcnt(0)
	s_barrier
	v_mfma_f32_16x16x32_bf16 v[140:143], v[72:75], v[182:185], 0
	v_mfma_f32_16x16x32_bf16 v[136:139], v[92:95], v[182:185], 0
	v_mfma_f32_16x16x32_bf16 v[124:127], v[72:75], v[192:195], 0
	v_mfma_f32_16x16x32_bf16 v[120:123], v[92:95], v[192:195], 0
	v_mfma_f32_16x16x32_bf16 v[108:111], v[72:75], v[200:203], 0
	v_mfma_f32_16x16x32_bf16 v[104:107], v[92:95], v[200:203], 0
	v_mfma_f32_16x16x32_bf16 v[80:83], v[72:75], v[208:211], 0
	v_mfma_f32_16x16x32_bf16 v[76:79], v[92:95], v[208:211], 0
	v_mfma_f32_16x16x32_bf16 v[140:143], v[84:87], v[188:191], v[140:143]
	v_mfma_f32_16x16x32_bf16 v[136:139], v[96:99], v[188:191], v[136:139]
	v_mfma_f32_16x16x32_bf16 v[124:127], v[84:87], v[196:199], v[124:127]
	v_mfma_f32_16x16x32_bf16 v[120:123], v[96:99], v[196:199], v[120:123]
	v_mfma_f32_16x16x32_bf16 v[108:111], v[84:87], v[204:207], v[108:111]
	v_mfma_f32_16x16x32_bf16 v[104:107], v[96:99], v[204:207], v[104:107]
	v_mfma_f32_16x16x32_bf16 v[80:83], v[84:87], v[212:215], v[80:83]
	v_mfma_f32_16x16x32_bf16 v[76:79], v[96:99], v[212:215], v[76:79]
	v_mfma_f32_16x16x32_bf16 v[132:135], v[156:159], v[182:185], 0
	v_mfma_f32_16x16x32_bf16 v[128:131], v[174:177], v[182:185], 0
	v_mfma_f32_16x16x32_bf16 v[116:119], v[156:159], v[192:195], 0
	v_mfma_f32_16x16x32_bf16 v[112:115], v[174:177], v[192:195], 0
	v_mfma_f32_16x16x32_bf16 v[100:103], v[156:159], v[200:203], 0
	v_mfma_f32_16x16x32_bf16 v[88:91], v[174:177], v[200:203], 0
	v_mfma_f32_16x16x32_bf16 v[68:71], v[156:159], v[208:211], 0
	v_mfma_f32_16x16x32_bf16 v[64:67], v[174:177], v[208:211], 0
	v_mfma_f32_16x16x32_bf16 v[132:135], v[160:163], v[188:191], v[132:135]
	v_mfma_f32_16x16x32_bf16 v[128:131], v[178:181], v[188:191], v[128:131]
	v_mfma_f32_16x16x32_bf16 v[116:119], v[160:163], v[196:199], v[116:119]
	v_mfma_f32_16x16x32_bf16 v[112:115], v[178:181], v[196:199], v[112:115]
	v_mfma_f32_16x16x32_bf16 v[100:103], v[160:163], v[204:207], v[100:103]
	v_mfma_f32_16x16x32_bf16 v[88:91], v[178:181], v[204:207], v[88:91]
	v_mfma_f32_16x16x32_bf16 v[68:71], v[160:163], v[212:215], v[68:71]
	v_mfma_f32_16x16x32_bf16 v[64:67], v[178:181], v[212:215], v[64:67]
	s_barrier
	s_add_i32 s59, s53, s33
	v_lshl_add_u64 v[164:165], s[40:41], 0, v[144:145]
	s_mov_b32 m0, s59
	ds_read_b128 v[182:185], v171 offset:16384
	ds_read_b128 v[188:191], v171 offset:17408
	ds_read_b128 v[192:195], v171 offset:18432
	ds_read_b128 v[196:199], v171 offset:19456
	ds_read_b128 v[200:203], v171 offset:20480
	ds_read_b128 v[204:207], v171 offset:21504
	ds_read_b128 v[208:211], v171 offset:22528
	ds_read_b128 v[212:215], v171 offset:23552
	global_load_lds_dwordx4 v[164:165], off
	s_add_i32 m0, s59, 0x2000
	s_add_u32 s60, s40, 0x80000
	v_lshl_add_u64 v[216:217], s[40:41], 0, v[146:147]
	s_addc_u32 s61, s41, 0
	s_add_i32 s59, s54, s33
	global_load_lds_dwordx4 v[216:217], off
	v_lshl_add_u64 v[218:219], s[60:61], 0, v[144:145]
	s_mov_b32 m0, s59
	v_lshl_add_u64 v[220:221], s[42:43], 0, v[146:147]
	global_load_lds_dwordx4 v[218:219], off
	v_lshl_add_u64 v[218:219], s[60:61], 0, v[146:147]
	s_add_i32 m0, s59, 0x2000
	s_nop 0
	global_load_lds_dwordx4 v[218:219], off
	v_lshl_add_u64 v[218:219], s[42:43], 0, v[144:145]
	s_mov_b32 m0, s37
	s_nop 0
	global_load_lds_dwordx4 v[218:219], off
	s_mov_b32 m0, s44
	s_nop 0
	global_load_lds_dwordx4 v[220:221], off
	s_waitcnt vmcnt(8)
	s_waitcnt lgkmcnt(0)
	s_barrier
; #define PG8_STAGE(bufoff, gbase, voff) do { _Pragma("unroll") for (int _i = 0; _i < 2; ++_i) \
;         __builtin_amdgcn_global_load_lds((const unsigned*)((const char*)(gbase) + (voff)[_i]), (PG8_LAS unsigned*)(lds + (bufoff) + ldsw + _i * 8192), 16, 0, 0); } while (0)
; #define PG8_LDA(dst, b, h) do { _Pragma("unroll") for (int m = 0; m < 4; ++m) _Pragma("unroll") for (int k = 0; k < 2; ++k) dst[m][k] = *(const PG8_LAS bf16x8*)(lds + PG8_SA(b, h) + aoff + m * 2048 + k * 1024); } while (0)
; #define PG8_LDB(dst, b, h) do { _Pragma("unroll") for (int n = 0; n < 2; ++n) _Pragma("unroll") for (int k = 0; k < 2; ++k) dst[n][k] = *(const PG8_LAS bf16x8*)(lds + PG8_SB(b, h) + boff + n * 2048 + k * 1024); } while (0)
; #define PG8_MMA(ai, bj, At, Bt) do { __builtin_amdgcn_s_setprio(1); _Pragma("unroll") for (int m = 0; m < 4; ++m) _Pragma("unroll") for (int n = 0; n < 2; ++n) _Pragma("unroll") for (int k = 0; k < 2; ++k) \
;         acc[ai][bj][m][n] = __builtin_amdgcn_mfma_f32_16x16x32_bf16(Bt[n][k], At[m][k], acc[ai][bj][m][n], 0, 0, 0); __builtin_amdgcn_s_setprio(0); } while (0)
; #define PG8_WAIT_V(n) asm volatile("s_waitcnt vmcnt(" #n ")" ::: "memory")
; #define PG8_WAIT_L(n) asm volatile("s_waitcnt lgkmcnt(" #n ")" ::: "memory")
; #define PG8_BAR __builtin_amdgcn_s_barrier()
; #define PG8_SCHED __builtin_amdgcn_sched_barrier(0)
; template <class Epi, class Sched, bool ALIGN_EPI = false, bool SP2 = false>
; __device__ __forceinline__ void gemm_phase(PG8_LAS unsigned char* lds, const Gemm g, const Sched& S, const Epi& E) {
;     ...
;             PG8_WAIT_V(8); PG8_WAIT_L(0); PG8_BAR; PG8_MMA(1, 0, At, B0); PG8_MMA(1, 1, At, B1); PG8_BAR; PG8_SCHED;
;             PG8_LDB(B0, 1, 0); PG8_LDB(B1, 1, 1); PG8_SCHED; PG8_LDA(At, 1, 0); PG8_STAGE(PG8_SA(0, 1), a2 + hstep, voffA);
;             PG8_WAIT_V(8); PG8_WAIT_L(0); PG8_BAR; PG8_MMA(0, 0, At, B0); PG8_MMA(0, 1, At, B1); PG8_BAR; PG8_SCHED;
	v_mfma_f32_16x16x32_bf16 v[60:63], v[72:75], v[182:185], 0
	v_mfma_f32_16x16x32_bf16 v[56:59], v[92:95], v[182:185], 0
	v_mfma_f32_16x16x32_bf16 v[44:47], v[72:75], v[192:195], 0
	v_mfma_f32_16x16x32_bf16 v[40:43], v[92:95], v[192:195], 0
	v_mfma_f32_16x16x32_bf16 v[28:31], v[72:75], v[200:203], 0
	v_mfma_f32_16x16x32_bf16 v[24:27], v[92:95], v[200:203], 0
	v_mfma_f32_16x16x32_bf16 v[12:15], v[72:75], v[208:211], 0
	v_mfma_f32_16x16x32_bf16 v[8:11], v[92:95], v[208:211], 0
	v_mfma_f32_16x16x32_bf16 v[60:63], v[84:87], v[188:191], v[60:63]
	v_mfma_f32_16x16x32_bf16 v[56:59], v[96:99], v[188:191], v[56:59]
	v_mfma_f32_16x16x32_bf16 v[44:47], v[84:87], v[196:199], v[44:47]
	v_mfma_f32_16x16x32_bf16 v[40:43], v[96:99], v[196:199], v[40:43]
	v_mfma_f32_16x16x32_bf16 v[28:31], v[84:87], v[204:207], v[28:31]
	v_mfma_f32_16x16x32_bf16 v[24:27], v[96:99], v[204:207], v[24:27]
	v_mfma_f32_16x16x32_bf16 v[12:15], v[84:87], v[212:215], v[12:15]
	v_mfma_f32_16x16x32_bf16 v[8:11], v[96:99], v[212:215], v[8:11]
	v_mfma_f32_16x16x32_bf16 v[52:55], v[156:159], v[182:185], 0
	v_mfma_f32_16x16x32_bf16 v[48:51], v[174:177], v[182:185], 0
	v_mfma_f32_16x16x32_bf16 v[36:39], v[156:159], v[192:195], 0
	v_mfma_f32_16x16x32_bf16 v[32:35], v[174:177], v[192:195], 0
	v_mfma_f32_16x16x32_bf16 v[20:23], v[156:159], v[200:203], 0
	v_mfma_f32_16x16x32_bf16 v[16:19], v[174:177], v[200:203], 0
	v_mfma_f32_16x16x32_bf16 v[4:7], v[156:159], v[208:211], 0
	v_mfma_f32_16x16x32_bf16 v[0:3], v[174:177], v[208:211], 0
	v_mfma_f32_16x16x32_bf16 v[52:55], v[160:163], v[188:191], v[52:55]
	v_mfma_f32_16x16x32_bf16 v[48:51], v[178:181], v[188:191], v[48:51]
	v_mfma_f32_16x16x32_bf16 v[36:39], v[160:163], v[196:199], v[36:39]
	v_mfma_f32_16x16x32_bf16 v[32:35], v[178:181], v[196:199], v[32:35]
	v_mfma_f32_16x16x32_bf16 v[20:23], v[160:163], v[204:207], v[20:23]
	v_mfma_f32_16x16x32_bf16 v[16:19], v[178:181], v[204:207], v[16:19]
	v_mfma_f32_16x16x32_bf16 v[4:7], v[160:163], v[212:215], v[4:7]
	v_mfma_f32_16x16x32_bf16 v[0:3], v[178:181], v[212:215], v[0:3]
	s_barrier
	s_add_i32 s59, 0, 0x18000
	s_add_i32 s60, 0, 0x1c000
	v_add_u32_e32 v96, s59, v167
	v_add_u32_e32 v173, s60, v167
	ds_read_b128 v[72:75], v96
	ds_read_b128 v[84:87], v96 offset:1024
	ds_read_b128 v[92:95], v96 offset:2048
	ds_read_b128 v[96:99], v96 offset:3072
	ds_read_b128 v[156:159], v173
	ds_read_b128 v[160:163], v173 offset:1024
	ds_read_b128 v[174:177], v173 offset:2048
	ds_read_b128 v[178:181], v173 offset:3072
	s_add_u32 s42, s42, 0x80000
	s_addc_u32 s43, s43, 0
	s_mov_b32 m0, s45
	v_lshl_add_u64 v[222:223], s[42:43], 0, v[144:145]
	ds_read_b128 v[182:185], v171 offset:32768
	ds_read_b128 v[188:191], v171 offset:33792
	ds_read_b128 v[192:195], v171 offset:34816
	ds_read_b128 v[196:199], v171 offset:35840
	ds_read_b128 v[200:203], v171 offset:36864
	ds_read_b128 v[204:207], v171 offset:37888
	ds_read_b128 v[208:211], v171 offset:38912
	ds_read_b128 v[212:215], v171 offset:39936
	global_load_lds_dwordx4 v[222:223], off
	v_lshl_add_u64 v[222:223], s[42:43], 0, v[146:147]
	s_mov_b32 m0, s46
	s_nop 0
	global_load_lds_dwordx4 v[222:223], off
	s_waitcnt vmcnt(8)
	s_waitcnt lgkmcnt(0)
	s_barrier
	v_mfma_f32_16x16x32_bf16 v[140:143], v[72:75], v[182:185], v[140:143]
	v_mfma_f32_16x16x32_bf16 v[136:139], v[92:95], v[182:185], v[136:139]
	v_mfma_f32_16x16x32_bf16 v[124:127], v[72:75], v[192:195], v[124:127]
	v_mfma_f32_16x16x32_bf16 v[120:123], v[92:95], v[192:195], v[120:123]
	v_mfma_f32_16x16x32_bf16 v[108:111], v[72:75], v[200:203], v[108:111]
	v_mfma_f32_16x16x32_bf16 v[104:107], v[92:95], v[200:203], v[104:107]
	v_mfma_f32_16x16x32_bf16 v[80:83], v[72:75], v[208:211], v[80:83]
	v_mfma_f32_16x16x32_bf16 v[76:79], v[92:95], v[208:211], v[76:79]
	v_mfma_f32_16x16x32_bf16 v[140:143], v[84:87], v[188:191], v[140:143]
	v_mfma_f32_16x16x32_bf16 v[136:139], v[96:99], v[188:191], v[136:139]
	v_mfma_f32_16x16x32_bf16 v[124:127], v[84:87], v[196:199], v[124:127]
	v_mfma_f32_16x16x32_bf16 v[120:123], v[96:99], v[196:199], v[120:123]
	v_mfma_f32_16x16x32_bf16 v[108:111], v[84:87], v[204:207], v[108:111]
	v_mfma_f32_16x16x32_bf16 v[104:107], v[96:99], v[204:207], v[104:107]
	v_mfma_f32_16x16x32_bf16 v[80:83], v[84:87], v[212:215], v[80:83]
	v_mfma_f32_16x16x32_bf16 v[76:79], v[96:99], v[212:215], v[76:79]
	v_mfma_f32_16x16x32_bf16 v[132:135], v[156:159], v[182:185], v[132:135]
	v_mfma_f32_16x16x32_bf16 v[128:131], v[174:177], v[182:185], v[128:131]
	v_mfma_f32_16x16x32_bf16 v[116:119], v[156:159], v[192:195], v[116:119]
	v_mfma_f32_16x16x32_bf16 v[112:115], v[174:177], v[192:195], v[112:115]
	v_mfma_f32_16x16x32_bf16 v[100:103], v[156:159], v[200:203], v[100:103]
	v_mfma_f32_16x16x32_bf16 v[88:91], v[174:177], v[200:203], v[88:91]
	v_mfma_f32_16x16x32_bf16 v[68:71], v[156:159], v[208:211], v[68:71]
	v_mfma_f32_16x16x32_bf16 v[64:67], v[174:177], v[208:211], v[64:67]
	v_mfma_f32_16x16x32_bf16 v[132:135], v[160:163], v[188:191], v[132:135]
	v_mfma_f32_16x16x32_bf16 v[128:131], v[178:181], v[188:191], v[128:131]
	v_mfma_f32_16x16x32_bf16 v[116:119], v[160:163], v[196:199], v[116:119]
	v_mfma_f32_16x16x32_bf16 v[112:115], v[178:181], v[196:199], v[112:115]
	v_mfma_f32_16x16x32_bf16 v[100:103], v[160:163], v[204:207], v[100:103]
	v_mfma_f32_16x16x32_bf16 v[88:91], v[178:181], v[204:207], v[88:91]
	v_mfma_f32_16x16x32_bf16 v[68:71], v[160:163], v[212:215], v[68:71]
	v_mfma_f32_16x16x32_bf16 v[64:67], v[178:181], v[212:215], v[64:67]
	s_barrier
; #define PG8_STAGE(bufoff, gbase, voff) do { _Pragma("unroll") for (int _i = 0; _i < 2; ++_i) \
;         __builtin_amdgcn_global_load_lds((const unsigned*)((const char*)(gbase) + (voff)[_i]), (PG8_LAS unsigned*)(lds + (bufoff) + ldsw + _i * 8192), 16, 0, 0); } while (0)
; #define PG8_LDA(dst, b, h) do { _Pragma("unroll") for (int m = 0; m < 4; ++m) _Pragma("unroll") for (int k = 0; k < 2; ++k) dst[m][k] = *(const PG8_LAS bf16x8*)(lds + PG8_SA(b, h) + aoff + m * 2048 + k * 1024); } while (0)
; #define PG8_LDB(dst, b, h) do { _Pragma("unroll") for (int n = 0; n < 2; ++n) _Pragma("unroll") for (int k = 0; k < 2; ++k) dst[n][k] = *(const PG8_LAS bf16x8*)(lds + PG8_SB(b, h) + boff + n * 2048 + k * 1024); } while (0)
; #define PG8_MMA(ai, bj, At, Bt) do { __builtin_amdgcn_s_setprio(1); _Pragma("unroll") for (int m = 0; m < 4; ++m) _Pragma("unroll") for (int n = 0; n < 2; ++n) _Pragma("unroll") for (int k = 0; k < 2; ++k) \
;         acc[ai][bj][m][n] = __builtin_amdgcn_mfma_f32_16x16x32_bf16(Bt[n][k], At[m][k], acc[ai][bj][m][n], 0, 0, 0); __builtin_amdgcn_s_setprio(0); } while (0)
; #define PG8_WAIT_V(n) asm volatile("s_waitcnt vmcnt(" #n ")" ::: "memory")
; template <class Epi, class Sched, bool ALIGN_EPI = false, bool SP2 = false>
; __device__ __forceinline__ void gemm_phase(PG8_LAS unsigned char* lds, const Gemm g, const Sched& S, const Epi& E) {
;     ...
;             PG8_LDB(B0, 0, 0); PG8_LDB(B1, 0, 1); PG8_SCHED; PG8_LDA(At, 0, 0); PG8_STAGE(PG8_SA(1, 1), a1 + hstep, voffA);
;             PG8_WAIT_V(8); PG8_WAIT_L(0); PG8_BAR; PG8_MMA(0, 0, At, B0); PG8_MMA(0, 1, At, B1); PG8_BAR; PG8_SCHED;
;             PG8_LDA(At, 0, 1); PG8_STAGE(PG8_SB(0, 0), b2, voffB); PG8_STAGE(PG8_SB(0, 1), b2 + hstep, voffB); PG8_STAGE(PG8_SA(0, 0), a2, voffA);
;             PG8_WAIT_V(8); PG8_WAIT_L(0); PG8_BAR; PG8_MMA(1, 0, At, B0); PG8_MMA(1, 1, At, B1); PG8_BAR; PG8_SCHED;
;             PG8_LDB(B0, 1, 0); PG8_LDB(B1, 1, 1); PG8_SCHED; PG8_LDA(At, 1, 0); PG8_STAGE(PG8_SA(0, 1), a2 + hstep, voffA);
;             PG8_WAIT_V(8); PG8_WAIT_L(0); PG8_BAR; PG8_MMA(0, 0, At, B0); PG8_MMA(0, 1, At, B1); PG8_BAR; PG8_SCHED;
;             PG8_LDA(At, 1, 1); PG8_STAGE(PG8_SB(1, 0), b3, voffB); PG8_STAGE(PG8_SB(1, 1), b3 + hstep, voffB); PG8_STAGE(PG8_SA(1, 0), a3, voffA);
;             PG8_WAIT_V(8); PG8_WAIT_L(0); PG8_BAR; PG8_MMA(1, 0, At, B0); PG8_MMA(1, 1, At, B1); PG8_BAR; PG8_SCHED;
	s_add_i32 s42, s59, s33
	v_lshl_add_u64 v[164:165], v[164:165], 0, s[12:13]
	s_mov_b32 m0, s42
	ds_read_b128 v[182:185], v171 offset:49152
	ds_read_b128 v[188:191], v171 offset:50176
	ds_read_b128 v[192:195], v171 offset:51200
	ds_read_b128 v[196:199], v171 offset:52224
	ds_read_b128 v[200:203], v171 offset:53248
	ds_read_b128 v[204:207], v171 offset:54272
	ds_read_b128 v[208:211], v171 offset:55296
	ds_read_b128 v[212:215], v171 offset:56320
	global_load_lds_dwordx4 v[164:165], off
	s_add_i32 m0, s42, 0x2000
	s_add_u32 s40, s40, 0x80080
	v_lshl_add_u64 v[164:165], v[216:217], 0, s[12:13]
	s_addc_u32 s41, s41, 0
	s_add_i32 s42, s60, s33
	global_load_lds_dwordx4 v[164:165], off
	v_lshl_add_u64 v[164:165], s[40:41], 0, v[144:145]
	s_mov_b32 m0, s42
	s_nop 0
	global_load_lds_dwordx4 v[164:165], off
	v_lshl_add_u64 v[164:165], s[40:41], 0, v[146:147]
	s_add_i32 m0, s42, 0x2000
	s_nop 0
	global_load_lds_dwordx4 v[164:165], off
	v_lshl_add_u64 v[164:165], v[218:219], 0, s[12:13]
	s_mov_b32 m0, s50
	s_nop 0
	global_load_lds_dwordx4 v[164:165], off
	v_lshl_add_u64 v[164:165], v[220:221], 0, s[12:13]
	s_mov_b32 m0, s51
	s_nop 0
	global_load_lds_dwordx4 v[164:165], off
	s_waitcnt vmcnt(8)
	s_waitcnt lgkmcnt(0)
	s_barrier
	v_mfma_f32_16x16x32_bf16 v[60:63], v[72:75], v[182:185], v[60:63]
	v_mfma_f32_16x16x32_bf16 v[56:59], v[92:95], v[182:185], v[56:59]
	v_mfma_f32_16x16x32_bf16 v[44:47], v[72:75], v[192:195], v[44:47]
	v_mfma_f32_16x16x32_bf16 v[40:43], v[92:95], v[192:195], v[40:43]
	v_mfma_f32_16x16x32_bf16 v[28:31], v[72:75], v[200:203], v[28:31]
	v_mfma_f32_16x16x32_bf16 v[24:27], v[92:95], v[200:203], v[24:27]
	v_mfma_f32_16x16x32_bf16 v[12:15], v[72:75], v[208:211], v[12:15]
	v_mfma_f32_16x16x32_bf16 v[8:11], v[92:95], v[208:211], v[8:11]
	v_mfma_f32_16x16x32_bf16 v[60:63], v[84:87], v[188:191], v[60:63]
	v_mfma_f32_16x16x32_bf16 v[56:59], v[96:99], v[188:191], v[56:59]
	v_mfma_f32_16x16x32_bf16 v[44:47], v[84:87], v[196:199], v[44:47]
	v_mfma_f32_16x16x32_bf16 v[40:43], v[96:99], v[196:199], v[40:43]
	v_mfma_f32_16x16x32_bf16 v[28:31], v[84:87], v[204:207], v[28:31]
	v_mfma_f32_16x16x32_bf16 v[24:27], v[96:99], v[204:207], v[24:27]
	v_mfma_f32_16x16x32_bf16 v[12:15], v[84:87], v[212:215], v[12:15]
	v_mfma_f32_16x16x32_bf16 v[8:11], v[96:99], v[212:215], v[8:11]
	v_mfma_f32_16x16x32_bf16 v[52:55], v[156:159], v[182:185], v[52:55]
	v_mfma_f32_16x16x32_bf16 v[48:51], v[174:177], v[182:185], v[48:51]
	v_mfma_f32_16x16x32_bf16 v[36:39], v[156:159], v[192:195], v[36:39]
	v_mfma_f32_16x16x32_bf16 v[32:35], v[174:177], v[192:195], v[32:35]
	v_mfma_f32_16x16x32_bf16 v[20:23], v[156:159], v[200:203], v[20:23]
	v_mfma_f32_16x16x32_bf16 v[16:19], v[174:177], v[200:203], v[16:19]
	v_mfma_f32_16x16x32_bf16 v[4:7], v[156:159], v[208:211], v[4:7]
	v_mfma_f32_16x16x32_bf16 v[0:3], v[174:177], v[208:211], v[0:3]
	v_mfma_f32_16x16x32_bf16 v[52:55], v[160:163], v[188:191], v[52:55]
	v_mfma_f32_16x16x32_bf16 v[48:51], v[178:181], v[188:191], v[48:51]
	v_mfma_f32_16x16x32_bf16 v[36:39], v[160:163], v[196:199], v[36:39]
	v_mfma_f32_16x16x32_bf16 v[32:35], v[178:181], v[196:199], v[32:35]
	v_mfma_f32_16x16x32_bf16 v[20:23], v[160:163], v[204:207], v[20:23]
	v_mfma_f32_16x16x32_bf16 v[16:19], v[178:181], v[204:207], v[16:19]
	v_mfma_f32_16x16x32_bf16 v[4:7], v[160:163], v[212:215], v[4:7]
	v_mfma_f32_16x16x32_bf16 v[0:3], v[178:181], v[212:215], v[0:3]
	s_barrier
	s_add_i32 s58, s58, 2
	s_add_u32 s38, s38, 0x100
	s_addc_u32 s39, s39, 0
	s_add_u32 s56, s56, 0x100
	s_addc_u32 s57, s57, 0
	s_cmp_gt_u32 s58, 29
.LBB0_894:
	ds_read_b128 v[72:75], v169
	ds_read_b128 v[84:87], v169 offset:1024
	ds_read_b128 v[92:95], v169 offset:2048
	ds_read_b128 v[96:99], v169 offset:3072
	ds_read_b128 v[156:159], v170
	ds_read_b128 v[160:163], v170 offset:1024
	ds_read_b128 v[174:177], v170 offset:2048
	ds_read_b128 v[178:181], v170 offset:3072
	s_add_u32 s40, s38, 0xfff80080
	s_addc_u32 s41, s39, -1
	s_cmp_eq_u32 s58, 28
	s_cselect_b32 s43, s25, s41
	s_cselect_b32 s42, s35, s40
	s_cselect_b32 s41, s27, s57
	s_cselect_b32 s40, s55, s56
	v_lshl_add_u64 v[164:165], s[38:39], 0, v[148:149]
	s_add_i32 m0, s37, 0xc000
	ds_read_b128 v[182:185], v171
	ds_read_b128 v[188:191], v171 offset:1024
	ds_read_b128 v[192:195], v171 offset:2048
	ds_read_b128 v[196:199], v171 offset:3072
	ds_read_b128 v[200:203], v171 offset:4096
	ds_read_b128 v[204:207], v171 offset:5120
	ds_read_b128 v[208:211], v171 offset:6144
	ds_read_b128 v[212:215], v171 offset:7168
	global_load_lds_dwordx4 v[164:165], off
	v_lshl_add_u64 v[164:165], s[38:39], 0, v[150:151]
	s_add_i32 m0, s37, 0xe000
	s_nop 0
	global_load_lds_dwordx4 v[164:165], off
	s_waitcnt vmcnt(8)
	s_waitcnt lgkmcnt(0)
	s_barrier
; #define PG8_STAGE(bufoff, gbase, voff) do { _Pragma("unroll") for (int _i = 0; _i < 2; ++_i) \
;         __builtin_amdgcn_global_load_lds((const unsigned*)((const char*)(gbase) + (voff)[_i]), (PG8_LAS unsigned*)(lds + (bufoff) + ldsw + _i * 8192), 16, 0, 0); } while (0)
; #define PG8_LDA(dst, b, h) do { _Pragma("unroll") for (int m = 0; m < 4; ++m) _Pragma("unroll") for (int k = 0; k < 2; ++k) dst[m][k] = *(const PG8_LAS bf16x8*)(lds + PG8_SA(b, h) + aoff + m * 2048 + k * 1024); } while (0)
; #define PG8_MMA(ai, bj, At, Bt) do { __builtin_amdgcn_s_setprio(1); _Pragma("unroll") for (int m = 0; m < 4; ++m) _Pragma("unroll") for (int n = 0; n < 2; ++n) _Pragma("unroll") for (int k = 0; k < 2; ++k) \
;         acc[ai][bj][m][n] = __builtin_amdgcn_mfma_f32_16x16x32_bf16(Bt[n][k], At[m][k], acc[ai][bj][m][n], 0, 0, 0); __builtin_amdgcn_s_setprio(0); } while (0)
; #define PG8_WAIT_V(n) asm volatile("s_waitcnt vmcnt(" #n ")" ::: "memory")
; #define PG8_WAIT_L(n) asm volatile("s_waitcnt lgkmcnt(" #n ")" ::: "memory")
; #define PG8_BAR __builtin_amdgcn_s_barrier()
; #define PG8_SCHED __builtin_amdgcn_sched_barrier(0)
; template <class Epi, class Sched, bool ALIGN_EPI = false, bool SP2 = false>
; __device__ __forceinline__ void gemm_phase(PG8_LAS unsigned char* lds, const Gemm g, const Sched& S, const Epi& E) {
;     ...
;             PG8_WAIT_V(8); PG8_WAIT_L(0); PG8_BAR; PG8_MMA(0, 0, At, B0); PG8_MMA(0, 1, At, B1); PG8_BAR; PG8_SCHED;
;             PG8_LDA(At, 0, 1); PG8_STAGE(PG8_SB(0, 0), b2, voffB); PG8_STAGE(PG8_SB(0, 1), b2 + hstep, voffB); PG8_STAGE(PG8_SA(0, 0), a2, voffA);
;             PG8_WAIT_V(8); PG8_WAIT_L(0); PG8_BAR; PG8_MMA(1, 0, At, B0); PG8_MMA(1, 1, At, B1); PG8_BAR; PG8_SCHED;
	v_mfma_f32_16x16x32_bf16 v[140:143], v[72:75], v[182:185], v[140:143]
	v_mfma_f32_16x16x32_bf16 v[136:139], v[92:95], v[182:185], v[136:139]
	v_mfma_f32_16x16x32_bf16 v[124:127], v[72:75], v[192:195], v[124:127]
	v_mfma_f32_16x16x32_bf16 v[120:123], v[92:95], v[192:195], v[120:123]
	v_mfma_f32_16x16x32_bf16 v[108:111], v[72:75], v[200:203], v[108:111]
	v_mfma_f32_16x16x32_bf16 v[104:107], v[92:95], v[200:203], v[104:107]
	v_mfma_f32_16x16x32_bf16 v[80:83], v[72:75], v[208:211], v[80:83]
	v_mfma_f32_16x16x32_bf16 v[76:79], v[92:95], v[208:211], v[76:79]
	v_mfma_f32_16x16x32_bf16 v[140:143], v[84:87], v[188:191], v[140:143]
	v_mfma_f32_16x16x32_bf16 v[136:139], v[96:99], v[188:191], v[136:139]
	v_mfma_f32_16x16x32_bf16 v[124:127], v[84:87], v[196:199], v[124:127]
	v_mfma_f32_16x16x32_bf16 v[120:123], v[96:99], v[196:199], v[120:123]
	v_mfma_f32_16x16x32_bf16 v[108:111], v[84:87], v[204:207], v[108:111]
	v_mfma_f32_16x16x32_bf16 v[104:107], v[96:99], v[204:207], v[104:107]
	v_mfma_f32_16x16x32_bf16 v[80:83], v[84:87], v[212:215], v[80:83]
	v_mfma_f32_16x16x32_bf16 v[76:79], v[96:99], v[212:215], v[76:79]
	v_mfma_f32_16x16x32_bf16 v[132:135], v[156:159], v[182:185], v[132:135]
	v_mfma_f32_16x16x32_bf16 v[128:131], v[174:177], v[182:185], v[128:131]
	v_mfma_f32_16x16x32_bf16 v[116:119], v[156:159], v[192:195], v[116:119]
	v_mfma_f32_16x16x32_bf16 v[112:115], v[174:177], v[192:195], v[112:115]
	v_mfma_f32_16x16x32_bf16 v[100:103], v[156:159], v[200:203], v[100:103]
	v_mfma_f32_16x16x32_bf16 v[88:91], v[174:177], v[200:203], v[88:91]
	v_mfma_f32_16x16x32_bf16 v[68:71], v[156:159], v[208:211], v[68:71]
	v_mfma_f32_16x16x32_bf16 v[64:67], v[174:177], v[208:211], v[64:67]
	v_mfma_f32_16x16x32_bf16 v[132:135], v[160:163], v[188:191], v[132:135]
	v_mfma_f32_16x16x32_bf16 v[128:131], v[178:181], v[188:191], v[128:131]
	v_mfma_f32_16x16x32_bf16 v[116:119], v[160:163], v[196:199], v[116:119]
	v_mfma_f32_16x16x32_bf16 v[112:115], v[178:181], v[196:199], v[112:115]
	v_mfma_f32_16x16x32_bf16 v[100:103], v[160:163], v[204:207], v[100:103]
	v_mfma_f32_16x16x32_bf16 v[88:91], v[178:181], v[204:207], v[88:91]
	v_mfma_f32_16x16x32_bf16 v[68:71], v[160:163], v[212:215], v[68:71]
	v_mfma_f32_16x16x32_bf16 v[64:67], v[178:181], v[212:215], v[64:67]
	s_barrier
	s_add_i32 s59, s53, s33
	v_lshl_add_u64 v[164:165], s[40:41], 0, v[144:145]
	s_mov_b32 m0, s59
	ds_read_b128 v[182:185], v171 offset:16384
	ds_read_b128 v[188:191], v171 offset:17408
	ds_read_b128 v[192:195], v171 offset:18432
	ds_read_b128 v[196:199], v171 offset:19456
	ds_read_b128 v[200:203], v171 offset:20480
	ds_read_b128 v[204:207], v171 offset:21504
	ds_read_b128 v[208:211], v171 offset:22528
	ds_read_b128 v[212:215], v171 offset:23552
	global_load_lds_dwordx4 v[164:165], off
	s_add_i32 m0, s59, 0x2000
	s_add_u32 s60, s40, 0x80000
	v_lshl_add_u64 v[216:217], s[40:41], 0, v[146:147]
	s_addc_u32 s61, s41, 0
	s_add_i32 s59, s54, s33
	global_load_lds_dwordx4 v[216:217], off
	v_lshl_add_u64 v[218:219], s[60:61], 0, v[144:145]
	s_mov_b32 m0, s59
	v_lshl_add_u64 v[220:221], s[42:43], 0, v[146:147]
	global_load_lds_dwordx4 v[218:219], off
	v_lshl_add_u64 v[218:219], s[60:61], 0, v[146:147]
	s_add_i32 m0, s59, 0x2000
	s_nop 0
	global_load_lds_dwordx4 v[218:219], off
	v_lshl_add_u64 v[218:219], s[42:43], 0, v[144:145]
	s_mov_b32 m0, s37
	s_nop 0
	global_load_lds_dwordx4 v[218:219], off
	s_mov_b32 m0, s44
	s_nop 0
	global_load_lds_dwordx4 v[220:221], off
	s_waitcnt vmcnt(8)
	s_waitcnt lgkmcnt(0)
	s_barrier
	v_mfma_f32_16x16x32_bf16 v[60:63], v[72:75], v[182:185], v[60:63]
	v_mfma_f32_16x16x32_bf16 v[56:59], v[92:95], v[182:185], v[56:59]
	v_mfma_f32_16x16x32_bf16 v[44:47], v[72:75], v[192:195], v[44:47]
	v_mfma_f32_16x16x32_bf16 v[40:43], v[92:95], v[192:195], v[40:43]
	v_mfma_f32_16x16x32_bf16 v[28:31], v[72:75], v[200:203], v[28:31]
	v_mfma_f32_16x16x32_bf16 v[24:27], v[92:95], v[200:203], v[24:27]
	v_mfma_f32_16x16x32_bf16 v[12:15], v[72:75], v[208:211], v[12:15]
	v_mfma_f32_16x16x32_bf16 v[8:11], v[92:95], v[208:211], v[8:11]
	v_mfma_f32_16x16x32_bf16 v[60:63], v[84:87], v[188:191], v[60:63]
	v_mfma_f32_16x16x32_bf16 v[56:59], v[96:99], v[188:191], v[56:59]
	v_mfma_f32_16x16x32_bf16 v[44:47], v[84:87], v[196:199], v[44:47]
	v_mfma_f32_16x16x32_bf16 v[40:43], v[96:99], v[196:199], v[40:43]
	v_mfma_f32_16x16x32_bf16 v[28:31], v[84:87], v[204:207], v[28:31]
	v_mfma_f32_16x16x32_bf16 v[24:27], v[96:99], v[204:207], v[24:27]
	v_mfma_f32_16x16x32_bf16 v[12:15], v[84:87], v[212:215], v[12:15]
	v_mfma_f32_16x16x32_bf16 v[8:11], v[96:99], v[212:215], v[8:11]
	v_mfma_f32_16x16x32_bf16 v[52:55], v[156:159], v[182:185], v[52:55]
	v_mfma_f32_16x16x32_bf16 v[48:51], v[174:177], v[182:185], v[48:51]
	v_mfma_f32_16x16x32_bf16 v[36:39], v[156:159], v[192:195], v[36:39]
	v_mfma_f32_16x16x32_bf16 v[32:35], v[174:177], v[192:195], v[32:35]
	v_mfma_f32_16x16x32_bf16 v[20:23], v[156:159], v[200:203], v[20:23]
	v_mfma_f32_16x16x32_bf16 v[16:19], v[174:177], v[200:203], v[16:19]
	v_mfma_f32_16x16x32_bf16 v[4:7], v[156:159], v[208:211], v[4:7]
	v_mfma_f32_16x16x32_bf16 v[0:3], v[174:177], v[208:211], v[0:3]
	v_mfma_f32_16x16x32_bf16 v[52:55], v[160:163], v[188:191], v[52:55]
	v_mfma_f32_16x16x32_bf16 v[48:51], v[178:181], v[188:191], v[48:51]
	v_mfma_f32_16x16x32_bf16 v[36:39], v[160:163], v[196:199], v[36:39]
	v_mfma_f32_16x16x32_bf16 v[32:35], v[178:181], v[196:199], v[32:35]
	v_mfma_f32_16x16x32_bf16 v[20:23], v[160:163], v[204:207], v[20:23]
	v_mfma_f32_16x16x32_bf16 v[16:19], v[178:181], v[204:207], v[16:19]
	v_mfma_f32_16x16x32_bf16 v[4:7], v[160:163], v[212:215], v[4:7]
	v_mfma_f32_16x16x32_bf16 v[0:3], v[178:181], v[212:215], v[0:3]
	s_barrier
; #define PG8_STAGE(bufoff, gbase, voff) do { _Pragma("unroll") for (int _i = 0; _i < 2; ++_i) \
;         __builtin_amdgcn_global_load_lds((const unsigned*)((const char*)(gbase) + (voff)[_i]), (PG8_LAS unsigned*)(lds + (bufoff) + ldsw + _i * 8192), 16, 0, 0); } while (0)
; #define PG8_LDA(dst, b, h) do { _Pragma("unroll") for (int m = 0; m < 4; ++m) _Pragma("unroll") for (int k = 0; k < 2; ++k) dst[m][k] = *(const PG8_LAS bf16x8*)(lds + PG8_SA(b, h) + aoff + m * 2048 + k * 1024); } while (0)
; #define PG8_LDB(dst, b, h) do { _Pragma("unroll") for (int n = 0; n < 2; ++n) _Pragma("unroll") for (int k = 0; k < 2; ++k) dst[n][k] = *(const PG8_LAS bf16x8*)(lds + PG8_SB(b, h) + boff + n * 2048 + k * 1024); } while (0)
; #define PG8_MMA(ai, bj, At, Bt) do { __builtin_amdgcn_s_setprio(1); _Pragma("unroll") for (int m = 0; m < 4; ++m) _Pragma("unroll") for (int n = 0; n < 2; ++n) _Pragma("unroll") for (int k = 0; k < 2; ++k) \
;         acc[ai][bj][m][n] = __builtin_amdgcn_mfma_f32_16x16x32_bf16(Bt[n][k], At[m][k], acc[ai][bj][m][n], 0, 0, 0); __builtin_amdgcn_s_setprio(0); } while (0)
; #define PG8_WAIT_V(n) asm volatile("s_waitcnt vmcnt(" #n ")" ::: "memory")
; #define PG8_WAIT_L(n) asm volatile("s_waitcnt lgkmcnt(" #n ")" ::: "memory")
; #define PG8_BAR __builtin_amdgcn_s_barrier()
; #define PG8_SCHED __builtin_amdgcn_sched_barrier(0)
; template <class Epi, class Sched, bool ALIGN_EPI = false, bool SP2 = false>
; __device__ __forceinline__ void gemm_phase(PG8_LAS unsigned char* lds, const Gemm g, const Sched& S, const Epi& E) {
;     ...
;             PG8_LDB(B0, 1, 0); PG8_LDB(B1, 1, 1); PG8_SCHED; PG8_LDA(At, 1, 0); PG8_STAGE(PG8_SA(0, 1), a2 + hstep, voffA);
;             PG8_WAIT_V(8); PG8_WAIT_L(0); PG8_BAR; PG8_MMA(0, 0, At, B0); PG8_MMA(0, 1, At, B1); PG8_BAR; PG8_SCHED;
;             PG8_LDA(At, 1, 1); PG8_STAGE(PG8_SB(1, 0), b3, voffB); PG8_STAGE(PG8_SB(1, 1), b3 + hstep, voffB); PG8_STAGE(PG8_SA(1, 0), a3, voffA);
;             PG8_WAIT_V(8); PG8_WAIT_L(0); PG8_BAR; PG8_MMA(1, 0, At, B0); PG8_MMA(1, 1, At, B1); PG8_BAR; PG8_SCHED;
;     ...
;         if constexpr (ALIGN_EPI) { if (wr == 0) PG8_BAR; }
	s_add_i32 s59, 0, 0x18000
	s_add_i32 s60, 0, 0x1c000
	v_add_u32_e32 v96, s59, v167
	v_add_u32_e32 v173, s60, v167
	ds_read_b128 v[72:75], v96
	ds_read_b128 v[84:87], v96 offset:1024
	ds_read_b128 v[92:95], v96 offset:2048
	ds_read_b128 v[96:99], v96 offset:3072
	ds_read_b128 v[156:159], v173
	ds_read_b128 v[160:163], v173 offset:1024
	ds_read_b128 v[174:177], v173 offset:2048
	ds_read_b128 v[178:181], v173 offset:3072
	s_add_u32 s42, s42, 0x80000
	s_addc_u32 s43, s43, 0
	s_mov_b32 m0, s45
	v_lshl_add_u64 v[222:223], s[42:43], 0, v[144:145]
	ds_read_b128 v[182:185], v171 offset:32768
	ds_read_b128 v[188:191], v171 offset:33792
	ds_read_b128 v[192:195], v171 offset:34816
	ds_read_b128 v[196:199], v171 offset:35840
	ds_read_b128 v[200:203], v171 offset:36864
	ds_read_b128 v[204:207], v171 offset:37888
	ds_read_b128 v[208:211], v171 offset:38912
	ds_read_b128 v[212:215], v171 offset:39936
	global_load_lds_dwordx4 v[222:223], off
	v_lshl_add_u64 v[222:223], s[42:43], 0, v[146:147]
	s_mov_b32 m0, s46
	s_nop 0
	global_load_lds_dwordx4 v[222:223], off
	s_waitcnt vmcnt(8)
	s_waitcnt lgkmcnt(0)
	s_barrier
	v_mfma_f32_16x16x32_bf16 v[140:143], v[72:75], v[182:185], v[140:143]
	v_mfma_f32_16x16x32_bf16 v[136:139], v[92:95], v[182:185], v[136:139]
	v_mfma_f32_16x16x32_bf16 v[124:127], v[72:75], v[192:195], v[124:127]
	v_mfma_f32_16x16x32_bf16 v[120:123], v[92:95], v[192:195], v[120:123]
	v_mfma_f32_16x16x32_bf16 v[108:111], v[72:75], v[200:203], v[108:111]
	v_mfma_f32_16x16x32_bf16 v[104:107], v[92:95], v[200:203], v[104:107]
	v_mfma_f32_16x16x32_bf16 v[80:83], v[72:75], v[208:211], v[80:83]
	v_mfma_f32_16x16x32_bf16 v[76:79], v[92:95], v[208:211], v[76:79]
	v_mfma_f32_16x16x32_bf16 v[140:143], v[84:87], v[188:191], v[140:143]
	v_mfma_f32_16x16x32_bf16 v[136:139], v[96:99], v[188:191], v[136:139]
	v_mfma_f32_16x16x32_bf16 v[124:127], v[84:87], v[196:199], v[124:127]
	v_mfma_f32_16x16x32_bf16 v[120:123], v[96:99], v[196:199], v[120:123]
	v_mfma_f32_16x16x32_bf16 v[108:111], v[84:87], v[204:207], v[108:111]
	v_mfma_f32_16x16x32_bf16 v[104:107], v[96:99], v[204:207], v[104:107]
	v_mfma_f32_16x16x32_bf16 v[80:83], v[84:87], v[212:215], v[80:83]
	v_mfma_f32_16x16x32_bf16 v[76:79], v[96:99], v[212:215], v[76:79]
	v_mfma_f32_16x16x32_bf16 v[132:135], v[156:159], v[182:185], v[132:135]
	v_mfma_f32_16x16x32_bf16 v[128:131], v[174:177], v[182:185], v[128:131]
	v_mfma_f32_16x16x32_bf16 v[116:119], v[156:159], v[192:195], v[116:119]
	v_mfma_f32_16x16x32_bf16 v[112:115], v[174:177], v[192:195], v[112:115]
	v_mfma_f32_16x16x32_bf16 v[100:103], v[156:159], v[200:203], v[100:103]
	v_mfma_f32_16x16x32_bf16 v[88:91], v[174:177], v[200:203], v[88:91]
	v_mfma_f32_16x16x32_bf16 v[68:71], v[156:159], v[208:211], v[68:71]
	v_mfma_f32_16x16x32_bf16 v[64:67], v[174:177], v[208:211], v[64:67]
	v_mfma_f32_16x16x32_bf16 v[132:135], v[160:163], v[188:191], v[132:135]
	v_mfma_f32_16x16x32_bf16 v[128:131], v[178:181], v[188:191], v[128:131]
	v_mfma_f32_16x16x32_bf16 v[116:119], v[160:163], v[196:199], v[116:119]
	v_mfma_f32_16x16x32_bf16 v[112:115], v[178:181], v[196:199], v[112:115]
	v_mfma_f32_16x16x32_bf16 v[100:103], v[160:163], v[204:207], v[100:103]
	v_mfma_f32_16x16x32_bf16 v[88:91], v[178:181], v[204:207], v[88:91]
	v_mfma_f32_16x16x32_bf16 v[68:71], v[160:163], v[212:215], v[68:71]
	v_mfma_f32_16x16x32_bf16 v[64:67], v[178:181], v[212:215], v[64:67]
	s_barrier
	s_add_i32 s42, s59, s33
	v_lshl_add_u64 v[164:165], v[164:165], 0, s[12:13]
	s_mov_b32 m0, s42
	ds_read_b128 v[182:185], v171 offset:49152
	ds_read_b128 v[188:191], v171 offset:50176
	ds_read_b128 v[192:195], v171 offset:51200
	ds_read_b128 v[196:199], v171 offset:52224
	ds_read_b128 v[200:203], v171 offset:53248
	ds_read_b128 v[204:207], v171 offset:54272
	ds_read_b128 v[208:211], v171 offset:55296
	ds_read_b128 v[212:215], v171 offset:56320
	global_load_lds_dwordx4 v[164:165], off
	s_add_i32 m0, s42, 0x2000
	s_add_u32 s40, s40, 0x80080
	v_lshl_add_u64 v[164:165], v[216:217], 0, s[12:13]
	s_addc_u32 s41, s41, 0
	s_add_i32 s42, s60, s33
	global_load_lds_dwordx4 v[164:165], off
	v_lshl_add_u64 v[164:165], s[40:41], 0, v[144:145]
	s_mov_b32 m0, s42
	s_nop 0
	global_load_lds_dwordx4 v[164:165], off
	v_lshl_add_u64 v[164:165], s[40:41], 0, v[146:147]
	s_add_i32 m0, s42, 0x2000
	s_nop 0
	global_load_lds_dwordx4 v[164:165], off
	v_lshl_add_u64 v[164:165], v[218:219], 0, s[12:13]
	s_mov_b32 m0, s50
	s_nop 0
	global_load_lds_dwordx4 v[164:165], off
	v_lshl_add_u64 v[164:165], v[220:221], 0, s[12:13]
	s_mov_b32 m0, s51
	s_nop 0
	global_load_lds_dwordx4 v[164:165], off
	s_waitcnt vmcnt(8)
	s_waitcnt lgkmcnt(0)
	s_barrier
	v_mfma_f32_16x16x32_bf16 v[60:63], v[72:75], v[182:185], v[60:63]
	v_mfma_f32_16x16x32_bf16 v[56:59], v[92:95], v[182:185], v[56:59]
	v_mfma_f32_16x16x32_bf16 v[44:47], v[72:75], v[192:195], v[44:47]
	v_mfma_f32_16x16x32_bf16 v[40:43], v[92:95], v[192:195], v[40:43]
	v_mfma_f32_16x16x32_bf16 v[28:31], v[72:75], v[200:203], v[28:31]
	v_mfma_f32_16x16x32_bf16 v[24:27], v[92:95], v[200:203], v[24:27]
	v_mfma_f32_16x16x32_bf16 v[12:15], v[72:75], v[208:211], v[12:15]
	v_mfma_f32_16x16x32_bf16 v[8:11], v[92:95], v[208:211], v[8:11]
	v_mfma_f32_16x16x32_bf16 v[60:63], v[84:87], v[188:191], v[60:63]
	v_mfma_f32_16x16x32_bf16 v[56:59], v[96:99], v[188:191], v[56:59]
	v_mfma_f32_16x16x32_bf16 v[44:47], v[84:87], v[196:199], v[44:47]
	v_mfma_f32_16x16x32_bf16 v[40:43], v[96:99], v[196:199], v[40:43]
	v_mfma_f32_16x16x32_bf16 v[28:31], v[84:87], v[204:207], v[28:31]
	v_mfma_f32_16x16x32_bf16 v[24:27], v[96:99], v[204:207], v[24:27]
	v_mfma_f32_16x16x32_bf16 v[12:15], v[84:87], v[212:215], v[12:15]
	v_mfma_f32_16x16x32_bf16 v[8:11], v[96:99], v[212:215], v[8:11]
	v_mfma_f32_16x16x32_bf16 v[52:55], v[156:159], v[182:185], v[52:55]
	v_mfma_f32_16x16x32_bf16 v[48:51], v[174:177], v[182:185], v[48:51]
	v_mfma_f32_16x16x32_bf16 v[36:39], v[156:159], v[192:195], v[36:39]
	v_mfma_f32_16x16x32_bf16 v[32:35], v[174:177], v[192:195], v[32:35]
	v_mfma_f32_16x16x32_bf16 v[20:23], v[156:159], v[200:203], v[20:23]
	v_mfma_f32_16x16x32_bf16 v[16:19], v[174:177], v[200:203], v[16:19]
	v_mfma_f32_16x16x32_bf16 v[4:7], v[156:159], v[208:211], v[4:7]
	v_mfma_f32_16x16x32_bf16 v[0:3], v[174:177], v[208:211], v[0:3]
	v_mfma_f32_16x16x32_bf16 v[52:55], v[160:163], v[188:191], v[52:55]
	v_mfma_f32_16x16x32_bf16 v[48:51], v[178:181], v[188:191], v[48:51]
	v_mfma_f32_16x16x32_bf16 v[36:39], v[160:163], v[196:199], v[36:39]
	v_mfma_f32_16x16x32_bf16 v[32:35], v[178:181], v[196:199], v[32:35]
	v_mfma_f32_16x16x32_bf16 v[20:23], v[160:163], v[204:207], v[20:23]
	v_mfma_f32_16x16x32_bf16 v[16:19], v[178:181], v[204:207], v[16:19]
	v_mfma_f32_16x16x32_bf16 v[4:7], v[160:163], v[212:215], v[4:7]
	v_mfma_f32_16x16x32_bf16 v[0:3], v[178:181], v[212:215], v[0:3]
	s_barrier
	s_add_i32 s58, s58, 2
	s_add_u32 s38, s38, 0x100
	s_addc_u32 s39, s39, 0
	s_add_u32 s56, s56, 0x100
	s_addc_u32 s57, s57, 0
	s_cmp_gt_u32 s58, 29
	s_cbranch_scc0 .LBB0_894
	s_setprio 0
	s_and_b64 vcc, exec, s[14:15]
	s_cbranch_vccz .LBB0_897
	s_barrier

;     __device__ __forceinline__ bool next(int i, Unit& u) const { if (!base.next(i >> 1, u)) return false; if (i & 1) { u.pm += 64; u.pn += 8; } return true; }
; #define PG8_STAGE(bufoff, gbase, voff) do { _Pragma("unroll") for (int _i = 0; _i < 2; ++_i) \
;         __builtin_amdgcn_global_load_lds((const unsigned*)((const char*)(gbase) + (voff)[_i]), (PG8_LAS unsigned*)(lds + (bufoff) + ldsw + _i * 8192), 16, 0, 0); } while (0)
; #define PG8_LDA(dst, b, h) do { _Pragma("unroll") for (int m = 0; m < 4; ++m) _Pragma("unroll") for (int k = 0; k < 2; ++k) dst[m][k] = *(const PG8_LAS bf16x8*)(lds + PG8_SA(b, h) + aoff + m * 2048 + k * 1024); } while (0)
; #define PG8_LDB(dst, b, h) do { _Pragma("unroll") for (int n = 0; n < 2; ++n) _Pragma("unroll") for (int k = 0; k < 2; ++k) dst[n][k] = *(const PG8_LAS bf16x8*)(lds + PG8_SB(b, h) + boff + n * 2048 + k * 1024); } while (0)
; #define PG8_WAIT_V(n) asm volatile("s_waitcnt vmcnt(" #n ")" ::: "memory")
; #define PG8_BAR __builtin_amdgcn_s_barrier()
; template <class Epi, class Sched, bool ALIGN_EPI = false, bool SP2 = false>
; __device__ __forceinline__ void gemm_phase(PG8_LAS unsigned char* lds, const Gemm g, const Sched& S, const Epi& E) {
;     ...
;         const bool has_next = S.next(ui + 1, nxt);
;         const char* nA = has_next ? (const char*)g.A + (size_t)nxt.pm * tstep : cA; const char* nB = has_next ? (const char*)g.Bt + (size_t)nxt.pn * tstep : cB;
;         for (int t = 0; t < nt; t += 2) {
;             const bool last = (t == nt - 2);
;             const char* a1 = cA + (size_t)(t + 1) * kstep;
;             const char* a2 = last ? nA : cA + (size_t)(t + 2) * kstep; const char* b2 = last ? nB : cB + (size_t)(t + 2) * kstep;
;             const char* a3 = a2 + kstep; const char* b3 = b2 + kstep;
;             if (last && has_next) S.a_ready(nxt);
;             if constexpr (SP2) {
;             PG8_LDB(B0, 0, 0); PG8_LDB(B1, 0, 1); PG8_SCHED; PG8_LDA(At, 0, 0); PG8_STAGE(PG8_SA(1, 1), a1 + hstep, voffA);
;             PG8_WAIT_V(8); PG8_WAIT_L(0); PG8_BAR; PG8_MMA(0, 0, At, B0); PG8_MMA(0, 1, At, B1); PG8_BAR; PG8_SCHED;
;             PG8_LDA(At, 0, 1); PG8_STAGE(PG8_SB(0, 0), b2, voffB); PG8_STAGE(PG8_SB(0, 1), b2 + hstep, voffB); PG8_STAGE(PG8_SA(0, 0), a2, voffA);
;             PG8_WAIT_V(8); PG8_WAIT_L(0); PG8_BAR; PG8_MMA(1, 0, At, B0); PG8_MMA(1, 1, At, B1); PG8_BAR; PG8_SCHED;
.LBB0_993:
	s_ashr_i32 s15, s14, 31
	s_lshl_b64 s[18:19], s[14:15], 20
	s_add_u32 s18, s8, s18
	s_addc_u32 s19, s9, s19
	s_and_b64 s[20:21], s[4:5], exec
	s_cselect_b32 s15, s19, s25
	s_cselect_b32 s43, s18, s24
	s_ashr_i32 s17, s16, 31
	s_lshl_b64 s[20:21], s[16:17], 20
	v_readlane_b32 s28, v236, 52
	v_readlane_b32 s29, v236, 53
	s_add_u32 s20, s28, s20
	s_addc_u32 s21, s29, s21
	s_and_b64 s[28:29], s[4:5], exec
	s_cselect_b32 s17, s21, s27
	s_cselect_b32 s44, s20, s26
	s_add_u32 s24, s24, 0x80080
	s_addc_u32 s25, s25, 0
	s_add_u32 s45, s26, 0x100
	s_addc_u32 s46, s27, 0
	s_mov_b32 s47, -2
	s_cmp_eq_u64 s[12:13], 0
	s_cbranch_scc0 .Lprio_skip_994
	s_setprio 1
.Lprio_skip_994:
	ds_read_b128 v[128:131], v173
	ds_read_b128 v[132:135], v173 offset:1024
	ds_read_b128 v[136:139], v173 offset:2048
	ds_read_b128 v[140:143], v173 offset:3072
	ds_read_b128 v[176:179], v174
	ds_read_b128 v[180:183], v174 offset:1024
	ds_read_b128 v[188:191], v174 offset:2048
	ds_read_b128 v[192:195], v174 offset:3072
	s_add_u32 s26, s24, 0xfff80080
	s_addc_u32 s27, s25, -1
	s_cmp_eq_u32 s47, 28
	s_cselect_b32 s29, s15, s27
	s_cselect_b32 s28, s43, s26
	s_cselect_b32 s27, s17, s46
	s_cselect_b32 s26, s44, s45
	v_lshl_add_u64 v[160:161], s[24:25], 0, v[152:153]
	s_add_i32 m0, s23, 0xc000
	ds_read_b128 v[196:199], v175
	ds_read_b128 v[200:203], v175 offset:1024
	ds_read_b128 v[204:207], v175 offset:2048
	ds_read_b128 v[208:211], v175 offset:3072
	ds_read_b128 v[212:215], v175 offset:4096
	ds_read_b128 v[216:219], v175 offset:5120
	ds_read_b128 v[220:223], v175 offset:6144
	ds_read_b128 v[224:227], v175 offset:7168
	global_load_lds_dwordx4 v[160:161], off
	v_lshl_add_u64 v[160:161], s[24:25], 0, v[154:155]
	s_add_i32 m0, s23, 0xe000
	s_nop 0
	global_load_lds_dwordx4 v[160:161], off
	s_waitcnt vmcnt(8)
	s_waitcnt lgkmcnt(0)
	s_barrier
	v_mfma_f32_16x16x32_bf16 v[124:127], v[128:131], v[196:199], 0
	v_mfma_f32_16x16x32_bf16 v[120:123], v[136:139], v[196:199], 0
	v_mfma_f32_16x16x32_bf16 v[108:111], v[128:131], v[204:207], 0
	v_mfma_f32_16x16x32_bf16 v[104:107], v[136:139], v[204:207], 0
	v_mfma_f32_16x16x32_bf16 v[92:95], v[128:131], v[212:215], 0
	v_mfma_f32_16x16x32_bf16 v[88:91], v[136:139], v[212:215], 0
	v_mfma_f32_16x16x32_bf16 v[76:79], v[128:131], v[220:223], 0
	v_mfma_f32_16x16x32_bf16 v[72:75], v[136:139], v[220:223], 0
	v_mfma_f32_16x16x32_bf16 v[124:127], v[132:135], v[200:203], v[124:127]
	v_mfma_f32_16x16x32_bf16 v[120:123], v[140:143], v[200:203], v[120:123]
	v_mfma_f32_16x16x32_bf16 v[108:111], v[132:135], v[208:211], v[108:111]
	v_mfma_f32_16x16x32_bf16 v[104:107], v[140:143], v[208:211], v[104:107]
	v_mfma_f32_16x16x32_bf16 v[92:95], v[132:135], v[216:219], v[92:95]
	v_mfma_f32_16x16x32_bf16 v[88:91], v[140:143], v[216:219], v[88:91]
	v_mfma_f32_16x16x32_bf16 v[76:79], v[132:135], v[224:227], v[76:79]
	v_mfma_f32_16x16x32_bf16 v[72:75], v[140:143], v[224:227], v[72:75]
	v_mfma_f32_16x16x32_bf16 v[116:119], v[176:179], v[196:199], 0
	v_mfma_f32_16x16x32_bf16 v[112:115], v[188:191], v[196:199], 0
	v_mfma_f32_16x16x32_bf16 v[100:103], v[176:179], v[204:207], 0
	v_mfma_f32_16x16x32_bf16 v[96:99], v[188:191], v[204:207], 0
	v_mfma_f32_16x16x32_bf16 v[84:87], v[176:179], v[212:215], 0
	v_mfma_f32_16x16x32_bf16 v[80:83], v[188:191], v[212:215], 0
	v_mfma_f32_16x16x32_bf16 v[68:71], v[176:179], v[220:223], 0
	v_mfma_f32_16x16x32_bf16 v[64:67], v[188:191], v[220:223], 0
	v_mfma_f32_16x16x32_bf16 v[116:119], v[180:183], v[200:203], v[116:119]
	v_mfma_f32_16x16x32_bf16 v[112:115], v[192:195], v[200:203], v[112:115]
	v_mfma_f32_16x16x32_bf16 v[100:103], v[180:183], v[208:211], v[100:103]
	v_mfma_f32_16x16x32_bf16 v[96:99], v[192:195], v[208:211], v[96:99]
	v_mfma_f32_16x16x32_bf16 v[84:87], v[180:183], v[216:219], v[84:87]
	v_mfma_f32_16x16x32_bf16 v[80:83], v[192:195], v[216:219], v[80:83]
	v_mfma_f32_16x16x32_bf16 v[68:71], v[180:183], v[224:227], v[68:71]
	v_mfma_f32_16x16x32_bf16 v[64:67], v[192:195], v[224:227], v[64:67]
	s_barrier
	s_add_i32 s48, s40, s31
	v_lshl_add_u64 v[160:161], s[26:27], 0, v[146:147]
	s_mov_b32 m0, s48
	ds_read_b128 v[196:199], v175 offset:16384
	ds_read_b128 v[200:203], v175 offset:17408
	ds_read_b128 v[204:207], v175 offset:18432
	ds_read_b128 v[208:211], v175 offset:19456
	ds_read_b128 v[212:215], v175 offset:20480
	ds_read_b128 v[216:219], v175 offset:21504
	ds_read_b128 v[220:223], v175 offset:22528
	ds_read_b128 v[224:227], v175 offset:23552
	global_load_lds_dwordx4 v[160:161], off
	s_add_i32 m0, s48, 0x2000
	s_add_u32 s48, s26, 0x80000
	v_lshl_add_u64 v[184:185], s[26:27], 0, v[150:151]
	s_addc_u32 s49, s27, 0
	s_add_i32 s50, s41, s31
	global_load_lds_dwordx4 v[184:185], off
	v_lshl_add_u64 v[228:229], s[48:49], 0, v[146:147]
	s_mov_b32 m0, s50
	v_lshl_add_u64 v[230:231], s[28:29], 0, v[148:149]
	global_load_lds_dwordx4 v[228:229], off
	v_lshl_add_u64 v[228:229], s[48:49], 0, v[150:151]
	s_add_i32 m0, s50, 0x2000
	s_nop 0
	global_load_lds_dwordx4 v[228:229], off
	v_lshl_add_u64 v[228:229], s[28:29], 0, v[144:145]
	s_mov_b32 m0, s23
	s_nop 0
	global_load_lds_dwordx4 v[228:229], off
	s_mov_b32 m0, s33
	s_nop 0
	global_load_lds_dwordx4 v[230:231], off
	s_waitcnt vmcnt(8)
	s_waitcnt lgkmcnt(0)
	s_barrier
; #define PG8_STAGE(bufoff, gbase, voff) do { _Pragma("unroll") for (int _i = 0; _i < 2; ++_i) \
;         __builtin_amdgcn_global_load_lds((const unsigned*)((const char*)(gbase) + (voff)[_i]), (PG8_LAS unsigned*)(lds + (bufoff) + ldsw + _i * 8192), 16, 0, 0); } while (0)
; #define PG8_LDA(dst, b, h) do { _Pragma("unroll") for (int m = 0; m < 4; ++m) _Pragma("unroll") for (int k = 0; k < 2; ++k) dst[m][k] = *(const PG8_LAS bf16x8*)(lds + PG8_SA(b, h) + aoff + m * 2048 + k * 1024); } while (0)
; #define PG8_LDB(dst, b, h) do { _Pragma("unroll") for (int n = 0; n < 2; ++n) _Pragma("unroll") for (int k = 0; k < 2; ++k) dst[n][k] = *(const PG8_LAS bf16x8*)(lds + PG8_SB(b, h) + boff + n * 2048 + k * 1024); } while (0)
; #define PG8_MMA(ai, bj, At, Bt) do { __builtin_amdgcn_s_setprio(1); _Pragma("unroll") for (int m = 0; m < 4; ++m) _Pragma("unroll") for (int n = 0; n < 2; ++n) _Pragma("unroll") for (int k = 0; k < 2; ++k) \
;         acc[ai][bj][m][n] = __builtin_amdgcn_mfma_f32_16x16x32_bf16(Bt[n][k], At[m][k], acc[ai][bj][m][n], 0, 0, 0); __builtin_amdgcn_s_setprio(0); } while (0)
; #define PG8_WAIT_V(n) asm volatile("s_waitcnt vmcnt(" #n ")" ::: "memory")
; #define PG8_WAIT_L(n) asm volatile("s_waitcnt lgkmcnt(" #n ")" ::: "memory")
; #define PG8_BAR __builtin_amdgcn_s_barrier()
; #define PG8_SCHED __builtin_amdgcn_sched_barrier(0)
; template <class Epi, class Sched, bool ALIGN_EPI = false, bool SP2 = false>
; __device__ __forceinline__ void gemm_phase(PG8_LAS unsigned char* lds, const Gemm g, const Sched& S, const Epi& E) {
;     ...
;             PG8_WAIT_V(8); PG8_WAIT_L(0); PG8_BAR; PG8_MMA(1, 0, At, B0); PG8_MMA(1, 1, At, B1); PG8_BAR; PG8_SCHED;
;             PG8_LDB(B0, 1, 0); PG8_LDB(B1, 1, 1); PG8_SCHED; PG8_LDA(At, 1, 0); PG8_STAGE(PG8_SA(0, 1), a2 + hstep, voffA);
;             PG8_WAIT_V(8); PG8_WAIT_L(0); PG8_BAR; PG8_MMA(0, 0, At, B0); PG8_MMA(0, 1, At, B1); PG8_BAR; PG8_SCHED;
	v_mfma_f32_16x16x32_bf16 v[60:63], v[128:131], v[196:199], 0
	v_mfma_f32_16x16x32_bf16 v[56:59], v[136:139], v[196:199], 0
	v_mfma_f32_16x16x32_bf16 v[44:47], v[128:131], v[204:207], 0
	v_mfma_f32_16x16x32_bf16 v[40:43], v[136:139], v[204:207], 0
	v_mfma_f32_16x16x32_bf16 v[28:31], v[128:131], v[212:215], 0
	v_mfma_f32_16x16x32_bf16 v[24:27], v[136:139], v[212:215], 0
	v_mfma_f32_16x16x32_bf16 v[12:15], v[128:131], v[220:223], 0
	v_mfma_f32_16x16x32_bf16 v[8:11], v[136:139], v[220:223], 0
	v_mfma_f32_16x16x32_bf16 v[60:63], v[132:135], v[200:203], v[60:63]
	v_mfma_f32_16x16x32_bf16 v[56:59], v[140:143], v[200:203], v[56:59]
	v_mfma_f32_16x16x32_bf16 v[44:47], v[132:135], v[208:211], v[44:47]
	v_mfma_f32_16x16x32_bf16 v[40:43], v[140:143], v[208:211], v[40:43]
	v_mfma_f32_16x16x32_bf16 v[28:31], v[132:135], v[216:219], v[28:31]
	v_mfma_f32_16x16x32_bf16 v[24:27], v[140:143], v[216:219], v[24:27]
	v_mfma_f32_16x16x32_bf16 v[12:15], v[132:135], v[224:227], v[12:15]
	v_mfma_f32_16x16x32_bf16 v[8:11], v[140:143], v[224:227], v[8:11]
	v_mfma_f32_16x16x32_bf16 v[52:55], v[176:179], v[196:199], 0
	v_mfma_f32_16x16x32_bf16 v[48:51], v[188:191], v[196:199], 0
	v_mfma_f32_16x16x32_bf16 v[36:39], v[176:179], v[204:207], 0
	v_mfma_f32_16x16x32_bf16 v[32:35], v[188:191], v[204:207], 0
	v_mfma_f32_16x16x32_bf16 v[20:23], v[176:179], v[212:215], 0
	v_mfma_f32_16x16x32_bf16 v[16:19], v[188:191], v[212:215], 0
	v_mfma_f32_16x16x32_bf16 v[4:7], v[176:179], v[220:223], 0
	v_mfma_f32_16x16x32_bf16 v[0:3], v[188:191], v[220:223], 0
	v_mfma_f32_16x16x32_bf16 v[52:55], v[180:183], v[200:203], v[52:55]
	v_mfma_f32_16x16x32_bf16 v[48:51], v[192:195], v[200:203], v[48:51]
	v_mfma_f32_16x16x32_bf16 v[36:39], v[180:183], v[208:211], v[36:39]
	v_mfma_f32_16x16x32_bf16 v[32:35], v[192:195], v[208:211], v[32:35]
	v_mfma_f32_16x16x32_bf16 v[20:23], v[180:183], v[216:219], v[20:23]
	v_mfma_f32_16x16x32_bf16 v[16:19], v[192:195], v[216:219], v[16:19]
	v_mfma_f32_16x16x32_bf16 v[4:7], v[180:183], v[224:227], v[4:7]
	v_mfma_f32_16x16x32_bf16 v[0:3], v[192:195], v[224:227], v[0:3]
	s_barrier
	s_add_i32 s48, 0, 0x18000
	s_add_i32 s49, 0, 0x1c000
	v_add_u32_e32 v140, s48, v163
	v_add_u32_e32 v187, s49, v163
	ds_read_b128 v[128:131], v140
	ds_read_b128 v[132:135], v140 offset:1024
	ds_read_b128 v[136:139], v140 offset:2048
	ds_read_b128 v[140:143], v140 offset:3072
	ds_read_b128 v[176:179], v187
	ds_read_b128 v[180:183], v187 offset:1024
	ds_read_b128 v[188:191], v187 offset:2048
	ds_read_b128 v[192:195], v187 offset:3072
	s_add_u32 s28, s28, 0x80000
	s_addc_u32 s29, s29, 0
	s_mov_b32 m0, s34
	v_lshl_add_u64 v[232:233], s[28:29], 0, v[144:145]
	ds_read_b128 v[196:199], v175 offset:32768
	ds_read_b128 v[200:203], v175 offset:33792
	ds_read_b128 v[204:207], v175 offset:34816
	ds_read_b128 v[208:211], v175 offset:35840
	ds_read_b128 v[212:215], v175 offset:36864
	ds_read_b128 v[216:219], v175 offset:37888
	ds_read_b128 v[220:223], v175 offset:38912
	ds_read_b128 v[224:227], v175 offset:39936
	global_load_lds_dwordx4 v[232:233], off
	v_lshl_add_u64 v[232:233], s[28:29], 0, v[148:149]
	s_mov_b32 m0, s35
	s_nop 0
	global_load_lds_dwordx4 v[232:233], off
	s_waitcnt vmcnt(8)
	s_waitcnt lgkmcnt(0)
	s_barrier
	v_mfma_f32_16x16x32_bf16 v[124:127], v[128:131], v[196:199], v[124:127]
	v_mfma_f32_16x16x32_bf16 v[120:123], v[136:139], v[196:199], v[120:123]
	v_mfma_f32_16x16x32_bf16 v[108:111], v[128:131], v[204:207], v[108:111]
	v_mfma_f32_16x16x32_bf16 v[104:107], v[136:139], v[204:207], v[104:107]
	v_mfma_f32_16x16x32_bf16 v[92:95], v[128:131], v[212:215], v[92:95]
	v_mfma_f32_16x16x32_bf16 v[88:91], v[136:139], v[212:215], v[88:91]
	v_mfma_f32_16x16x32_bf16 v[76:79], v[128:131], v[220:223], v[76:79]
	v_mfma_f32_16x16x32_bf16 v[72:75], v[136:139], v[220:223], v[72:75]
	v_mfma_f32_16x16x32_bf16 v[124:127], v[132:135], v[200:203], v[124:127]
	v_mfma_f32_16x16x32_bf16 v[120:123], v[140:143], v[200:203], v[120:123]
	v_mfma_f32_16x16x32_bf16 v[108:111], v[132:135], v[208:211], v[108:111]
	v_mfma_f32_16x16x32_bf16 v[104:107], v[140:143], v[208:211], v[104:107]
	v_mfma_f32_16x16x32_bf16 v[92:95], v[132:135], v[216:219], v[92:95]
	v_mfma_f32_16x16x32_bf16 v[88:91], v[140:143], v[216:219], v[88:91]
	v_mfma_f32_16x16x32_bf16 v[76:79], v[132:135], v[224:227], v[76:79]
	v_mfma_f32_16x16x32_bf16 v[72:75], v[140:143], v[224:227], v[72:75]
	v_mfma_f32_16x16x32_bf16 v[116:119], v[176:179], v[196:199], v[116:119]
	v_mfma_f32_16x16x32_bf16 v[112:115], v[188:191], v[196:199], v[112:115]
	v_mfma_f32_16x16x32_bf16 v[100:103], v[176:179], v[204:207], v[100:103]
	v_mfma_f32_16x16x32_bf16 v[96:99], v[188:191], v[204:207], v[96:99]
	v_mfma_f32_16x16x32_bf16 v[84:87], v[176:179], v[212:215], v[84:87]
	v_mfma_f32_16x16x32_bf16 v[80:83], v[188:191], v[212:215], v[80:83]
	v_mfma_f32_16x16x32_bf16 v[68:71], v[176:179], v[220:223], v[68:71]
	v_mfma_f32_16x16x32_bf16 v[64:67], v[188:191], v[220:223], v[64:67]
	v_mfma_f32_16x16x32_bf16 v[116:119], v[180:183], v[200:203], v[116:119]
	v_mfma_f32_16x16x32_bf16 v[112:115], v[192:195], v[200:203], v[112:115]
	v_mfma_f32_16x16x32_bf16 v[100:103], v[180:183], v[208:211], v[100:103]
	v_mfma_f32_16x16x32_bf16 v[96:99], v[192:195], v[208:211], v[96:99]
	v_mfma_f32_16x16x32_bf16 v[84:87], v[180:183], v[216:219], v[84:87]
	v_mfma_f32_16x16x32_bf16 v[80:83], v[192:195], v[216:219], v[80:83]
	v_mfma_f32_16x16x32_bf16 v[68:71], v[180:183], v[224:227], v[68:71]
	v_mfma_f32_16x16x32_bf16 v[64:67], v[192:195], v[224:227], v[64:67]
	s_barrier
; #define PG8_STAGE(bufoff, gbase, voff) do { _Pragma("unroll") for (int _i = 0; _i < 2; ++_i) \
;         __builtin_amdgcn_global_load_lds((const unsigned*)((const char*)(gbase) + (voff)[_i]), (PG8_LAS unsigned*)(lds + (bufoff) + ldsw + _i * 8192), 16, 0, 0); } while (0)
; #define PG8_LDA(dst, b, h) do { _Pragma("unroll") for (int m = 0; m < 4; ++m) _Pragma("unroll") for (int k = 0; k < 2; ++k) dst[m][k] = *(const PG8_LAS bf16x8*)(lds + PG8_SA(b, h) + aoff + m * 2048 + k * 1024); } while (0)
; #define PG8_LDB(dst, b, h) do { _Pragma("unroll") for (int n = 0; n < 2; ++n) _Pragma("unroll") for (int k = 0; k < 2; ++k) dst[n][k] = *(const PG8_LAS bf16x8*)(lds + PG8_SB(b, h) + boff + n * 2048 + k * 1024); } while (0)
; #define PG8_MMA(ai, bj, At, Bt) do { __builtin_amdgcn_s_setprio(1); _Pragma("unroll") for (int m = 0; m < 4; ++m) _Pragma("unroll") for (int n = 0; n < 2; ++n) _Pragma("unroll") for (int k = 0; k < 2; ++k) \
;         acc[ai][bj][m][n] = __builtin_amdgcn_mfma_f32_16x16x32_bf16(Bt[n][k], At[m][k], acc[ai][bj][m][n], 0, 0, 0); __builtin_amdgcn_s_setprio(0); } while (0)
; #define PG8_WAIT_V(n) asm volatile("s_waitcnt vmcnt(" #n ")" ::: "memory")
; template <class Epi, class Sched, bool ALIGN_EPI = false, bool SP2 = false>
; __device__ __forceinline__ void gemm_phase(PG8_LAS unsigned char* lds, const Gemm g, const Sched& S, const Epi& E) {
;     ...
;             PG8_LDB(B0, 0, 0); PG8_LDB(B1, 0, 1); PG8_SCHED; PG8_LDA(At, 0, 0); PG8_STAGE(PG8_SA(1, 1), a1 + hstep, voffA);
;             PG8_WAIT_V(8); PG8_WAIT_L(0); PG8_BAR; PG8_MMA(0, 0, At, B0); PG8_MMA(0, 1, At, B1); PG8_BAR; PG8_SCHED;
;             PG8_LDA(At, 0, 1); PG8_STAGE(PG8_SB(0, 0), b2, voffB); PG8_STAGE(PG8_SB(0, 1), b2 + hstep, voffB); PG8_STAGE(PG8_SA(0, 0), a2, voffA);
;             PG8_WAIT_V(8); PG8_WAIT_L(0); PG8_BAR; PG8_MMA(1, 0, At, B0); PG8_MMA(1, 1, At, B1); PG8_BAR; PG8_SCHED;
;             PG8_LDB(B0, 1, 0); PG8_LDB(B1, 1, 1); PG8_SCHED; PG8_LDA(At, 1, 0); PG8_STAGE(PG8_SA(0, 1), a2 + hstep, voffA);
;             PG8_WAIT_V(8); PG8_WAIT_L(0); PG8_BAR; PG8_MMA(0, 0, At, B0); PG8_MMA(0, 1, At, B1); PG8_BAR; PG8_SCHED;
;             PG8_LDA(At, 1, 1); PG8_STAGE(PG8_SB(1, 0), b3, voffB); PG8_STAGE(PG8_SB(1, 1), b3 + hstep, voffB); PG8_STAGE(PG8_SA(1, 0), a3, voffA);
;             PG8_WAIT_V(8); PG8_WAIT_L(0); PG8_BAR; PG8_MMA(1, 0, At, B0); PG8_MMA(1, 1, At, B1); PG8_BAR; PG8_SCHED;
	s_add_i32 s28, s48, s31
	v_lshl_add_u64 v[160:161], v[160:161], 0, s[10:11]
	s_mov_b32 m0, s28
	ds_read_b128 v[196:199], v175 offset:49152
	ds_read_b128 v[200:203], v175 offset:50176
	ds_read_b128 v[204:207], v175 offset:51200
	ds_read_b128 v[208:211], v175 offset:52224
	ds_read_b128 v[212:215], v175 offset:53248
	ds_read_b128 v[216:219], v175 offset:54272
	ds_read_b128 v[220:223], v175 offset:55296
	ds_read_b128 v[224:227], v175 offset:56320
	global_load_lds_dwordx4 v[160:161], off
	s_add_i32 m0, s28, 0x2000
	s_add_u32 s26, s26, 0x80080
	v_lshl_add_u64 v[160:161], v[184:185], 0, s[10:11]
	s_addc_u32 s27, s27, 0
	s_add_i32 s28, s49, s31
	global_load_lds_dwordx4 v[160:161], off
	v_lshl_add_u64 v[160:161], s[26:27], 0, v[146:147]
	s_mov_b32 m0, s28
	s_nop 0
	global_load_lds_dwordx4 v[160:161], off
	v_lshl_add_u64 v[160:161], s[26:27], 0, v[150:151]
	s_add_i32 m0, s28, 0x2000
	s_nop 0
	global_load_lds_dwordx4 v[160:161], off
	v_lshl_add_u64 v[160:161], v[228:229], 0, s[10:11]
	s_mov_b32 m0, s38
	s_nop 0
	global_load_lds_dwordx4 v[160:161], off
	v_lshl_add_u64 v[160:161], v[230:231], 0, s[10:11]
	s_mov_b32 m0, s39
	s_nop 0
	global_load_lds_dwordx4 v[160:161], off
	s_waitcnt vmcnt(8)
	s_waitcnt lgkmcnt(0)
	s_barrier
	v_mfma_f32_16x16x32_bf16 v[60:63], v[128:131], v[196:199], v[60:63]
	v_mfma_f32_16x16x32_bf16 v[56:59], v[136:139], v[196:199], v[56:59]
	v_mfma_f32_16x16x32_bf16 v[44:47], v[128:131], v[204:207], v[44:47]
	v_mfma_f32_16x16x32_bf16 v[40:43], v[136:139], v[204:207], v[40:43]
	v_mfma_f32_16x16x32_bf16 v[28:31], v[128:131], v[212:215], v[28:31]
	v_mfma_f32_16x16x32_bf16 v[24:27], v[136:139], v[212:215], v[24:27]
	v_mfma_f32_16x16x32_bf16 v[12:15], v[128:131], v[220:223], v[12:15]
	v_mfma_f32_16x16x32_bf16 v[8:11], v[136:139], v[220:223], v[8:11]
	v_mfma_f32_16x16x32_bf16 v[60:63], v[132:135], v[200:203], v[60:63]
	v_mfma_f32_16x16x32_bf16 v[56:59], v[140:143], v[200:203], v[56:59]
	v_mfma_f32_16x16x32_bf16 v[44:47], v[132:135], v[208:211], v[44:47]
	v_mfma_f32_16x16x32_bf16 v[40:43], v[140:143], v[208:211], v[40:43]
	v_mfma_f32_16x16x32_bf16 v[28:31], v[132:135], v[216:219], v[28:31]
	v_mfma_f32_16x16x32_bf16 v[24:27], v[140:143], v[216:219], v[24:27]
	v_mfma_f32_16x16x32_bf16 v[12:15], v[132:135], v[224:227], v[12:15]
	v_mfma_f32_16x16x32_bf16 v[8:11], v[140:143], v[224:227], v[8:11]
	v_mfma_f32_16x16x32_bf16 v[52:55], v[176:179], v[196:199], v[52:55]
	v_mfma_f32_16x16x32_bf16 v[48:51], v[188:191], v[196:199], v[48:51]
	v_mfma_f32_16x16x32_bf16 v[36:39], v[176:179], v[204:207], v[36:39]
	v_mfma_f32_16x16x32_bf16 v[32:35], v[188:191], v[204:207], v[32:35]
	v_mfma_f32_16x16x32_bf16 v[20:23], v[176:179], v[212:215], v[20:23]
	v_mfma_f32_16x16x32_bf16 v[16:19], v[188:191], v[212:215], v[16:19]
	v_mfma_f32_16x16x32_bf16 v[4:7], v[176:179], v[220:223], v[4:7]
	v_mfma_f32_16x16x32_bf16 v[0:3], v[188:191], v[220:223], v[0:3]
	v_mfma_f32_16x16x32_bf16 v[52:55], v[180:183], v[200:203], v[52:55]
	v_mfma_f32_16x16x32_bf16 v[48:51], v[192:195], v[200:203], v[48:51]
	v_mfma_f32_16x16x32_bf16 v[36:39], v[180:183], v[208:211], v[36:39]
	v_mfma_f32_16x16x32_bf16 v[32:35], v[192:195], v[208:211], v[32:35]
	v_mfma_f32_16x16x32_bf16 v[20:23], v[180:183], v[216:219], v[20:23]
	v_mfma_f32_16x16x32_bf16 v[16:19], v[192:195], v[216:219], v[16:19]
	v_mfma_f32_16x16x32_bf16 v[4:7], v[180:183], v[224:227], v[4:7]
	v_mfma_f32_16x16x32_bf16 v[0:3], v[192:195], v[224:227], v[0:3]
	s_barrier
	s_add_i32 s47, s47, 2
	s_add_u32 s24, s24, 0x100
	s_addc_u32 s25, s25, 0
	s_add_u32 s45, s45, 0x100
	s_addc_u32 s46, s46, 0
	s_cmp_gt_u32 s47, 29
.LBB0_994:
	ds_read_b128 v[128:131], v173
	ds_read_b128 v[132:135], v173 offset:1024
	ds_read_b128 v[136:139], v173 offset:2048
	ds_read_b128 v[140:143], v173 offset:3072
	ds_read_b128 v[176:179], v174
	ds_read_b128 v[180:183], v174 offset:1024
	ds_read_b128 v[188:191], v174 offset:2048
	ds_read_b128 v[192:195], v174 offset:3072
	s_add_u32 s26, s24, 0xfff80080
	s_addc_u32 s27, s25, -1
	s_cmp_eq_u32 s47, 28
	s_cselect_b32 s29, s15, s27
	s_cselect_b32 s28, s43, s26
	s_cselect_b32 s27, s17, s46
	s_cselect_b32 s26, s44, s45
	v_lshl_add_u64 v[160:161], s[24:25], 0, v[152:153]
	s_add_i32 m0, s23, 0xc000
	ds_read_b128 v[196:199], v175
	ds_read_b128 v[200:203], v175 offset:1024
	ds_read_b128 v[204:207], v175 offset:2048
	ds_read_b128 v[208:211], v175 offset:3072
	ds_read_b128 v[212:215], v175 offset:4096
	ds_read_b128 v[216:219], v175 offset:5120
	ds_read_b128 v[220:223], v175 offset:6144
	ds_read_b128 v[224:227], v175 offset:7168
	global_load_lds_dwordx4 v[160:161], off
	v_lshl_add_u64 v[160:161], s[24:25], 0, v[154:155]
	s_add_i32 m0, s23, 0xe000
	s_nop 0
	global_load_lds_dwordx4 v[160:161], off
	s_waitcnt vmcnt(8)
	s_waitcnt lgkmcnt(0)
	s_barrier
; #define PG8_STAGE(bufoff, gbase, voff) do { _Pragma("unroll") for (int _i = 0; _i < 2; ++_i) \
;         __builtin_amdgcn_global_load_lds((const unsigned*)((const char*)(gbase) + (voff)[_i]), (PG8_LAS unsigned*)(lds + (bufoff) + ldsw + _i * 8192), 16, 0, 0); } while (0)
; #define PG8_LDA(dst, b, h) do { _Pragma("unroll") for (int m = 0; m < 4; ++m) _Pragma("unroll") for (int k = 0; k < 2; ++k) dst[m][k] = *(const PG8_LAS bf16x8*)(lds + PG8_SA(b, h) + aoff + m * 2048 + k * 1024); } while (0)
; #define PG8_MMA(ai, bj, At, Bt) do { __builtin_amdgcn_s_setprio(1); _Pragma("unroll") for (int m = 0; m < 4; ++m) _Pragma("unroll") for (int n = 0; n < 2; ++n) _Pragma("unroll") for (int k = 0; k < 2; ++k) \
;         acc[ai][bj][m][n] = __builtin_amdgcn_mfma_f32_16x16x32_bf16(Bt[n][k], At[m][k], acc[ai][bj][m][n], 0, 0, 0); __builtin_amdgcn_s_setprio(0); } while (0)
; #define PG8_WAIT_V(n) asm volatile("s_waitcnt vmcnt(" #n ")" ::: "memory")
; #define PG8_WAIT_L(n) asm volatile("s_waitcnt lgkmcnt(" #n ")" ::: "memory")
; #define PG8_BAR __builtin_amdgcn_s_barrier()
; #define PG8_SCHED __builtin_amdgcn_sched_barrier(0)
; template <class Epi, class Sched, bool ALIGN_EPI = false, bool SP2 = false>
; __device__ __forceinline__ void gemm_phase(PG8_LAS unsigned char* lds, const Gemm g, const Sched& S, const Epi& E) {
;     ...
;             PG8_WAIT_V(8); PG8_WAIT_L(0); PG8_BAR; PG8_MMA(0, 0, At, B0); PG8_MMA(0, 1, At, B1); PG8_BAR; PG8_SCHED;
;             PG8_LDA(At, 0, 1); PG8_STAGE(PG8_SB(0, 0), b2, voffB); PG8_STAGE(PG8_SB(0, 1), b2 + hstep, voffB); PG8_STAGE(PG8_SA(0, 0), a2, voffA);
;             PG8_WAIT_V(8); PG8_WAIT_L(0); PG8_BAR; PG8_MMA(1, 0, At, B0); PG8_MMA(1, 1, At, B1); PG8_BAR; PG8_SCHED;
	v_mfma_f32_16x16x32_bf16 v[124:127], v[128:131], v[196:199], v[124:127]
	v_mfma_f32_16x16x32_bf16 v[120:123], v[136:139], v[196:199], v[120:123]
	v_mfma_f32_16x16x32_bf16 v[108:111], v[128:131], v[204:207], v[108:111]
	v_mfma_f32_16x16x32_bf16 v[104:107], v[136:139], v[204:207], v[104:107]
	v_mfma_f32_16x16x32_bf16 v[92:95], v[128:131], v[212:215], v[92:95]
	v_mfma_f32_16x16x32_bf16 v[88:91], v[136:139], v[212:215], v[88:91]
	v_mfma_f32_16x16x32_bf16 v[76:79], v[128:131], v[220:223], v[76:79]
	v_mfma_f32_16x16x32_bf16 v[72:75], v[136:139], v[220:223], v[72:75]
	v_mfma_f32_16x16x32_bf16 v[124:127], v[132:135], v[200:203], v[124:127]
	v_mfma_f32_16x16x32_bf16 v[120:123], v[140:143], v[200:203], v[120:123]
	v_mfma_f32_16x16x32_bf16 v[108:111], v[132:135], v[208:211], v[108:111]
	v_mfma_f32_16x16x32_bf16 v[104:107], v[140:143], v[208:211], v[104:107]
	v_mfma_f32_16x16x32_bf16 v[92:95], v[132:135], v[216:219], v[92:95]
	v_mfma_f32_16x16x32_bf16 v[88:91], v[140:143], v[216:219], v[88:91]
	v_mfma_f32_16x16x32_bf16 v[76:79], v[132:135], v[224:227], v[76:79]
	v_mfma_f32_16x16x32_bf16 v[72:75], v[140:143], v[224:227], v[72:75]
	v_mfma_f32_16x16x32_bf16 v[116:119], v[176:179], v[196:199], v[116:119]
	v_mfma_f32_16x16x32_bf16 v[112:115], v[188:191], v[196:199], v[112:115]
	v_mfma_f32_16x16x32_bf16 v[100:103], v[176:179], v[204:207], v[100:103]
	v_mfma_f32_16x16x32_bf16 v[96:99], v[188:191], v[204:207], v[96:99]
	v_mfma_f32_16x16x32_bf16 v[84:87], v[176:179], v[212:215], v[84:87]
	v_mfma_f32_16x16x32_bf16 v[80:83], v[188:191], v[212:215], v[80:83]
	v_mfma_f32_16x16x32_bf16 v[68:71], v[176:179], v[220:223], v[68:71]
	v_mfma_f32_16x16x32_bf16 v[64:67], v[188:191], v[220:223], v[64:67]
	v_mfma_f32_16x16x32_bf16 v[116:119], v[180:183], v[200:203], v[116:119]
	v_mfma_f32_16x16x32_bf16 v[112:115], v[192:195], v[200:203], v[112:115]
	v_mfma_f32_16x16x32_bf16 v[100:103], v[180:183], v[208:211], v[100:103]
	v_mfma_f32_16x16x32_bf16 v[96:99], v[192:195], v[208:211], v[96:99]
	v_mfma_f32_16x16x32_bf16 v[84:87], v[180:183], v[216:219], v[84:87]
	v_mfma_f32_16x16x32_bf16 v[80:83], v[192:195], v[216:219], v[80:83]
	v_mfma_f32_16x16x32_bf16 v[68:71], v[180:183], v[224:227], v[68:71]
	v_mfma_f32_16x16x32_bf16 v[64:67], v[192:195], v[224:227], v[64:67]
	s_barrier
	s_add_i32 s48, s40, s31
	v_lshl_add_u64 v[160:161], s[26:27], 0, v[146:147]
	s_mov_b32 m0, s48
	ds_read_b128 v[196:199], v175 offset:16384
	ds_read_b128 v[200:203], v175 offset:17408
	ds_read_b128 v[204:207], v175 offset:18432
	ds_read_b128 v[208:211], v175 offset:19456
	ds_read_b128 v[212:215], v175 offset:20480
	ds_read_b128 v[216:219], v175 offset:21504
	ds_read_b128 v[220:223], v175 offset:22528
	ds_read_b128 v[224:227], v175 offset:23552
	global_load_lds_dwordx4 v[160:161], off
	s_add_i32 m0, s48, 0x2000
	s_add_u32 s48, s26, 0x80000
	v_lshl_add_u64 v[184:185], s[26:27], 0, v[150:151]
	s_addc_u32 s49, s27, 0
	s_add_i32 s50, s41, s31
	global_load_lds_dwordx4 v[184:185], off
	v_lshl_add_u64 v[228:229], s[48:49], 0, v[146:147]
	s_mov_b32 m0, s50
	v_lshl_add_u64 v[230:231], s[28:29], 0, v[148:149]
	global_load_lds_dwordx4 v[228:229], off
	v_lshl_add_u64 v[228:229], s[48:49], 0, v[150:151]
	s_add_i32 m0, s50, 0x2000
	s_nop 0
	global_load_lds_dwordx4 v[228:229], off
	v_lshl_add_u64 v[228:229], s[28:29], 0, v[144:145]
	s_mov_b32 m0, s23
	s_nop 0
	global_load_lds_dwordx4 v[228:229], off
	s_mov_b32 m0, s33
	s_nop 0
	global_load_lds_dwordx4 v[230:231], off
	s_waitcnt vmcnt(8)
	s_waitcnt lgkmcnt(0)
	s_barrier
	v_mfma_f32_16x16x32_bf16 v[60:63], v[128:131], v[196:199], v[60:63]
	v_mfma_f32_16x16x32_bf16 v[56:59], v[136:139], v[196:199], v[56:59]
	v_mfma_f32_16x16x32_bf16 v[44:47], v[128:131], v[204:207], v[44:47]
	v_mfma_f32_16x16x32_bf16 v[40:43], v[136:139], v[204:207], v[40:43]
	v_mfma_f32_16x16x32_bf16 v[28:31], v[128:131], v[212:215], v[28:31]
	v_mfma_f32_16x16x32_bf16 v[24:27], v[136:139], v[212:215], v[24:27]
	v_mfma_f32_16x16x32_bf16 v[12:15], v[128:131], v[220:223], v[12:15]
	v_mfma_f32_16x16x32_bf16 v[8:11], v[136:139], v[220:223], v[8:11]
	v_mfma_f32_16x16x32_bf16 v[60:63], v[132:135], v[200:203], v[60:63]
	v_mfma_f32_16x16x32_bf16 v[56:59], v[140:143], v[200:203], v[56:59]
	v_mfma_f32_16x16x32_bf16 v[44:47], v[132:135], v[208:211], v[44:47]
	v_mfma_f32_16x16x32_bf16 v[40:43], v[140:143], v[208:211], v[40:43]
	v_mfma_f32_16x16x32_bf16 v[28:31], v[132:135], v[216:219], v[28:31]
	v_mfma_f32_16x16x32_bf16 v[24:27], v[140:143], v[216:219], v[24:27]
	v_mfma_f32_16x16x32_bf16 v[12:15], v[132:135], v[224:227], v[12:15]
	v_mfma_f32_16x16x32_bf16 v[8:11], v[140:143], v[224:227], v[8:11]
	v_mfma_f32_16x16x32_bf16 v[52:55], v[176:179], v[196:199], v[52:55]
	v_mfma_f32_16x16x32_bf16 v[48:51], v[188:191], v[196:199], v[48:51]
	v_mfma_f32_16x16x32_bf16 v[36:39], v[176:179], v[204:207], v[36:39]
	v_mfma_f32_16x16x32_bf16 v[32:35], v[188:191], v[204:207], v[32:35]
	v_mfma_f32_16x16x32_bf16 v[20:23], v[176:179], v[212:215], v[20:23]
	v_mfma_f32_16x16x32_bf16 v[16:19], v[188:191], v[212:215], v[16:19]
	v_mfma_f32_16x16x32_bf16 v[4:7], v[176:179], v[220:223], v[4:7]
	v_mfma_f32_16x16x32_bf16 v[0:3], v[188:191], v[220:223], v[0:3]
	v_mfma_f32_16x16x32_bf16 v[52:55], v[180:183], v[200:203], v[52:55]
	v_mfma_f32_16x16x32_bf16 v[48:51], v[192:195], v[200:203], v[48:51]
	v_mfma_f32_16x16x32_bf16 v[36:39], v[180:183], v[208:211], v[36:39]
	v_mfma_f32_16x16x32_bf16 v[32:35], v[192:195], v[208:211], v[32:35]
	v_mfma_f32_16x16x32_bf16 v[20:23], v[180:183], v[216:219], v[20:23]
	v_mfma_f32_16x16x32_bf16 v[16:19], v[192:195], v[216:219], v[16:19]
	v_mfma_f32_16x16x32_bf16 v[4:7], v[180:183], v[224:227], v[4:7]
	v_mfma_f32_16x16x32_bf16 v[0:3], v[192:195], v[224:227], v[0:3]
	s_barrier
; #define PG8_STAGE(bufoff, gbase, voff) do { _Pragma("unroll") for (int _i = 0; _i < 2; ++_i) \
;         __builtin_amdgcn_global_load_lds((const unsigned*)((const char*)(gbase) + (voff)[_i]), (PG8_LAS unsigned*)(lds + (bufoff) + ldsw + _i * 8192), 16, 0, 0); } while (0)
; #define PG8_LDA(dst, b, h) do { _Pragma("unroll") for (int m = 0; m < 4; ++m) _Pragma("unroll") for (int k = 0; k < 2; ++k) dst[m][k] = *(const PG8_LAS bf16x8*)(lds + PG8_SA(b, h) + aoff + m * 2048 + k * 1024); } while (0)
; #define PG8_LDB(dst, b, h) do { _Pragma("unroll") for (int n = 0; n < 2; ++n) _Pragma("unroll") for (int k = 0; k < 2; ++k) dst[n][k] = *(const PG8_LAS bf16x8*)(lds + PG8_SB(b, h) + boff + n * 2048 + k * 1024); } while (0)
; #define PG8_MMA(ai, bj, At, Bt) do { __builtin_amdgcn_s_setprio(1); _Pragma("unroll") for (int m = 0; m < 4; ++m) _Pragma("unroll") for (int n = 0; n < 2; ++n) _Pragma("unroll") for (int k = 0; k < 2; ++k) \
;         acc[ai][bj][m][n] = __builtin_amdgcn_mfma_f32_16x16x32_bf16(Bt[n][k], At[m][k], acc[ai][bj][m][n], 0, 0, 0); __builtin_amdgcn_s_setprio(0); } while (0)
; #define PG8_WAIT_V(n) asm volatile("s_waitcnt vmcnt(" #n ")" ::: "memory")
; #define PG8_WAIT_L(n) asm volatile("s_waitcnt lgkmcnt(" #n ")" ::: "memory")
; #define PG8_BAR __builtin_amdgcn_s_barrier()
; #define PG8_SCHED __builtin_amdgcn_sched_barrier(0)
; template <class Epi, class Sched, bool ALIGN_EPI = false, bool SP2 = false>
; __device__ __forceinline__ void gemm_phase(PG8_LAS unsigned char* lds, const Gemm g, const Sched& S, const Epi& E) {
;     ...
;             PG8_LDB(B0, 1, 0); PG8_LDB(B1, 1, 1); PG8_SCHED; PG8_LDA(At, 1, 0); PG8_STAGE(PG8_SA(0, 1), a2 + hstep, voffA);
;             PG8_WAIT_V(8); PG8_WAIT_L(0); PG8_BAR; PG8_MMA(0, 0, At, B0); PG8_MMA(0, 1, At, B1); PG8_BAR; PG8_SCHED;
	s_add_i32 s48, 0, 0x18000
	s_add_i32 s49, 0, 0x1c000
	v_add_u32_e32 v140, s48, v163
	v_add_u32_e32 v187, s49, v163
	ds_read_b128 v[128:131], v140
	ds_read_b128 v[132:135], v140 offset:1024
	ds_read_b128 v[136:139], v140 offset:2048
	ds_read_b128 v[140:143], v140 offset:3072
	ds_read_b128 v[176:179], v187
	ds_read_b128 v[180:183], v187 offset:1024
	ds_read_b128 v[188:191], v187 offset:2048
	ds_read_b128 v[192:195], v187 offset:3072
	s_add_u32 s28, s28, 0x80000
	s_addc_u32 s29, s29, 0
	s_mov_b32 m0, s34
	v_lshl_add_u64 v[232:233], s[28:29], 0, v[144:145]
	ds_read_b128 v[196:199], v175 offset:32768
	ds_read_b128 v[200:203], v175 offset:33792
	ds_read_b128 v[204:207], v175 offset:34816
	ds_read_b128 v[208:211], v175 offset:35840
	ds_read_b128 v[212:215], v175 offset:36864
	ds_read_b128 v[216:219], v175 offset:37888
	ds_read_b128 v[220:223], v175 offset:38912
	ds_read_b128 v[224:227], v175 offset:39936
	global_load_lds_dwordx4 v[232:233], off
	v_lshl_add_u64 v[232:233], s[28:29], 0, v[148:149]
	s_mov_b32 m0, s35
	s_nop 0
	global_load_lds_dwordx4 v[232:233], off
	s_waitcnt vmcnt(8)
	s_waitcnt lgkmcnt(0)
	s_barrier
	v_mfma_f32_16x16x32_bf16 v[124:127], v[128:131], v[196:199], v[124:127]
	v_mfma_f32_16x16x32_bf16 v[120:123], v[136:139], v[196:199], v[120:123]
	v_mfma_f32_16x16x32_bf16 v[108:111], v[128:131], v[204:207], v[108:111]
	v_mfma_f32_16x16x32_bf16 v[104:107], v[136:139], v[204:207], v[104:107]
	v_mfma_f32_16x16x32_bf16 v[92:95], v[128:131], v[212:215], v[92:95]
	v_mfma_f32_16x16x32_bf16 v[88:91], v[136:139], v[212:215], v[88:91]
	v_mfma_f32_16x16x32_bf16 v[76:79], v[128:131], v[220:223], v[76:79]
	v_mfma_f32_16x16x32_bf16 v[72:75], v[136:139], v[220:223], v[72:75]
	v_mfma_f32_16x16x32_bf16 v[124:127], v[132:135], v[200:203], v[124:127]
	v_mfma_f32_16x16x32_bf16 v[120:123], v[140:143], v[200:203], v[120:123]
	v_mfma_f32_16x16x32_bf16 v[108:111], v[132:135], v[208:211], v[108:111]
	v_mfma_f32_16x16x32_bf16 v[104:107], v[140:143], v[208:211], v[104:107]
	v_mfma_f32_16x16x32_bf16 v[92:95], v[132:135], v[216:219], v[92:95]
	v_mfma_f32_16x16x32_bf16 v[88:91], v[140:143], v[216:219], v[88:91]
	v_mfma_f32_16x16x32_bf16 v[76:79], v[132:135], v[224:227], v[76:79]
	v_mfma_f32_16x16x32_bf16 v[72:75], v[140:143], v[224:227], v[72:75]
	v_mfma_f32_16x16x32_bf16 v[116:119], v[176:179], v[196:199], v[116:119]
	v_mfma_f32_16x16x32_bf16 v[112:115], v[188:191], v[196:199], v[112:115]
	v_mfma_f32_16x16x32_bf16 v[100:103], v[176:179], v[204:207], v[100:103]
	v_mfma_f32_16x16x32_bf16 v[96:99], v[188:191], v[204:207], v[96:99]
	v_mfma_f32_16x16x32_bf16 v[84:87], v[176:179], v[212:215], v[84:87]
	v_mfma_f32_16x16x32_bf16 v[80:83], v[188:191], v[212:215], v[80:83]
	v_mfma_f32_16x16x32_bf16 v[68:71], v[176:179], v[220:223], v[68:71]
	v_mfma_f32_16x16x32_bf16 v[64:67], v[188:191], v[220:223], v[64:67]
	v_mfma_f32_16x16x32_bf16 v[116:119], v[180:183], v[200:203], v[116:119]
	v_mfma_f32_16x16x32_bf16 v[112:115], v[192:195], v[200:203], v[112:115]
	v_mfma_f32_16x16x32_bf16 v[100:103], v[180:183], v[208:211], v[100:103]
	v_mfma_f32_16x16x32_bf16 v[96:99], v[192:195], v[208:211], v[96:99]
	v_mfma_f32_16x16x32_bf16 v[84:87], v[180:183], v[216:219], v[84:87]
	v_mfma_f32_16x16x32_bf16 v[80:83], v[192:195], v[216:219], v[80:83]
	v_mfma_f32_16x16x32_bf16 v[68:71], v[180:183], v[224:227], v[68:71]
	v_mfma_f32_16x16x32_bf16 v[64:67], v[192:195], v[224:227], v[64:67]
	s_barrier
; #define PG8_STAGE(bufoff, gbase, voff) do { _Pragma("unroll") for (int _i = 0; _i < 2; ++_i) \
;         __builtin_amdgcn_global_load_lds((const unsigned*)((const char*)(gbase) + (voff)[_i]), (PG8_LAS unsigned*)(lds + (bufoff) + ldsw + _i * 8192), 16, 0, 0); } while (0)
; #define PG8_LDA(dst, b, h) do { _Pragma("unroll") for (int m = 0; m < 4; ++m) _Pragma("unroll") for (int k = 0; k < 2; ++k) dst[m][k] = *(const PG8_LAS bf16x8*)(lds + PG8_SA(b, h) + aoff + m * 2048 + k * 1024); } while (0)
; #define PG8_MMA(ai, bj, At, Bt) do { __builtin_amdgcn_s_setprio(1); _Pragma("unroll") for (int m = 0; m < 4; ++m) _Pragma("unroll") for (int n = 0; n < 2; ++n) _Pragma("unroll") for (int k = 0; k < 2; ++k) \
;         acc[ai][bj][m][n] = __builtin_amdgcn_mfma_f32_16x16x32_bf16(Bt[n][k], At[m][k], acc[ai][bj][m][n], 0, 0, 0); __builtin_amdgcn_s_setprio(0); } while (0)
; #define PG8_WAIT_V(n) asm volatile("s_waitcnt vmcnt(" #n ")" ::: "memory")
; #define PG8_WAIT_L(n) asm volatile("s_waitcnt lgkmcnt(" #n ")" ::: "memory")
; #define PG8_BAR __builtin_amdgcn_s_barrier()
; #define PG8_SCHED __builtin_amdgcn_sched_barrier(0)
; template <class Epi, class Sched, bool ALIGN_EPI = false, bool SP2 = false>
; __device__ __forceinline__ void gemm_phase(PG8_LAS unsigned char* lds, const Gemm g, const Sched& S, const Epi& E) {
;     ...
;             PG8_LDA(At, 1, 1); PG8_STAGE(PG8_SB(1, 0), b3, voffB); PG8_STAGE(PG8_SB(1, 1), b3 + hstep, voffB); PG8_STAGE(PG8_SA(1, 0), a3, voffA);
;             PG8_WAIT_V(8); PG8_WAIT_L(0); PG8_BAR; PG8_MMA(1, 0, At, B0); PG8_MMA(1, 1, At, B1); PG8_BAR; PG8_SCHED;
;     ...
;         if constexpr (ALIGN_EPI) { if (wr == 0) PG8_BAR; }
	s_add_i32 s28, s48, s31
	v_lshl_add_u64 v[160:161], v[160:161], 0, s[10:11]
	s_mov_b32 m0, s28
	ds_read_b128 v[196:199], v175 offset:49152
	ds_read_b128 v[200:203], v175 offset:50176
	ds_read_b128 v[204:207], v175 offset:51200
	ds_read_b128 v[208:211], v175 offset:52224
	ds_read_b128 v[212:215], v175 offset:53248
	ds_read_b128 v[216:219], v175 offset:54272
	ds_read_b128 v[220:223], v175 offset:55296
	ds_read_b128 v[224:227], v175 offset:56320
	global_load_lds_dwordx4 v[160:161], off
	s_add_i32 m0, s28, 0x2000
	s_add_u32 s26, s26, 0x80080
	v_lshl_add_u64 v[160:161], v[184:185], 0, s[10:11]
	s_addc_u32 s27, s27, 0
	s_add_i32 s28, s49, s31
	global_load_lds_dwordx4 v[160:161], off
	v_lshl_add_u64 v[160:161], s[26:27], 0, v[146:147]
	s_mov_b32 m0, s28
	s_nop 0
	global_load_lds_dwordx4 v[160:161], off
	v_lshl_add_u64 v[160:161], s[26:27], 0, v[150:151]
	s_add_i32 m0, s28, 0x2000
	s_nop 0
	global_load_lds_dwordx4 v[160:161], off
	v_lshl_add_u64 v[160:161], v[228:229], 0, s[10:11]
	s_mov_b32 m0, s38
	s_nop 0
	global_load_lds_dwordx4 v[160:161], off
	v_lshl_add_u64 v[160:161], v[230:231], 0, s[10:11]
	s_mov_b32 m0, s39
	s_nop 0
	global_load_lds_dwordx4 v[160:161], off
	s_waitcnt vmcnt(8)
	s_waitcnt lgkmcnt(0)
	s_barrier
	v_mfma_f32_16x16x32_bf16 v[60:63], v[128:131], v[196:199], v[60:63]
	v_mfma_f32_16x16x32_bf16 v[56:59], v[136:139], v[196:199], v[56:59]
	v_mfma_f32_16x16x32_bf16 v[44:47], v[128:131], v[204:207], v[44:47]
	v_mfma_f32_16x16x32_bf16 v[40:43], v[136:139], v[204:207], v[40:43]
	v_mfma_f32_16x16x32_bf16 v[28:31], v[128:131], v[212:215], v[28:31]
	v_mfma_f32_16x16x32_bf16 v[24:27], v[136:139], v[212:215], v[24:27]
	v_mfma_f32_16x16x32_bf16 v[12:15], v[128:131], v[220:223], v[12:15]
	v_mfma_f32_16x16x32_bf16 v[8:11], v[136:139], v[220:223], v[8:11]
	v_mfma_f32_16x16x32_bf16 v[60:63], v[132:135], v[200:203], v[60:63]
	v_mfma_f32_16x16x32_bf16 v[56:59], v[140:143], v[200:203], v[56:59]
	v_mfma_f32_16x16x32_bf16 v[44:47], v[132:135], v[208:211], v[44:47]
	v_mfma_f32_16x16x32_bf16 v[40:43], v[140:143], v[208:211], v[40:43]
	v_mfma_f32_16x16x32_bf16 v[28:31], v[132:135], v[216:219], v[28:31]
	v_mfma_f32_16x16x32_bf16 v[24:27], v[140:143], v[216:219], v[24:27]
	v_mfma_f32_16x16x32_bf16 v[12:15], v[132:135], v[224:227], v[12:15]
	v_mfma_f32_16x16x32_bf16 v[8:11], v[140:143], v[224:227], v[8:11]
	v_mfma_f32_16x16x32_bf16 v[52:55], v[176:179], v[196:199], v[52:55]
	v_mfma_f32_16x16x32_bf16 v[48:51], v[188:191], v[196:199], v[48:51]
	v_mfma_f32_16x16x32_bf16 v[36:39], v[176:179], v[204:207], v[36:39]
	v_mfma_f32_16x16x32_bf16 v[32:35], v[188:191], v[204:207], v[32:35]
	v_mfma_f32_16x16x32_bf16 v[20:23], v[176:179], v[212:215], v[20:23]
	v_mfma_f32_16x16x32_bf16 v[16:19], v[188:191], v[212:215], v[16:19]
	v_mfma_f32_16x16x32_bf16 v[4:7], v[176:179], v[220:223], v[4:7]
	v_mfma_f32_16x16x32_bf16 v[0:3], v[188:191], v[220:223], v[0:3]
	v_mfma_f32_16x16x32_bf16 v[52:55], v[180:183], v[200:203], v[52:55]
	v_mfma_f32_16x16x32_bf16 v[48:51], v[192:195], v[200:203], v[48:51]
	v_mfma_f32_16x16x32_bf16 v[36:39], v[180:183], v[208:211], v[36:39]
	v_mfma_f32_16x16x32_bf16 v[32:35], v[192:195], v[208:211], v[32:35]
	v_mfma_f32_16x16x32_bf16 v[20:23], v[180:183], v[216:219], v[20:23]
	v_mfma_f32_16x16x32_bf16 v[16:19], v[192:195], v[216:219], v[16:19]
	v_mfma_f32_16x16x32_bf16 v[4:7], v[180:183], v[224:227], v[4:7]
	v_mfma_f32_16x16x32_bf16 v[0:3], v[192:195], v[224:227], v[0:3]
	s_barrier
	s_add_i32 s47, s47, 2
	s_add_u32 s24, s24, 0x100
	s_addc_u32 s25, s25, 0
	s_add_u32 s45, s45, 0x100
	s_addc_u32 s46, s46, 0
	s_cmp_gt_u32 s47, 29
	s_cbranch_scc0 .LBB0_994
	s_setprio 0
	s_and_b64 vcc, exec, s[12:13]
	s_cbranch_vccz .LBB0_997
	s_barrier

;     __device__ __forceinline__ bool next(int i, Unit& u) const { if (!base.next(i >> 1, u)) return false; if (i & 1) { u.pm += 64; u.pn += 8; } return true; }
; #define PG8_STAGE(bufoff, gbase, voff) do { _Pragma("unroll") for (int _i = 0; _i < 2; ++_i) \
;         __builtin_amdgcn_global_load_lds((const unsigned*)((const char*)(gbase) + (voff)[_i]), (PG8_LAS unsigned*)(lds + (bufoff) + ldsw + _i * 8192), 16, 0, 0); } while (0)
; #define PG8_LDA(dst, b, h) do { _Pragma("unroll") for (int m = 0; m < 4; ++m) _Pragma("unroll") for (int k = 0; k < 2; ++k) dst[m][k] = *(const PG8_LAS bf16x8*)(lds + PG8_SA(b, h) + aoff + m * 2048 + k * 1024); } while (0)
; #define PG8_LDB(dst, b, h) do { _Pragma("unroll") for (int n = 0; n < 2; ++n) _Pragma("unroll") for (int k = 0; k < 2; ++k) dst[n][k] = *(const PG8_LAS bf16x8*)(lds + PG8_SB(b, h) + boff + n * 2048 + k * 1024); } while (0)
; #define PG8_WAIT_V(n) asm volatile("s_waitcnt vmcnt(" #n ")" ::: "memory")
; #define PG8_BAR __builtin_amdgcn_s_barrier()
; template <class Epi, class Sched, bool ALIGN_EPI = false, bool SP2 = false>
; __device__ __forceinline__ void gemm_phase(PG8_LAS unsigned char* lds, const Gemm g, const Sched& S, const Epi& E) {
;     ...
;         const bool has_next = S.next(ui + 1, nxt);
;         const char* nA = has_next ? (const char*)g.A + (size_t)nxt.pm * tstep : cA; const char* nB = has_next ? (const char*)g.Bt + (size_t)nxt.pn * tstep : cB;
;         for (int t = 0; t < nt; t += 2) {
;             const bool last = (t == nt - 2);
;             const char* a1 = cA + (size_t)(t + 1) * kstep;
;             const char* a2 = last ? nA : cA + (size_t)(t + 2) * kstep; const char* b2 = last ? nB : cB + (size_t)(t + 2) * kstep;
;             const char* a3 = a2 + kstep; const char* b3 = b2 + kstep;
;             if (last && has_next) S.a_ready(nxt);
;             if constexpr (SP2) {
;             PG8_LDB(B0, 0, 0); PG8_LDB(B1, 0, 1); PG8_SCHED; PG8_LDA(At, 0, 0); PG8_STAGE(PG8_SA(1, 1), a1 + hstep, voffA);
;             PG8_WAIT_V(8); PG8_WAIT_L(0); PG8_BAR; PG8_MMA(0, 0, At, B0); PG8_MMA(0, 1, At, B1); PG8_BAR; PG8_SCHED;
;             PG8_LDA(At, 0, 1); PG8_STAGE(PG8_SB(0, 0), b2, voffB); PG8_STAGE(PG8_SB(0, 1), b2 + hstep, voffB); PG8_STAGE(PG8_SA(0, 0), a2, voffA);
;             PG8_WAIT_V(8); PG8_WAIT_L(0); PG8_BAR; PG8_MMA(1, 0, At, B0); PG8_MMA(1, 1, At, B1); PG8_BAR; PG8_SCHED;
.LBB0_1070:
	s_ashr_i32 s19, s18, 31
	s_lshl_b64 s[20:21], s[18:19], 22
	s_add_u32 s20, s72, s20
	s_addc_u32 s21, s73, s21
	s_and_b64 s[22:23], s[0:1], exec
	s_cselect_b32 s19, s21, s27
	s_cselect_b32 s51, s20, s26
	s_ashr_i32 s17, s16, 31
	s_lshl_b64 s[22:23], s[16:17], 22
	v_readlane_b32 s30, v236, 54
	v_readlane_b32 s31, v236, 55
	s_add_u32 s22, s30, s22
	s_addc_u32 s23, s31, s23
	s_and_b64 s[30:31], s[0:1], exec
	s_cselect_b32 s17, s23, s29
	s_cselect_b32 s52, s22, s28
	s_add_u32 s26, s26, 0x200080
	s_addc_u32 s27, s27, 0
	s_add_u32 s53, s28, 0x100
	s_addc_u32 s54, s29, 0
	s_mov_b32 s55, -2
	s_cmp_eq_u64 s[6:7], 0
	s_cbranch_scc0 .Lprio_skip_1071
	s_setprio 1
.Lprio_skip_1071:
	ds_read_b128 v[64:67], v165
	ds_read_b128 v[108:111], v165 offset:1024
	ds_read_b128 v[116:119], v165 offset:2048
	ds_read_b128 v[128:131], v165 offset:3072
	ds_read_b128 v[156:159], v166
	ds_read_b128 v[168:171], v166 offset:1024
	ds_read_b128 v[172:175], v166 offset:2048
	ds_read_b128 v[176:179], v166 offset:3072
	s_add_u32 s28, s26, 0xffe00080
	s_addc_u32 s29, s27, -1
	s_cmpk_eq_i32 s55, 0x7c
	s_cselect_b32 s31, s19, s29
	s_cselect_b32 s30, s51, s28
	s_cselect_b32 s29, s17, s54
	s_cselect_b32 s28, s52, s53
	v_lshl_add_u64 v[160:161], s[26:27], 0, v[148:149]
	s_add_i32 m0, s35, 0xc000
	ds_read_b128 v[180:183], v167
	ds_read_b128 v[184:187], v167 offset:1024
	ds_read_b128 v[188:191], v167 offset:2048
	ds_read_b128 v[192:195], v167 offset:3072
	ds_read_b128 v[196:199], v167 offset:4096
	ds_read_b128 v[200:203], v167 offset:5120
	ds_read_b128 v[204:207], v167 offset:6144
	ds_read_b128 v[208:211], v167 offset:7168
	global_load_lds_dwordx4 v[160:161], off
	v_lshl_add_u64 v[160:161], s[26:27], 0, v[150:151]
	s_add_i32 m0, s35, 0xe000
	s_nop 0
	global_load_lds_dwordx4 v[160:161], off
	s_waitcnt vmcnt(8)
	s_waitcnt lgkmcnt(0)
	s_barrier
	v_mfma_f32_16x16x32_bf16 v[140:143], v[64:67], v[180:183], 0
	v_mfma_f32_16x16x32_bf16 v[136:139], v[116:119], v[180:183], 0
	v_mfma_f32_16x16x32_bf16 v[120:123], v[64:67], v[188:191], 0
	v_mfma_f32_16x16x32_bf16 v[112:115], v[116:119], v[188:191], 0
	v_mfma_f32_16x16x32_bf16 v[96:99], v[64:67], v[196:199], 0
	v_mfma_f32_16x16x32_bf16 v[92:95], v[116:119], v[196:199], 0
	v_mfma_f32_16x16x32_bf16 v[80:83], v[64:67], v[204:207], 0
	v_mfma_f32_16x16x32_bf16 v[76:79], v[116:119], v[204:207], 0
	v_mfma_f32_16x16x32_bf16 v[140:143], v[108:111], v[184:187], v[140:143]
	v_mfma_f32_16x16x32_bf16 v[136:139], v[128:131], v[184:187], v[136:139]
	v_mfma_f32_16x16x32_bf16 v[120:123], v[108:111], v[192:195], v[120:123]
	v_mfma_f32_16x16x32_bf16 v[112:115], v[128:131], v[192:195], v[112:115]
	v_mfma_f32_16x16x32_bf16 v[96:99], v[108:111], v[200:203], v[96:99]
	v_mfma_f32_16x16x32_bf16 v[92:95], v[128:131], v[200:203], v[92:95]
	v_mfma_f32_16x16x32_bf16 v[80:83], v[108:111], v[208:211], v[80:83]
	v_mfma_f32_16x16x32_bf16 v[76:79], v[128:131], v[208:211], v[76:79]
	v_mfma_f32_16x16x32_bf16 v[132:135], v[156:159], v[180:183], 0
	v_mfma_f32_16x16x32_bf16 v[124:127], v[172:175], v[180:183], 0
	v_mfma_f32_16x16x32_bf16 v[104:107], v[156:159], v[188:191], 0
	v_mfma_f32_16x16x32_bf16 v[100:103], v[172:175], v[188:191], 0
	v_mfma_f32_16x16x32_bf16 v[88:91], v[156:159], v[196:199], 0
	v_mfma_f32_16x16x32_bf16 v[84:87], v[172:175], v[196:199], 0
	v_mfma_f32_16x16x32_bf16 v[72:75], v[156:159], v[204:207], 0
	v_mfma_f32_16x16x32_bf16 v[68:71], v[172:175], v[204:207], 0
	v_mfma_f32_16x16x32_bf16 v[132:135], v[168:171], v[184:187], v[132:135]
	v_mfma_f32_16x16x32_bf16 v[124:127], v[176:179], v[184:187], v[124:127]
	v_mfma_f32_16x16x32_bf16 v[104:107], v[168:171], v[192:195], v[104:107]
	v_mfma_f32_16x16x32_bf16 v[100:103], v[176:179], v[192:195], v[100:103]
	v_mfma_f32_16x16x32_bf16 v[88:91], v[168:171], v[200:203], v[88:91]
	v_mfma_f32_16x16x32_bf16 v[84:87], v[176:179], v[200:203], v[84:87]
	v_mfma_f32_16x16x32_bf16 v[72:75], v[168:171], v[208:211], v[72:75]
	v_mfma_f32_16x16x32_bf16 v[68:71], v[176:179], v[208:211], v[68:71]
	s_barrier
	s_add_i32 s56, s45, s34
	v_lshl_add_u64 v[160:161], s[28:29], 0, v[144:145]
	s_mov_b32 m0, s56
	ds_read_b128 v[180:183], v167 offset:16384
	ds_read_b128 v[184:187], v167 offset:17408
	ds_read_b128 v[188:191], v167 offset:18432
	ds_read_b128 v[192:195], v167 offset:19456
	ds_read_b128 v[196:199], v167 offset:20480
	ds_read_b128 v[200:203], v167 offset:21504
	ds_read_b128 v[204:207], v167 offset:22528
	ds_read_b128 v[208:211], v167 offset:23552
	global_load_lds_dwordx4 v[160:161], off
	s_add_i32 m0, s56, 0x2000
	s_add_u32 s56, s28, 0x200000
	v_lshl_add_u64 v[212:213], s[28:29], 0, v[146:147]
	s_addc_u32 s57, s29, 0
	s_add_i32 s58, s46, s34
	global_load_lds_dwordx4 v[212:213], off
	v_lshl_add_u64 v[214:215], s[56:57], 0, v[144:145]
	s_mov_b32 m0, s58
	v_lshl_add_u64 v[216:217], s[30:31], 0, v[146:147]
	global_load_lds_dwordx4 v[214:215], off
	v_lshl_add_u64 v[214:215], s[56:57], 0, v[146:147]
	s_add_i32 m0, s58, 0x2000
	s_nop 0
	global_load_lds_dwordx4 v[214:215], off
	v_lshl_add_u64 v[214:215], s[30:31], 0, v[144:145]
	s_mov_b32 m0, s35
	s_nop 0
	global_load_lds_dwordx4 v[214:215], off
	s_mov_b32 m0, s36
	s_nop 0
	global_load_lds_dwordx4 v[216:217], off
	s_waitcnt vmcnt(8)
	s_waitcnt lgkmcnt(0)
	s_barrier
; #define PG8_STAGE(bufoff, gbase, voff) do { _Pragma("unroll") for (int _i = 0; _i < 2; ++_i) \
;         __builtin_amdgcn_global_load_lds((const unsigned*)((const char*)(gbase) + (voff)[_i]), (PG8_LAS unsigned*)(lds + (bufoff) + ldsw + _i * 8192), 16, 0, 0); } while (0)
; #define PG8_LDA(dst, b, h) do { _Pragma("unroll") for (int m = 0; m < 4; ++m) _Pragma("unroll") for (int k = 0; k < 2; ++k) dst[m][k] = *(const PG8_LAS bf16x8*)(lds + PG8_SA(b, h) + aoff + m * 2048 + k * 1024); } while (0)
; #define PG8_LDB(dst, b, h) do { _Pragma("unroll") for (int n = 0; n < 2; ++n) _Pragma("unroll") for (int k = 0; k < 2; ++k) dst[n][k] = *(const PG8_LAS bf16x8*)(lds + PG8_SB(b, h) + boff + n * 2048 + k * 1024); } while (0)
; #define PG8_MMA(ai, bj, At, Bt) do { __builtin_amdgcn_s_setprio(1); _Pragma("unroll") for (int m = 0; m < 4; ++m) _Pragma("unroll") for (int n = 0; n < 2; ++n) _Pragma("unroll") for (int k = 0; k < 2; ++k) \
;         acc[ai][bj][m][n] = __builtin_amdgcn_mfma_f32_16x16x32_bf16(Bt[n][k], At[m][k], acc[ai][bj][m][n], 0, 0, 0); __builtin_amdgcn_s_setprio(0); } while (0)
; #define PG8_WAIT_V(n) asm volatile("s_waitcnt vmcnt(" #n ")" ::: "memory")
; #define PG8_WAIT_L(n) asm volatile("s_waitcnt lgkmcnt(" #n ")" ::: "memory")
; #define PG8_BAR __builtin_amdgcn_s_barrier()
; #define PG8_SCHED __builtin_amdgcn_sched_barrier(0)
; template <class Epi, class Sched, bool ALIGN_EPI = false, bool SP2 = false>
; __device__ __forceinline__ void gemm_phase(PG8_LAS unsigned char* lds, const Gemm g, const Sched& S, const Epi& E) {
;     ...
;             PG8_WAIT_V(8); PG8_WAIT_L(0); PG8_BAR; PG8_MMA(1, 0, At, B0); PG8_MMA(1, 1, At, B1); PG8_BAR; PG8_SCHED;
;             PG8_LDB(B0, 1, 0); PG8_LDB(B1, 1, 1); PG8_SCHED; PG8_LDA(At, 1, 0); PG8_STAGE(PG8_SA(0, 1), a2 + hstep, voffA);
;             PG8_WAIT_V(8); PG8_WAIT_L(0); PG8_BAR; PG8_MMA(0, 0, At, B0); PG8_MMA(0, 1, At, B1); PG8_BAR; PG8_SCHED;
	v_mfma_f32_16x16x32_bf16 v[60:63], v[64:67], v[180:183], 0
	v_mfma_f32_16x16x32_bf16 v[56:59], v[116:119], v[180:183], 0
	v_mfma_f32_16x16x32_bf16 v[44:47], v[64:67], v[188:191], 0
	v_mfma_f32_16x16x32_bf16 v[40:43], v[116:119], v[188:191], 0
	v_mfma_f32_16x16x32_bf16 v[28:31], v[64:67], v[196:199], 0
	v_mfma_f32_16x16x32_bf16 v[24:27], v[116:119], v[196:199], 0
	v_mfma_f32_16x16x32_bf16 v[12:15], v[64:67], v[204:207], 0
	v_mfma_f32_16x16x32_bf16 v[8:11], v[116:119], v[204:207], 0
	v_mfma_f32_16x16x32_bf16 v[60:63], v[108:111], v[184:187], v[60:63]
	v_mfma_f32_16x16x32_bf16 v[56:59], v[128:131], v[184:187], v[56:59]
	v_mfma_f32_16x16x32_bf16 v[44:47], v[108:111], v[192:195], v[44:47]
	v_mfma_f32_16x16x32_bf16 v[40:43], v[128:131], v[192:195], v[40:43]
	v_mfma_f32_16x16x32_bf16 v[28:31], v[108:111], v[200:203], v[28:31]
	v_mfma_f32_16x16x32_bf16 v[24:27], v[128:131], v[200:203], v[24:27]
	v_mfma_f32_16x16x32_bf16 v[12:15], v[108:111], v[208:211], v[12:15]
	v_mfma_f32_16x16x32_bf16 v[8:11], v[128:131], v[208:211], v[8:11]
	v_mfma_f32_16x16x32_bf16 v[52:55], v[156:159], v[180:183], 0
	v_mfma_f32_16x16x32_bf16 v[48:51], v[172:175], v[180:183], 0
	v_mfma_f32_16x16x32_bf16 v[36:39], v[156:159], v[188:191], 0
	v_mfma_f32_16x16x32_bf16 v[32:35], v[172:175], v[188:191], 0
	v_mfma_f32_16x16x32_bf16 v[20:23], v[156:159], v[196:199], 0
	v_mfma_f32_16x16x32_bf16 v[16:19], v[172:175], v[196:199], 0
	v_mfma_f32_16x16x32_bf16 v[4:7], v[156:159], v[204:207], 0
	v_mfma_f32_16x16x32_bf16 v[0:3], v[172:175], v[204:207], 0
	v_mfma_f32_16x16x32_bf16 v[52:55], v[168:171], v[184:187], v[52:55]
	v_mfma_f32_16x16x32_bf16 v[48:51], v[176:179], v[184:187], v[48:51]
	v_mfma_f32_16x16x32_bf16 v[36:39], v[168:171], v[192:195], v[36:39]
	v_mfma_f32_16x16x32_bf16 v[32:35], v[176:179], v[192:195], v[32:35]
	v_mfma_f32_16x16x32_bf16 v[20:23], v[168:171], v[200:203], v[20:23]
	v_mfma_f32_16x16x32_bf16 v[16:19], v[176:179], v[200:203], v[16:19]
	v_mfma_f32_16x16x32_bf16 v[4:7], v[168:171], v[208:211], v[4:7]
	v_mfma_f32_16x16x32_bf16 v[0:3], v[176:179], v[208:211], v[0:3]
	s_barrier
	s_add_i32 s56, 0, 0x18000
	s_add_i32 s57, 0, 0x1c000
	v_add_u32_e32 v128, s56, v163
	v_add_u32_e32 v176, s57, v163
	ds_read_b128 v[64:67], v128
	ds_read_b128 v[108:111], v128 offset:1024
	ds_read_b128 v[116:119], v128 offset:2048
	ds_read_b128 v[128:131], v128 offset:3072
	ds_read_b128 v[156:159], v176
	ds_read_b128 v[168:171], v176 offset:1024
	ds_read_b128 v[172:175], v176 offset:2048
	ds_read_b128 v[176:179], v176 offset:3072
	s_add_u32 s30, s30, 0x200000
	s_addc_u32 s31, s31, 0
	s_mov_b32 m0, s37
	v_lshl_add_u64 v[218:219], s[30:31], 0, v[144:145]
	ds_read_b128 v[180:183], v167 offset:32768
	ds_read_b128 v[184:187], v167 offset:33792
	ds_read_b128 v[188:191], v167 offset:34816
	ds_read_b128 v[192:195], v167 offset:35840
	ds_read_b128 v[196:199], v167 offset:36864
	ds_read_b128 v[200:203], v167 offset:37888
	ds_read_b128 v[204:207], v167 offset:38912
	ds_read_b128 v[208:211], v167 offset:39936
	global_load_lds_dwordx4 v[218:219], off
	v_lshl_add_u64 v[218:219], s[30:31], 0, v[146:147]
	s_mov_b32 m0, s38
	s_nop 0
	global_load_lds_dwordx4 v[218:219], off
	s_waitcnt vmcnt(8)
	s_waitcnt lgkmcnt(0)
	s_barrier
	v_mfma_f32_16x16x32_bf16 v[140:143], v[64:67], v[180:183], v[140:143]
	v_mfma_f32_16x16x32_bf16 v[136:139], v[116:119], v[180:183], v[136:139]
	v_mfma_f32_16x16x32_bf16 v[120:123], v[64:67], v[188:191], v[120:123]
	v_mfma_f32_16x16x32_bf16 v[112:115], v[116:119], v[188:191], v[112:115]
	v_mfma_f32_16x16x32_bf16 v[96:99], v[64:67], v[196:199], v[96:99]
	v_mfma_f32_16x16x32_bf16 v[92:95], v[116:119], v[196:199], v[92:95]
	v_mfma_f32_16x16x32_bf16 v[80:83], v[64:67], v[204:207], v[80:83]
	v_mfma_f32_16x16x32_bf16 v[76:79], v[116:119], v[204:207], v[76:79]
	v_mfma_f32_16x16x32_bf16 v[140:143], v[108:111], v[184:187], v[140:143]
	v_mfma_f32_16x16x32_bf16 v[136:139], v[128:131], v[184:187], v[136:139]
	v_mfma_f32_16x16x32_bf16 v[120:123], v[108:111], v[192:195], v[120:123]
	v_mfma_f32_16x16x32_bf16 v[112:115], v[128:131], v[192:195], v[112:115]
	v_mfma_f32_16x16x32_bf16 v[96:99], v[108:111], v[200:203], v[96:99]
	v_mfma_f32_16x16x32_bf16 v[92:95], v[128:131], v[200:203], v[92:95]
	v_mfma_f32_16x16x32_bf16 v[80:83], v[108:111], v[208:211], v[80:83]
	v_mfma_f32_16x16x32_bf16 v[76:79], v[128:131], v[208:211], v[76:79]
	v_mfma_f32_16x16x32_bf16 v[132:135], v[156:159], v[180:183], v[132:135]
	v_mfma_f32_16x16x32_bf16 v[124:127], v[172:175], v[180:183], v[124:127]
	v_mfma_f32_16x16x32_bf16 v[104:107], v[156:159], v[188:191], v[104:107]
	v_mfma_f32_16x16x32_bf16 v[100:103], v[172:175], v[188:191], v[100:103]
	v_mfma_f32_16x16x32_bf16 v[88:91], v[156:159], v[196:199], v[88:91]
	v_mfma_f32_16x16x32_bf16 v[84:87], v[172:175], v[196:199], v[84:87]
	v_mfma_f32_16x16x32_bf16 v[72:75], v[156:159], v[204:207], v[72:75]
	v_mfma_f32_16x16x32_bf16 v[68:71], v[172:175], v[204:207], v[68:71]
	v_mfma_f32_16x16x32_bf16 v[132:135], v[168:171], v[184:187], v[132:135]
	v_mfma_f32_16x16x32_bf16 v[124:127], v[176:179], v[184:187], v[124:127]
	v_mfma_f32_16x16x32_bf16 v[104:107], v[168:171], v[192:195], v[104:107]
	v_mfma_f32_16x16x32_bf16 v[100:103], v[176:179], v[192:195], v[100:103]
	v_mfma_f32_16x16x32_bf16 v[88:91], v[168:171], v[200:203], v[88:91]
	v_mfma_f32_16x16x32_bf16 v[84:87], v[176:179], v[200:203], v[84:87]
	v_mfma_f32_16x16x32_bf16 v[72:75], v[168:171], v[208:211], v[72:75]
	v_mfma_f32_16x16x32_bf16 v[68:71], v[176:179], v[208:211], v[68:71]
	s_barrier
; #define PG8_STAGE(bufoff, gbase, voff) do { _Pragma("unroll") for (int _i = 0; _i < 2; ++_i) \
;         __builtin_amdgcn_global_load_lds((const unsigned*)((const char*)(gbase) + (voff)[_i]), (PG8_LAS unsigned*)(lds + (bufoff) + ldsw + _i * 8192), 16, 0, 0); } while (0)
; #define PG8_LDA(dst, b, h) do { _Pragma("unroll") for (int m = 0; m < 4; ++m) _Pragma("unroll") for (int k = 0; k < 2; ++k) dst[m][k] = *(const PG8_LAS bf16x8*)(lds + PG8_SA(b, h) + aoff + m * 2048 + k * 1024); } while (0)
; #define PG8_LDB(dst, b, h) do { _Pragma("unroll") for (int n = 0; n < 2; ++n) _Pragma("unroll") for (int k = 0; k < 2; ++k) dst[n][k] = *(const PG8_LAS bf16x8*)(lds + PG8_SB(b, h) + boff + n * 2048 + k * 1024); } while (0)
; #define PG8_MMA(ai, bj, At, Bt) do { __builtin_amdgcn_s_setprio(1); _Pragma("unroll") for (int m = 0; m < 4; ++m) _Pragma("unroll") for (int n = 0; n < 2; ++n) _Pragma("unroll") for (int k = 0; k < 2; ++k) \
;         acc[ai][bj][m][n] = __builtin_amdgcn_mfma_f32_16x16x32_bf16(Bt[n][k], At[m][k], acc[ai][bj][m][n], 0, 0, 0); __builtin_amdgcn_s_setprio(0); } while (0)
; #define PG8_WAIT_V(n) asm volatile("s_waitcnt vmcnt(" #n ")" ::: "memory")
; template <class Epi, class Sched, bool ALIGN_EPI = false, bool SP2 = false>
; __device__ __forceinline__ void gemm_phase(PG8_LAS unsigned char* lds, const Gemm g, const Sched& S, const Epi& E) {
;     ...
;             PG8_LDB(B0, 0, 0); PG8_LDB(B1, 0, 1); PG8_SCHED; PG8_LDA(At, 0, 0); PG8_STAGE(PG8_SA(1, 1), a1 + hstep, voffA);
;             PG8_WAIT_V(8); PG8_WAIT_L(0); PG8_BAR; PG8_MMA(0, 0, At, B0); PG8_MMA(0, 1, At, B1); PG8_BAR; PG8_SCHED;
;             PG8_LDA(At, 0, 1); PG8_STAGE(PG8_SB(0, 0), b2, voffB); PG8_STAGE(PG8_SB(0, 1), b2 + hstep, voffB); PG8_STAGE(PG8_SA(0, 0), a2, voffA);
;             PG8_WAIT_V(8); PG8_WAIT_L(0); PG8_BAR; PG8_MMA(1, 0, At, B0); PG8_MMA(1, 1, At, B1); PG8_BAR; PG8_SCHED;
;             PG8_LDB(B0, 1, 0); PG8_LDB(B1, 1, 1); PG8_SCHED; PG8_LDA(At, 1, 0); PG8_STAGE(PG8_SA(0, 1), a2 + hstep, voffA);
;             PG8_WAIT_V(8); PG8_WAIT_L(0); PG8_BAR; PG8_MMA(0, 0, At, B0); PG8_MMA(0, 1, At, B1); PG8_BAR; PG8_SCHED;
;             PG8_LDA(At, 1, 1); PG8_STAGE(PG8_SB(1, 0), b3, voffB); PG8_STAGE(PG8_SB(1, 1), b3 + hstep, voffB); PG8_STAGE(PG8_SA(1, 0), a3, voffA);
;             PG8_WAIT_V(8); PG8_WAIT_L(0); PG8_BAR; PG8_MMA(1, 0, At, B0); PG8_MMA(1, 1, At, B1); PG8_BAR; PG8_SCHED;
	s_add_i32 s30, s56, s34
	v_lshl_add_u64 v[160:161], v[160:161], 0, s[4:5]
	s_mov_b32 m0, s30
	ds_read_b128 v[180:183], v167 offset:49152
	ds_read_b128 v[184:187], v167 offset:50176
	ds_read_b128 v[188:191], v167 offset:51200
	ds_read_b128 v[192:195], v167 offset:52224
	ds_read_b128 v[196:199], v167 offset:53248
	ds_read_b128 v[200:203], v167 offset:54272
	ds_read_b128 v[204:207], v167 offset:55296
	ds_read_b128 v[208:211], v167 offset:56320
	global_load_lds_dwordx4 v[160:161], off
	s_add_i32 m0, s30, 0x2000
	s_add_u32 s28, s28, 0x200080
	v_lshl_add_u64 v[160:161], v[212:213], 0, s[4:5]
	s_addc_u32 s29, s29, 0
	s_add_i32 s30, s57, s34
	global_load_lds_dwordx4 v[160:161], off
	v_lshl_add_u64 v[160:161], s[28:29], 0, v[144:145]
	s_mov_b32 m0, s30
	s_nop 0
	global_load_lds_dwordx4 v[160:161], off
	v_lshl_add_u64 v[160:161], s[28:29], 0, v[146:147]
	s_add_i32 m0, s30, 0x2000
	s_nop 0
	global_load_lds_dwordx4 v[160:161], off
	v_lshl_add_u64 v[160:161], v[214:215], 0, s[4:5]
	s_mov_b32 m0, s42
	s_nop 0
	global_load_lds_dwordx4 v[160:161], off
	v_lshl_add_u64 v[160:161], v[216:217], 0, s[4:5]
	s_mov_b32 m0, s43
	s_nop 0
	global_load_lds_dwordx4 v[160:161], off
	s_waitcnt vmcnt(8)
	s_waitcnt lgkmcnt(0)
	s_barrier
	v_mfma_f32_16x16x32_bf16 v[60:63], v[64:67], v[180:183], v[60:63]
	v_mfma_f32_16x16x32_bf16 v[56:59], v[116:119], v[180:183], v[56:59]
	v_mfma_f32_16x16x32_bf16 v[44:47], v[64:67], v[188:191], v[44:47]
	v_mfma_f32_16x16x32_bf16 v[40:43], v[116:119], v[188:191], v[40:43]
	v_mfma_f32_16x16x32_bf16 v[28:31], v[64:67], v[196:199], v[28:31]
	v_mfma_f32_16x16x32_bf16 v[24:27], v[116:119], v[196:199], v[24:27]
	v_mfma_f32_16x16x32_bf16 v[12:15], v[64:67], v[204:207], v[12:15]
	v_mfma_f32_16x16x32_bf16 v[8:11], v[116:119], v[204:207], v[8:11]
	v_mfma_f32_16x16x32_bf16 v[60:63], v[108:111], v[184:187], v[60:63]
	v_mfma_f32_16x16x32_bf16 v[56:59], v[128:131], v[184:187], v[56:59]
	v_mfma_f32_16x16x32_bf16 v[44:47], v[108:111], v[192:195], v[44:47]
	v_mfma_f32_16x16x32_bf16 v[40:43], v[128:131], v[192:195], v[40:43]
	v_mfma_f32_16x16x32_bf16 v[28:31], v[108:111], v[200:203], v[28:31]
	v_mfma_f32_16x16x32_bf16 v[24:27], v[128:131], v[200:203], v[24:27]
	v_mfma_f32_16x16x32_bf16 v[12:15], v[108:111], v[208:211], v[12:15]
	v_mfma_f32_16x16x32_bf16 v[8:11], v[128:131], v[208:211], v[8:11]
	v_mfma_f32_16x16x32_bf16 v[52:55], v[156:159], v[180:183], v[52:55]
	v_mfma_f32_16x16x32_bf16 v[48:51], v[172:175], v[180:183], v[48:51]
	v_mfma_f32_16x16x32_bf16 v[36:39], v[156:159], v[188:191], v[36:39]
	v_mfma_f32_16x16x32_bf16 v[32:35], v[172:175], v[188:191], v[32:35]
	v_mfma_f32_16x16x32_bf16 v[20:23], v[156:159], v[196:199], v[20:23]
	v_mfma_f32_16x16x32_bf16 v[16:19], v[172:175], v[196:199], v[16:19]
	v_mfma_f32_16x16x32_bf16 v[4:7], v[156:159], v[204:207], v[4:7]
	v_mfma_f32_16x16x32_bf16 v[0:3], v[172:175], v[204:207], v[0:3]
	v_mfma_f32_16x16x32_bf16 v[52:55], v[168:171], v[184:187], v[52:55]
	v_mfma_f32_16x16x32_bf16 v[48:51], v[176:179], v[184:187], v[48:51]
	v_mfma_f32_16x16x32_bf16 v[36:39], v[168:171], v[192:195], v[36:39]
	v_mfma_f32_16x16x32_bf16 v[32:35], v[176:179], v[192:195], v[32:35]
	v_mfma_f32_16x16x32_bf16 v[20:23], v[168:171], v[200:203], v[20:23]
	v_mfma_f32_16x16x32_bf16 v[16:19], v[176:179], v[200:203], v[16:19]
	v_mfma_f32_16x16x32_bf16 v[4:7], v[168:171], v[208:211], v[4:7]
	v_mfma_f32_16x16x32_bf16 v[0:3], v[176:179], v[208:211], v[0:3]
	s_barrier
	s_add_i32 s55, s55, 2
	s_add_u32 s26, s26, 0x100
	s_addc_u32 s27, s27, 0
	s_add_u32 s53, s53, 0x100
	s_addc_u32 s54, s54, 0
	s_cmpk_gt_u32 s55, 0x7d
.LBB0_1071:
	ds_read_b128 v[64:67], v165
	ds_read_b128 v[108:111], v165 offset:1024
	ds_read_b128 v[116:119], v165 offset:2048
	ds_read_b128 v[128:131], v165 offset:3072
	ds_read_b128 v[156:159], v166
	ds_read_b128 v[168:171], v166 offset:1024
	ds_read_b128 v[172:175], v166 offset:2048
	ds_read_b128 v[176:179], v166 offset:3072
	s_add_u32 s28, s26, 0xffe00080
	s_addc_u32 s29, s27, -1
	s_cmpk_eq_i32 s55, 0x7c
	s_cselect_b32 s31, s19, s29
	s_cselect_b32 s30, s51, s28
	s_cselect_b32 s29, s17, s54
	s_cselect_b32 s28, s52, s53
	v_lshl_add_u64 v[160:161], s[26:27], 0, v[148:149]
	s_add_i32 m0, s35, 0xc000
	ds_read_b128 v[180:183], v167
	ds_read_b128 v[184:187], v167 offset:1024
	ds_read_b128 v[188:191], v167 offset:2048
	ds_read_b128 v[192:195], v167 offset:3072
	ds_read_b128 v[196:199], v167 offset:4096
	ds_read_b128 v[200:203], v167 offset:5120
	ds_read_b128 v[204:207], v167 offset:6144
	ds_read_b128 v[208:211], v167 offset:7168
	global_load_lds_dwordx4 v[160:161], off
	v_lshl_add_u64 v[160:161], s[26:27], 0, v[150:151]
	s_add_i32 m0, s35, 0xe000
	s_nop 0
	global_load_lds_dwordx4 v[160:161], off
	s_waitcnt vmcnt(8)
	s_waitcnt lgkmcnt(0)
	s_barrier
; #define PG8_STAGE(bufoff, gbase, voff) do { _Pragma("unroll") for (int _i = 0; _i < 2; ++_i) \
;         __builtin_amdgcn_global_load_lds((const unsigned*)((const char*)(gbase) + (voff)[_i]), (PG8_LAS unsigned*)(lds + (bufoff) + ldsw + _i * 8192), 16, 0, 0); } while (0)
; #define PG8_LDA(dst, b, h) do { _Pragma("unroll") for (int m = 0; m < 4; ++m) _Pragma("unroll") for (int k = 0; k < 2; ++k) dst[m][k] = *(const PG8_LAS bf16x8*)(lds + PG8_SA(b, h) + aoff + m * 2048 + k * 1024); } while (0)
; #define PG8_MMA(ai, bj, At, Bt) do { __builtin_amdgcn_s_setprio(1); _Pragma("unroll") for (int m = 0; m < 4; ++m) _Pragma("unroll") for (int n = 0; n < 2; ++n) _Pragma("unroll") for (int k = 0; k < 2; ++k) \
;         acc[ai][bj][m][n] = __builtin_amdgcn_mfma_f32_16x16x32_bf16(Bt[n][k], At[m][k], acc[ai][bj][m][n], 0, 0, 0); __builtin_amdgcn_s_setprio(0); } while (0)
; #define PG8_WAIT_V(n) asm volatile("s_waitcnt vmcnt(" #n ")" ::: "memory")
; #define PG8_WAIT_L(n) asm volatile("s_waitcnt lgkmcnt(" #n ")" ::: "memory")
; #define PG8_BAR __builtin_amdgcn_s_barrier()
; #define PG8_SCHED __builtin_amdgcn_sched_barrier(0)
; template <class Epi, class Sched, bool ALIGN_EPI = false, bool SP2 = false>
; __device__ __forceinline__ void gemm_phase(PG8_LAS unsigned char* lds, const Gemm g, const Sched& S, const Epi& E) {
;     ...
;             PG8_WAIT_V(8); PG8_WAIT_L(0); PG8_BAR; PG8_MMA(0, 0, At, B0); PG8_MMA(0, 1, At, B1); PG8_BAR; PG8_SCHED;
;             PG8_LDA(At, 0, 1); PG8_STAGE(PG8_SB(0, 0), b2, voffB); PG8_STAGE(PG8_SB(0, 1), b2 + hstep, voffB); PG8_STAGE(PG8_SA(0, 0), a2, voffA);
;             PG8_WAIT_V(8); PG8_WAIT_L(0); PG8_BAR; PG8_MMA(1, 0, At, B0); PG8_MMA(1, 1, At, B1); PG8_BAR; PG8_SCHED;
	v_mfma_f32_16x16x32_bf16 v[140:143], v[64:67], v[180:183], v[140:143]
	v_mfma_f32_16x16x32_bf16 v[136:139], v[116:119], v[180:183], v[136:139]
	v_mfma_f32_16x16x32_bf16 v[120:123], v[64:67], v[188:191], v[120:123]
	v_mfma_f32_16x16x32_bf16 v[112:115], v[116:119], v[188:191], v[112:115]
	v_mfma_f32_16x16x32_bf16 v[96:99], v[64:67], v[196:199], v[96:99]
	v_mfma_f32_16x16x32_bf16 v[92:95], v[116:119], v[196:199], v[92:95]
	v_mfma_f32_16x16x32_bf16 v[80:83], v[64:67], v[204:207], v[80:83]
	v_mfma_f32_16x16x32_bf16 v[76:79], v[116:119], v[204:207], v[76:79]
	v_mfma_f32_16x16x32_bf16 v[140:143], v[108:111], v[184:187], v[140:143]
	v_mfma_f32_16x16x32_bf16 v[136:139], v[128:131], v[184:187], v[136:139]
	v_mfma_f32_16x16x32_bf16 v[120:123], v[108:111], v[192:195], v[120:123]
	v_mfma_f32_16x16x32_bf16 v[112:115], v[128:131], v[192:195], v[112:115]
	v_mfma_f32_16x16x32_bf16 v[96:99], v[108:111], v[200:203], v[96:99]
	v_mfma_f32_16x16x32_bf16 v[92:95], v[128:131], v[200:203], v[92:95]
	v_mfma_f32_16x16x32_bf16 v[80:83], v[108:111], v[208:211], v[80:83]
	v_mfma_f32_16x16x32_bf16 v[76:79], v[128:131], v[208:211], v[76:79]
	v_mfma_f32_16x16x32_bf16 v[132:135], v[156:159], v[180:183], v[132:135]
	v_mfma_f32_16x16x32_bf16 v[124:127], v[172:175], v[180:183], v[124:127]
	v_mfma_f32_16x16x32_bf16 v[104:107], v[156:159], v[188:191], v[104:107]
	v_mfma_f32_16x16x32_bf16 v[100:103], v[172:175], v[188:191], v[100:103]
	v_mfma_f32_16x16x32_bf16 v[88:91], v[156:159], v[196:199], v[88:91]
	v_mfma_f32_16x16x32_bf16 v[84:87], v[172:175], v[196:199], v[84:87]
	v_mfma_f32_16x16x32_bf16 v[72:75], v[156:159], v[204:207], v[72:75]
	v_mfma_f32_16x16x32_bf16 v[68:71], v[172:175], v[204:207], v[68:71]
	v_mfma_f32_16x16x32_bf16 v[132:135], v[168:171], v[184:187], v[132:135]
	v_mfma_f32_16x16x32_bf16 v[124:127], v[176:179], v[184:187], v[124:127]
	v_mfma_f32_16x16x32_bf16 v[104:107], v[168:171], v[192:195], v[104:107]
	v_mfma_f32_16x16x32_bf16 v[100:103], v[176:179], v[192:195], v[100:103]
	v_mfma_f32_16x16x32_bf16 v[88:91], v[168:171], v[200:203], v[88:91]
	v_mfma_f32_16x16x32_bf16 v[84:87], v[176:179], v[200:203], v[84:87]
	v_mfma_f32_16x16x32_bf16 v[72:75], v[168:171], v[208:211], v[72:75]
	v_mfma_f32_16x16x32_bf16 v[68:71], v[176:179], v[208:211], v[68:71]
	s_barrier
	s_add_i32 s56, s45, s34
	v_lshl_add_u64 v[160:161], s[28:29], 0, v[144:145]
	s_mov_b32 m0, s56
	ds_read_b128 v[180:183], v167 offset:16384
	ds_read_b128 v[184:187], v167 offset:17408
	ds_read_b128 v[188:191], v167 offset:18432
	ds_read_b128 v[192:195], v167 offset:19456
	ds_read_b128 v[196:199], v167 offset:20480
	ds_read_b128 v[200:203], v167 offset:21504
	ds_read_b128 v[204:207], v167 offset:22528
	ds_read_b128 v[208:211], v167 offset:23552
	global_load_lds_dwordx4 v[160:161], off
	s_add_i32 m0, s56, 0x2000
	s_add_u32 s56, s28, 0x200000
	v_lshl_add_u64 v[212:213], s[28:29], 0, v[146:147]
	s_addc_u32 s57, s29, 0
	s_add_i32 s58, s46, s34
	global_load_lds_dwordx4 v[212:213], off
	v_lshl_add_u64 v[214:215], s[56:57], 0, v[144:145]
	s_mov_b32 m0, s58
	v_lshl_add_u64 v[216:217], s[30:31], 0, v[146:147]
	global_load_lds_dwordx4 v[214:215], off
	v_lshl_add_u64 v[214:215], s[56:57], 0, v[146:147]
	s_add_i32 m0, s58, 0x2000
	s_nop 0
	global_load_lds_dwordx4 v[214:215], off
	v_lshl_add_u64 v[214:215], s[30:31], 0, v[144:145]
	s_mov_b32 m0, s35
	s_nop 0
	global_load_lds_dwordx4 v[214:215], off
	s_mov_b32 m0, s36
	s_nop 0
	global_load_lds_dwordx4 v[216:217], off
	s_waitcnt vmcnt(8)
	s_waitcnt lgkmcnt(0)
	s_barrier
	v_mfma_f32_16x16x32_bf16 v[60:63], v[64:67], v[180:183], v[60:63]
	v_mfma_f32_16x16x32_bf16 v[56:59], v[116:119], v[180:183], v[56:59]
	v_mfma_f32_16x16x32_bf16 v[44:47], v[64:67], v[188:191], v[44:47]
	v_mfma_f32_16x16x32_bf16 v[40:43], v[116:119], v[188:191], v[40:43]
	v_mfma_f32_16x16x32_bf16 v[28:31], v[64:67], v[196:199], v[28:31]
	v_mfma_f32_16x16x32_bf16 v[24:27], v[116:119], v[196:199], v[24:27]
	v_mfma_f32_16x16x32_bf16 v[12:15], v[64:67], v[204:207], v[12:15]
	v_mfma_f32_16x16x32_bf16 v[8:11], v[116:119], v[204:207], v[8:11]
	v_mfma_f32_16x16x32_bf16 v[60:63], v[108:111], v[184:187], v[60:63]
	v_mfma_f32_16x16x32_bf16 v[56:59], v[128:131], v[184:187], v[56:59]
	v_mfma_f32_16x16x32_bf16 v[44:47], v[108:111], v[192:195], v[44:47]
	v_mfma_f32_16x16x32_bf16 v[40:43], v[128:131], v[192:195], v[40:43]
	v_mfma_f32_16x16x32_bf16 v[28:31], v[108:111], v[200:203], v[28:31]
	v_mfma_f32_16x16x32_bf16 v[24:27], v[128:131], v[200:203], v[24:27]
	v_mfma_f32_16x16x32_bf16 v[12:15], v[108:111], v[208:211], v[12:15]
	v_mfma_f32_16x16x32_bf16 v[8:11], v[128:131], v[208:211], v[8:11]
	v_mfma_f32_16x16x32_bf16 v[52:55], v[156:159], v[180:183], v[52:55]
	v_mfma_f32_16x16x32_bf16 v[48:51], v[172:175], v[180:183], v[48:51]
	v_mfma_f32_16x16x32_bf16 v[36:39], v[156:159], v[188:191], v[36:39]
	v_mfma_f32_16x16x32_bf16 v[32:35], v[172:175], v[188:191], v[32:35]
	v_mfma_f32_16x16x32_bf16 v[20:23], v[156:159], v[196:199], v[20:23]
	v_mfma_f32_16x16x32_bf16 v[16:19], v[172:175], v[196:199], v[16:19]
	v_mfma_f32_16x16x32_bf16 v[4:7], v[156:159], v[204:207], v[4:7]
	v_mfma_f32_16x16x32_bf16 v[0:3], v[172:175], v[204:207], v[0:3]
	v_mfma_f32_16x16x32_bf16 v[52:55], v[168:171], v[184:187], v[52:55]
	v_mfma_f32_16x16x32_bf16 v[48:51], v[176:179], v[184:187], v[48:51]
	v_mfma_f32_16x16x32_bf16 v[36:39], v[168:171], v[192:195], v[36:39]
	v_mfma_f32_16x16x32_bf16 v[32:35], v[176:179], v[192:195], v[32:35]
	v_mfma_f32_16x16x32_bf16 v[20:23], v[168:171], v[200:203], v[20:23]
	v_mfma_f32_16x16x32_bf16 v[16:19], v[176:179], v[200:203], v[16:19]
	v_mfma_f32_16x16x32_bf16 v[4:7], v[168:171], v[208:211], v[4:7]
	v_mfma_f32_16x16x32_bf16 v[0:3], v[176:179], v[208:211], v[0:3]
	s_barrier
; #define PG8_STAGE(bufoff, gbase, voff) do { _Pragma("unroll") for (int _i = 0; _i < 2; ++_i) \
;         __builtin_amdgcn_global_load_lds((const unsigned*)((const char*)(gbase) + (voff)[_i]), (PG8_LAS unsigned*)(lds + (bufoff) + ldsw + _i * 8192), 16, 0, 0); } while (0)
; #define PG8_LDA(dst, b, h) do { _Pragma("unroll") for (int m = 0; m < 4; ++m) _Pragma("unroll") for (int k = 0; k < 2; ++k) dst[m][k] = *(const PG8_LAS bf16x8*)(lds + PG8_SA(b, h) + aoff + m * 2048 + k * 1024); } while (0)
; #define PG8_LDB(dst, b, h) do { _Pragma("unroll") for (int n = 0; n < 2; ++n) _Pragma("unroll") for (int k = 0; k < 2; ++k) dst[n][k] = *(const PG8_LAS bf16x8*)(lds + PG8_SB(b, h) + boff + n * 2048 + k * 1024); } while (0)
; #define PG8_MMA(ai, bj, At, Bt) do { __builtin_amdgcn_s_setprio(1); _Pragma("unroll") for (int m = 0; m < 4; ++m) _Pragma("unroll") for (int n = 0; n < 2; ++n) _Pragma("unroll") for (int k = 0; k < 2; ++k) \
;         acc[ai][bj][m][n] = __builtin_amdgcn_mfma_f32_16x16x32_bf16(Bt[n][k], At[m][k], acc[ai][bj][m][n], 0, 0, 0); __builtin_amdgcn_s_setprio(0); } while (0)
; #define PG8_WAIT_V(n) asm volatile("s_waitcnt vmcnt(" #n ")" ::: "memory")
; #define PG8_WAIT_L(n) asm volatile("s_waitcnt lgkmcnt(" #n ")" ::: "memory")
; #define PG8_BAR __builtin_amdgcn_s_barrier()
; #define PG8_SCHED __builtin_amdgcn_sched_barrier(0)
; template <class Epi, class Sched, bool ALIGN_EPI = false, bool SP2 = false>
; __device__ __forceinline__ void gemm_phase(PG8_LAS unsigned char* lds, const Gemm g, const Sched& S, const Epi& E) {
;     ...
;             PG8_LDB(B0, 1, 0); PG8_LDB(B1, 1, 1); PG8_SCHED; PG8_LDA(At, 1, 0); PG8_STAGE(PG8_SA(0, 1), a2 + hstep, voffA);
;             PG8_WAIT_V(8); PG8_WAIT_L(0); PG8_BAR; PG8_MMA(0, 0, At, B0); PG8_MMA(0, 1, At, B1); PG8_BAR; PG8_SCHED;
	s_add_i32 s56, 0, 0x18000
	s_add_i32 s57, 0, 0x1c000
	v_add_u32_e32 v128, s56, v163
	v_add_u32_e32 v176, s57, v163
	ds_read_b128 v[64:67], v128
	ds_read_b128 v[108:111], v128 offset:1024
	ds_read_b128 v[116:119], v128 offset:2048
	ds_read_b128 v[128:131], v128 offset:3072
	ds_read_b128 v[156:159], v176
	ds_read_b128 v[168:171], v176 offset:1024
	ds_read_b128 v[172:175], v176 offset:2048
	ds_read_b128 v[176:179], v176 offset:3072
	s_add_u32 s30, s30, 0x200000
	s_addc_u32 s31, s31, 0
	s_mov_b32 m0, s37
	v_lshl_add_u64 v[218:219], s[30:31], 0, v[144:145]
	ds_read_b128 v[180:183], v167 offset:32768
	ds_read_b128 v[184:187], v167 offset:33792
	ds_read_b128 v[188:191], v167 offset:34816
	ds_read_b128 v[192:195], v167 offset:35840
	ds_read_b128 v[196:199], v167 offset:36864
	ds_read_b128 v[200:203], v167 offset:37888
	ds_read_b128 v[204:207], v167 offset:38912
	ds_read_b128 v[208:211], v167 offset:39936
	global_load_lds_dwordx4 v[218:219], off
	v_lshl_add_u64 v[218:219], s[30:31], 0, v[146:147]
	s_mov_b32 m0, s38
	s_nop 0
	global_load_lds_dwordx4 v[218:219], off
	s_waitcnt vmcnt(8)
	s_waitcnt lgkmcnt(0)
	s_barrier
	v_mfma_f32_16x16x32_bf16 v[140:143], v[64:67], v[180:183], v[140:143]
	v_mfma_f32_16x16x32_bf16 v[136:139], v[116:119], v[180:183], v[136:139]
	v_mfma_f32_16x16x32_bf16 v[120:123], v[64:67], v[188:191], v[120:123]
	v_mfma_f32_16x16x32_bf16 v[112:115], v[116:119], v[188:191], v[112:115]
	v_mfma_f32_16x16x32_bf16 v[96:99], v[64:67], v[196:199], v[96:99]
	v_mfma_f32_16x16x32_bf16 v[92:95], v[116:119], v[196:199], v[92:95]
	v_mfma_f32_16x16x32_bf16 v[80:83], v[64:67], v[204:207], v[80:83]
	v_mfma_f32_16x16x32_bf16 v[76:79], v[116:119], v[204:207], v[76:79]
	v_mfma_f32_16x16x32_bf16 v[140:143], v[108:111], v[184:187], v[140:143]
	v_mfma_f32_16x16x32_bf16 v[136:139], v[128:131], v[184:187], v[136:139]
	v_mfma_f32_16x16x32_bf16 v[120:123], v[108:111], v[192:195], v[120:123]
	v_mfma_f32_16x16x32_bf16 v[112:115], v[128:131], v[192:195], v[112:115]
	v_mfma_f32_16x16x32_bf16 v[96:99], v[108:111], v[200:203], v[96:99]
	v_mfma_f32_16x16x32_bf16 v[92:95], v[128:131], v[200:203], v[92:95]
	v_mfma_f32_16x16x32_bf16 v[80:83], v[108:111], v[208:211], v[80:83]
	v_mfma_f32_16x16x32_bf16 v[76:79], v[128:131], v[208:211], v[76:79]
	v_mfma_f32_16x16x32_bf16 v[132:135], v[156:159], v[180:183], v[132:135]
	v_mfma_f32_16x16x32_bf16 v[124:127], v[172:175], v[180:183], v[124:127]
	v_mfma_f32_16x16x32_bf16 v[104:107], v[156:159], v[188:191], v[104:107]
	v_mfma_f32_16x16x32_bf16 v[100:103], v[172:175], v[188:191], v[100:103]
	v_mfma_f32_16x16x32_bf16 v[88:91], v[156:159], v[196:199], v[88:91]
	v_mfma_f32_16x16x32_bf16 v[84:87], v[172:175], v[196:199], v[84:87]
	v_mfma_f32_16x16x32_bf16 v[72:75], v[156:159], v[204:207], v[72:75]
	v_mfma_f32_16x16x32_bf16 v[68:71], v[172:175], v[204:207], v[68:71]
	v_mfma_f32_16x16x32_bf16 v[132:135], v[168:171], v[184:187], v[132:135]
	v_mfma_f32_16x16x32_bf16 v[124:127], v[176:179], v[184:187], v[124:127]
	v_mfma_f32_16x16x32_bf16 v[104:107], v[168:171], v[192:195], v[104:107]
	v_mfma_f32_16x16x32_bf16 v[100:103], v[176:179], v[192:195], v[100:103]
	v_mfma_f32_16x16x32_bf16 v[88:91], v[168:171], v[200:203], v[88:91]
	v_mfma_f32_16x16x32_bf16 v[84:87], v[176:179], v[200:203], v[84:87]
	v_mfma_f32_16x16x32_bf16 v[72:75], v[168:171], v[208:211], v[72:75]
	v_mfma_f32_16x16x32_bf16 v[68:71], v[176:179], v[208:211], v[68:71]
	s_barrier
; #define PG8_STAGE(bufoff, gbase, voff) do { _Pragma("unroll") for (int _i = 0; _i < 2; ++_i) \
;         __builtin_amdgcn_global_load_lds((const unsigned*)((const char*)(gbase) + (voff)[_i]), (PG8_LAS unsigned*)(lds + (bufoff) + ldsw + _i * 8192), 16, 0, 0); } while (0)
; #define PG8_LDA(dst, b, h) do { _Pragma("unroll") for (int m = 0; m < 4; ++m) _Pragma("unroll") for (int k = 0; k < 2; ++k) dst[m][k] = *(const PG8_LAS bf16x8*)(lds + PG8_SA(b, h) + aoff + m * 2048 + k * 1024); } while (0)
; #define PG8_MMA(ai, bj, At, Bt) do { __builtin_amdgcn_s_setprio(1); _Pragma("unroll") for (int m = 0; m < 4; ++m) _Pragma("unroll") for (int n = 0; n < 2; ++n) _Pragma("unroll") for (int k = 0; k < 2; ++k) \
;         acc[ai][bj][m][n] = __builtin_amdgcn_mfma_f32_16x16x32_bf16(Bt[n][k], At[m][k], acc[ai][bj][m][n], 0, 0, 0); __builtin_amdgcn_s_setprio(0); } while (0)
; #define PG8_WAIT_V(n) asm volatile("s_waitcnt vmcnt(" #n ")" ::: "memory")
; #define PG8_WAIT_L(n) asm volatile("s_waitcnt lgkmcnt(" #n ")" ::: "memory")
; #define PG8_BAR __builtin_amdgcn_s_barrier()
; #define PG8_SCHED __builtin_amdgcn_sched_barrier(0)
; template <class Epi, class Sched, bool ALIGN_EPI = false, bool SP2 = false>
; __device__ __forceinline__ void gemm_phase(PG8_LAS unsigned char* lds, const Gemm g, const Sched& S, const Epi& E) {
;     ...
;             PG8_LDA(At, 1, 1); PG8_STAGE(PG8_SB(1, 0), b3, voffB); PG8_STAGE(PG8_SB(1, 1), b3 + hstep, voffB); PG8_STAGE(PG8_SA(1, 0), a3, voffA);
;             PG8_WAIT_V(8); PG8_WAIT_L(0); PG8_BAR; PG8_MMA(1, 0, At, B0); PG8_MMA(1, 1, At, B1); PG8_BAR; PG8_SCHED;
;     ...
;         if constexpr (ALIGN_EPI) { if (wr == 0) PG8_BAR; }
	s_add_i32 s30, s56, s34
	v_lshl_add_u64 v[160:161], v[160:161], 0, s[4:5]
	s_mov_b32 m0, s30
	ds_read_b128 v[180:183], v167 offset:49152
	ds_read_b128 v[184:187], v167 offset:50176
	ds_read_b128 v[188:191], v167 offset:51200
	ds_read_b128 v[192:195], v167 offset:52224
	ds_read_b128 v[196:199], v167 offset:53248
	ds_read_b128 v[200:203], v167 offset:54272
	ds_read_b128 v[204:207], v167 offset:55296
	ds_read_b128 v[208:211], v167 offset:56320
	global_load_lds_dwordx4 v[160:161], off
	s_add_i32 m0, s30, 0x2000
	s_add_u32 s28, s28, 0x200080
	v_lshl_add_u64 v[160:161], v[212:213], 0, s[4:5]
	s_addc_u32 s29, s29, 0
	s_add_i32 s30, s57, s34
	global_load_lds_dwordx4 v[160:161], off
	v_lshl_add_u64 v[160:161], s[28:29], 0, v[144:145]
	s_mov_b32 m0, s30
	s_nop 0
	global_load_lds_dwordx4 v[160:161], off
	v_lshl_add_u64 v[160:161], s[28:29], 0, v[146:147]
	s_add_i32 m0, s30, 0x2000
	s_nop 0
	global_load_lds_dwordx4 v[160:161], off
	v_lshl_add_u64 v[160:161], v[214:215], 0, s[4:5]
	s_mov_b32 m0, s42
	s_nop 0
	global_load_lds_dwordx4 v[160:161], off
	v_lshl_add_u64 v[160:161], v[216:217], 0, s[4:5]
	s_mov_b32 m0, s43
	s_nop 0
	global_load_lds_dwordx4 v[160:161], off
	s_waitcnt vmcnt(8)
	s_waitcnt lgkmcnt(0)
	s_barrier
	v_mfma_f32_16x16x32_bf16 v[60:63], v[64:67], v[180:183], v[60:63]
	v_mfma_f32_16x16x32_bf16 v[56:59], v[116:119], v[180:183], v[56:59]
	v_mfma_f32_16x16x32_bf16 v[44:47], v[64:67], v[188:191], v[44:47]
	v_mfma_f32_16x16x32_bf16 v[40:43], v[116:119], v[188:191], v[40:43]
	v_mfma_f32_16x16x32_bf16 v[28:31], v[64:67], v[196:199], v[28:31]
	v_mfma_f32_16x16x32_bf16 v[24:27], v[116:119], v[196:199], v[24:27]
	v_mfma_f32_16x16x32_bf16 v[12:15], v[64:67], v[204:207], v[12:15]
	v_mfma_f32_16x16x32_bf16 v[8:11], v[116:119], v[204:207], v[8:11]
	v_mfma_f32_16x16x32_bf16 v[60:63], v[108:111], v[184:187], v[60:63]
	v_mfma_f32_16x16x32_bf16 v[56:59], v[128:131], v[184:187], v[56:59]
	v_mfma_f32_16x16x32_bf16 v[44:47], v[108:111], v[192:195], v[44:47]
	v_mfma_f32_16x16x32_bf16 v[40:43], v[128:131], v[192:195], v[40:43]
	v_mfma_f32_16x16x32_bf16 v[28:31], v[108:111], v[200:203], v[28:31]
	v_mfma_f32_16x16x32_bf16 v[24:27], v[128:131], v[200:203], v[24:27]
	v_mfma_f32_16x16x32_bf16 v[12:15], v[108:111], v[208:211], v[12:15]
	v_mfma_f32_16x16x32_bf16 v[8:11], v[128:131], v[208:211], v[8:11]
	v_mfma_f32_16x16x32_bf16 v[52:55], v[156:159], v[180:183], v[52:55]
	v_mfma_f32_16x16x32_bf16 v[48:51], v[172:175], v[180:183], v[48:51]
	v_mfma_f32_16x16x32_bf16 v[36:39], v[156:159], v[188:191], v[36:39]
	v_mfma_f32_16x16x32_bf16 v[32:35], v[172:175], v[188:191], v[32:35]
	v_mfma_f32_16x16x32_bf16 v[20:23], v[156:159], v[196:199], v[20:23]
	v_mfma_f32_16x16x32_bf16 v[16:19], v[172:175], v[196:199], v[16:19]
	v_mfma_f32_16x16x32_bf16 v[4:7], v[156:159], v[204:207], v[4:7]
	v_mfma_f32_16x16x32_bf16 v[0:3], v[172:175], v[204:207], v[0:3]
	v_mfma_f32_16x16x32_bf16 v[52:55], v[168:171], v[184:187], v[52:55]
	v_mfma_f32_16x16x32_bf16 v[48:51], v[176:179], v[184:187], v[48:51]
	v_mfma_f32_16x16x32_bf16 v[36:39], v[168:171], v[192:195], v[36:39]
	v_mfma_f32_16x16x32_bf16 v[32:35], v[176:179], v[192:195], v[32:35]
	v_mfma_f32_16x16x32_bf16 v[20:23], v[168:171], v[200:203], v[20:23]
	v_mfma_f32_16x16x32_bf16 v[16:19], v[176:179], v[200:203], v[16:19]
	v_mfma_f32_16x16x32_bf16 v[4:7], v[168:171], v[208:211], v[4:7]
	v_mfma_f32_16x16x32_bf16 v[0:3], v[176:179], v[208:211], v[0:3]
	s_barrier
	s_add_i32 s55, s55, 2
	s_add_u32 s26, s26, 0x100
	s_addc_u32 s27, s27, 0
	s_add_u32 s53, s53, 0x100
	s_addc_u32 s54, s54, 0
	s_cmpk_gt_u32 s55, 0x7d
	s_cbranch_scc0 .LBB0_1071
	s_setprio 0
	s_and_b64 vcc, exec, s[6:7]
	s_cbranch_vccz .LBB0_1074
	s_barrier
